# v36 stack + 297 compiler 's_nop 0' pads removed after packed-f32 ops (LLVM dst-sel forwarding rule misapplied to VOP3P op_sel_hi; hazard-checked, outputs unchanged)
# baseline (speedup 1.0000x reference)
; __device__ __forceinline__ f32x2 gelu_pk(f32x2 v) {
;     const f32x2 av = __builtin_elementwise_abs(v), d = av * 0.2316418882f + 1.0f;
;     f32x2 t; t.x = __builtin_amdgcn_rcpf(d.x); t.y = __builtin_amdgcn_rcpf(d.y);
;     f32x2 q = t * 0.5307027145f + (-0.7265760135f); q = q * t + 0.7107068705f; q = q * t + (-0.142248368f); q = q * t + 0.127414796f; q = q * t;
;     const f32x2 s = (v * v) * (-0.72134752044f);
;     f32x2 e; e.x = __builtin_amdgcn_exp2f(s.x); e.y = __builtin_amdgcn_exp2f(s.y);
;     const f32x2 m = v * (q * e), r = v - m;
;     f32x2 o; o.x = v.x < 0.f ? m.x : r.x; o.y = v.y < 0.f ? m.y : r.y; return o;
; }
; __device__ __forceinline__ float row_rstd(const float* slots, int row) {
;     const f32x4* s = (const f32x4*)(slots + (size_t)row * 16);
;     const f32x4 a = s[0], b = s[1], c = s[2], d = s[3];
;     const f32x4 t = (a + b) + (c + d);
;     const float ss = (t[0] + t[1]) + (t[2] + t[3]);
;     return __builtin_amdgcn_rsqf(ss * (1.0f / 1024.0f) + 1e-6f);
; }
; __device__ __forceinline__ void load_rs(const float* slots, int rowbase, int fr, int fq, float scale, float (&rs)[2][4]) {
;     float loc[2];
; #pragma unroll
;     for (int ai = 0; ai < 2; ++ai) loc[ai] = scale * row_rstd(slots, rowbase + ai * HALF + fq * 16 + fr);
; #pragma unroll
;     for (int ai = 0; ai < 2; ++ai)
; #pragma unroll
;         for (int m = 0; m < 4; ++m) rs[ai][m] = __shfl(loc[ai], m * 16 + fr);
.LBB0_276:
	s_lshl_b32 s8, s6, 8
	s_add_i32 s8, s8, s46
	v_or_b32_e32 v172, s8, v178
	v_ashrrev_i32_e32 v173, 31, v172
	v_lshlrev_b64 v[156:157], 6, v[172:173]
	v_lshl_add_u64 v[168:169], s[18:19], 0, v[156:157]
	global_load_dwordx4 v[156:159], v[168:169], off
	global_load_dwordx4 v[160:163], v[168:169], off offset:16
	global_load_dwordx4 v[164:167], v[168:169], off offset:32
	s_nop 0
	global_load_dwordx4 v[168:171], v[168:169], off offset:48
	s_cmp_gt_i32 s60, 1
	s_cselect_b64 s[0:1], -1, 0
	s_cmp_lt_i32 s60, 2
	s_waitcnt vmcnt(0) lgkmcnt(0)
	v_pk_add_f32 v[158:159], v[158:159], v[162:163]
	v_pk_add_f32 v[156:157], v[156:157], v[160:161]
	v_pk_add_f32 v[160:161], v[166:167], v[170:171]
	v_pk_add_f32 v[162:163], v[164:165], v[168:169]
	v_pk_add_f32 v[158:159], v[158:159], v[160:161]
	v_pk_add_f32 v[156:157], v[156:157], v[162:163]
	v_pk_mov_b32 v[160:161], v[156:157], v[158:159] op_sel:[1,0]
	v_mov_b32_e32 v157, v159
	v_pk_add_f32 v[156:157], v[160:161], v[156:157]
	v_add_f32_e32 v156, v156, v157
	v_fmamk_f32 v156, v156, 0x3a800000, v244
	v_rsq_f32_e32 v173, v156
	v_add_u32_e32 v156, 0x80, v172
	v_ashrrev_i32_e32 v157, 31, v156
	v_lshlrev_b64 v[156:157], 6, v[156:157]
	v_lshl_add_u64 v[168:169], s[18:19], 0, v[156:157]
	global_load_dwordx4 v[156:159], v[168:169], off
	global_load_dwordx4 v[160:163], v[168:169], off offset:16
	global_load_dwordx4 v[164:167], v[168:169], off offset:32
	s_nop 0
	global_load_dwordx4 v[168:171], v[168:169], off offset:48
	s_waitcnt vmcnt(0) lgkmcnt(0)
	v_pk_add_f32 v[158:159], v[158:159], v[162:163]
	v_pk_add_f32 v[156:157], v[156:157], v[160:161]
	v_pk_add_f32 v[160:161], v[166:167], v[170:171]
	v_pk_add_f32 v[162:163], v[164:165], v[168:169]
	v_pk_add_f32 v[158:159], v[158:159], v[160:161]
	v_pk_add_f32 v[156:157], v[156:157], v[162:163]
	v_add_f32_e32 v156, v156, v157
	v_add_f32_e32 v157, v158, v159
	v_add_f32_e32 v156, v156, v157
	v_fmamk_f32 v156, v156, 0x3a800000, v244
	v_rsq_f32_e32 v156, v156
	v_and_or_b32 v157, v252, 64, v176
	v_lshlrev_b32_e32 v157, 2, v157
	ds_bpermute_b32 v170, v157, v173
	ds_bpermute_b32 v168, v157, v173 offset:64
	ds_bpermute_b32 v166, v157, v173 offset:128
	ds_bpermute_b32 v164, v157, v173 offset:192
	ds_bpermute_b32 v162, v157, v156
	ds_bpermute_b32 v160, v157, v156 offset:64
	ds_bpermute_b32 v158, v157, v156 offset:128
	ds_bpermute_b32 v156, v157, v156 offset:192
	s_waitcnt lgkmcnt(7)
	v_pk_mul_f32 v[126:127], v[126:127], v[170:171] op_sel_hi:[1,0]
	v_pk_mul_f32 v[124:125], v[124:125], v[170:171] op_sel_hi:[1,0]
	v_pk_mul_f32 v[122:123], v[122:123], v[170:171] op_sel_hi:[1,0]
	v_pk_mul_f32 v[172:173], v[120:121], v[170:171] op_sel_hi:[1,0]
	s_cbranch_scc1 .LBB0_278
	v_and_b32_e32 v121, 0x7fffffff, v125
	v_and_b32_e32 v120, 0x7fffffff, v124
	v_pk_fma_f32 v[120:121], v[120:121], s[28:29], 1.0 op_sel_hi:[1,0,0]
	s_mov_b32 s2, 0xbf3a00e3
	v_rcp_f32_e32 v174, v120
	v_rcp_f32_e32 v175, v121
	v_mov_b64_e32 v[120:121], s[2:3]
	v_pk_mul_f32 v[182:183], v[124:125], v[124:125]
	s_mov_b32 s2, 0xbf38aa3b
	v_pk_fma_f32 v[180:181], v[174:175], s[30:31], v[120:121] op_sel_hi:[1,0,0]
	v_pk_mul_f32 v[182:183], v[182:183], s[2:3] op_sel_hi:[1,0]
	v_pk_fma_f32 v[180:181], v[174:175], v[180:181], s[36:37] op_sel_hi:[1,1,0]
	v_exp_f32_e32 v182, v182
	v_exp_f32_e32 v183, v183
	v_pk_fma_f32 v[180:181], v[174:175], v[180:181], s[80:81] op_sel_hi:[1,1,0]
	v_cmp_gt_f32_e32 vcc, 0, v124
	v_pk_fma_f32 v[180:181], v[174:175], v[180:181], s[64:65] op_sel_hi:[1,1,0]
	v_pk_mul_f32 v[174:175], v[174:175], v[180:181]
	v_pk_mul_f32 v[180:181], v[126:127], v[126:127]
	v_pk_mul_f32 v[174:175], v[182:183], v[174:175]
	v_pk_mul_f32 v[180:181], v[180:181], s[2:3] op_sel_hi:[1,0]
	v_pk_mul_f32 v[182:183], v[124:125], v[174:175]
	v_pk_fma_f32 v[174:175], v[124:125], v[174:175], v[124:125] neg_lo:[1,0,0] neg_hi:[1,0,0]
	v_exp_f32_e32 v180, v180
	v_cndmask_b32_e32 v124, v174, v182, vcc
	v_cmp_gt_f32_e32 vcc, 0, v125
	v_and_b32_e32 v174, 0x7fffffff, v126
	v_exp_f32_e32 v181, v181
	v_cndmask_b32_e32 v125, v175, v183, vcc
	v_and_b32_e32 v175, 0x7fffffff, v127
	v_pk_fma_f32 v[174:175], v[174:175], s[28:29], 1.0 op_sel_hi:[1,0,0]
	v_cmp_gt_f32_e32 vcc, 0, v126
	v_rcp_f32_e32 v174, v174
	v_rcp_f32_e32 v175, v175
	s_nop 0
	v_pk_fma_f32 v[182:183], v[174:175], s[30:31], v[120:121] op_sel_hi:[1,0,0]
	v_pk_fma_f32 v[182:183], v[174:175], v[182:183], s[36:37] op_sel_hi:[1,1,0]
	v_pk_fma_f32 v[182:183], v[174:175], v[182:183], s[80:81] op_sel_hi:[1,1,0]
	v_pk_fma_f32 v[182:183], v[174:175], v[182:183], s[64:65] op_sel_hi:[1,1,0]
	v_pk_mul_f32 v[174:175], v[174:175], v[182:183]
	v_pk_mul_f32 v[182:183], v[172:173], v[172:173]
	v_pk_mul_f32 v[174:175], v[180:181], v[174:175]
	v_pk_mul_f32 v[182:183], v[182:183], s[2:3] op_sel_hi:[1,0]
	v_pk_mul_f32 v[180:181], v[126:127], v[174:175]
	v_pk_fma_f32 v[174:175], v[126:127], v[174:175], v[126:127] neg_lo:[1,0,0] neg_hi:[1,0,0]
	v_exp_f32_e32 v182, v182
	v_cndmask_b32_e32 v126, v174, v180, vcc
	v_cmp_gt_f32_e32 vcc, 0, v127
	v_and_b32_e32 v174, 0x7fffffff, v172
	v_exp_f32_e32 v183, v183
	v_cndmask_b32_e32 v127, v175, v181, vcc
	v_and_b32_e32 v175, 0x7fffffff, v173
	v_pk_fma_f32 v[174:175], v[174:175], s[28:29], 1.0 op_sel_hi:[1,0,0]
	v_cmp_gt_f32_e32 vcc, 0, v172
	v_rcp_f32_e32 v174, v174
	v_rcp_f32_e32 v175, v175
	s_nop 0
	v_pk_fma_f32 v[180:181], v[174:175], s[30:31], v[120:121] op_sel_hi:[1,0,0]
	v_pk_fma_f32 v[180:181], v[174:175], v[180:181], s[36:37] op_sel_hi:[1,1,0]
	v_pk_fma_f32 v[180:181], v[174:175], v[180:181], s[80:81] op_sel_hi:[1,1,0]
	v_pk_fma_f32 v[180:181], v[174:175], v[180:181], s[64:65] op_sel_hi:[1,1,0]
	v_pk_mul_f32 v[174:175], v[174:175], v[180:181]
	v_pk_mul_f32 v[180:181], v[122:123], v[122:123]
	v_pk_mul_f32 v[174:175], v[182:183], v[174:175]
	v_pk_mul_f32 v[182:183], v[172:173], v[174:175]
	v_pk_fma_f32 v[174:175], v[172:173], v[174:175], v[172:173] neg_lo:[1,0,0] neg_hi:[1,0,0]
	v_cndmask_b32_e32 v172, v174, v182, vcc
	v_cmp_gt_f32_e32 vcc, 0, v173
	v_and_b32_e32 v174, 0x7fffffff, v122
	s_nop 0
	v_cndmask_b32_e32 v173, v175, v183, vcc
	v_and_b32_e32 v175, 0x7fffffff, v123
	v_pk_fma_f32 v[174:175], v[174:175], s[28:29], 1.0 op_sel_hi:[1,0,0]
	v_cmp_gt_f32_e32 vcc, 0, v122
	v_rcp_f32_e32 v174, v174
	v_rcp_f32_e32 v175, v175
	s_nop 0
	v_pk_fma_f32 v[120:121], v[174:175], s[30:31], v[120:121] op_sel_hi:[1,0,0]
	v_pk_fma_f32 v[120:121], v[174:175], v[120:121], s[36:37] op_sel_hi:[1,1,0]
	v_pk_fma_f32 v[120:121], v[174:175], v[120:121], s[80:81] op_sel_hi:[1,1,0]
	v_pk_fma_f32 v[120:121], v[174:175], v[120:121], s[64:65] op_sel_hi:[1,1,0]
	v_pk_mul_f32 v[120:121], v[174:175], v[120:121]
	v_pk_mul_f32 v[174:175], v[180:181], s[2:3] op_sel_hi:[1,0]
	v_exp_f32_e32 v174, v174
	v_exp_f32_e32 v175, v175
	s_nop 0
	v_pk_mul_f32 v[120:121], v[174:175], v[120:121]
	v_pk_mul_f32 v[174:175], v[122:123], v[120:121]
	v_pk_fma_f32 v[120:121], v[122:123], v[120:121], v[122:123] neg_lo:[1,0,0] neg_hi:[1,0,0]
	s_nop 0
	v_cndmask_b32_e32 v122, v120, v174, vcc
	v_cmp_gt_f32_e32 vcc, 0, v123
	s_nop 1
	v_cndmask_b32_e32 v123, v121, v175, vcc

; __device__ __forceinline__ unsigned cvt_pk_bf16(float lo, float hi) { unsigned r; asm volatile("v_cvt_pk_bf16_f32 %0, %1, %2" : "=v"(r) : "v"(lo), "v"(hi)); return r; }
; __device__ __forceinline__ f32x2 gelu_pk(f32x2 v) {
;     const f32x2 av = __builtin_elementwise_abs(v), d = av * 0.2316418882f + 1.0f;
;     f32x2 t; t.x = __builtin_amdgcn_rcpf(d.x); t.y = __builtin_amdgcn_rcpf(d.y);
;     f32x2 q = t * 0.5307027145f + (-0.7265760135f); q = q * t + 0.7107068705f; q = q * t + (-0.142248368f); q = q * t + 0.127414796f; q = q * t;
;     const f32x2 s = (v * v) * (-0.72134752044f);
;     f32x2 e; e.x = __builtin_amdgcn_exp2f(s.x); e.y = __builtin_amdgcn_exp2f(s.y);
;     const f32x2 m = v * (q * e), r = v - m;
;     f32x2 o; o.x = v.x < 0.f ? m.x : r.x; o.y = v.y < 0.f ? m.y : r.y; return o;
; }
;     __device__ __forceinline__ void operator()(const f32x4 (&acc)[2][2][4][2], const Unit& u, int wr, int wc, int fr, int fq) const {
;     ...
;             for (int m = 0; m < 4; ++m) { bf16_t* rowp = O + (size_t)(u.pm >> 5) * bgap + (size_t)u.pm * sm + (size_t)u.pn * sn + (size_t)(wr * 64 + fr + ai * HALF + m * 16) * ldc + wc * 32 + 8 * fq; const float sc = rs[ai][m]; float s1 = 0.f, s2 = 0.f;
; #pragma unroll
;                 for (int bj = 0; bj < 2; ++bj) { f32x4 v0 = acc[ai][bj][m][0] * sc, v1 = acc[ai][bj][m][1] * sc;
;                     if (do_gelu) { f32x2 a = gelu_pk((f32x2){v0[0], v0[1]}), b = gelu_pk((f32x2){v0[2], v0[3]}), c = gelu_pk((f32x2){v1[0], v1[1]}), d = gelu_pk((f32x2){v1[2], v1[3]});
;                         v0 = (f32x4){a.x, a.y, b.x, b.y}; v1 = (f32x4){c.x, c.y, d.x, d.y}; }
;                     if (do_stat) { s1 += ((v0[0] + v0[1]) + (v0[2] + v0[3])) + ((v1[0] + v1[1]) + (v1[2] + v1[3]));
;                         s2 += ((v0[0] * v0[0] + v0[1] * v0[1]) + (v0[2] * v0[2] + v0[3] * v0[3])) + ((v1[0] * v1[0] + v1[1] * v1[1]) + (v1[2] * v1[2] + v1[3] * v1[3])); }
;                     u32x4 w; w.x = cvt_pk_bf16(v0[0], v0[1]); w.y = cvt_pk_bf16(v0[2], v0[3]); w.z = cvt_pk_bf16(v1[0], v1[1]); w.w = cvt_pk_bf16(v1[2], v1[3]);
;                     *(u32x4*)(rowp + bj * HALF) = w; }
.LBB0_282:
	s_ashr_i32 s4, s6, 5
	s_mul_hi_i32 s5, s4, 0x1400000
	s_mul_i32 s4, s4, 0x1400000
	s_add_u32 s4, s12, s4
	s_addc_u32 s5, s13, s5
	s_mul_hi_i32 s9, s6, 0xc0000
	s_mul_i32 s6, s6, 0xc0000
	s_add_u32 s6, s4, s6
	s_addc_u32 s9, s5, s9
	s_ashr_i32 s61, s60, 31
	s_lshl_b64 s[4:5], s[60:61], 9
	s_add_u32 s16, s6, s4
	s_addc_u32 s17, s9, s5
	v_lshl_add_u64 v[174:175], s[16:17], 0, v[136:137]
	s_lshl_b32 s86, s47, 1
	v_cvt_pk_bf16_f32 v124, v124, v125
	v_cvt_pk_bf16_f32 v125, v126, v127
	v_cvt_pk_bf16_f32 v126, v172, v173
	v_cvt_pk_bf16_f32 v127, v122, v123
	v_mov_b32_e32 v122, v170
	v_mov_b32_e32 v123, v170
	v_mov_b32_e32 v171, v170
	v_lshl_add_u64 v[174:175], v[174:175], 0, s[86:87]
	v_pk_mul_f32 v[118:119], v[118:119], v[122:123]
	v_pk_mul_f32 v[114:115], v[114:115], v[122:123]
	v_cndmask_b32_e64 v122, 0, 1, s[0:1]
	v_lshl_add_u64 v[174:175], v[174:175], 0, v[192:193]
	v_pk_mul_f32 v[116:117], v[116:117], v[170:171]
	v_cmp_ne_u32_e64 s[42:43], 1, v122
	s_andn2_b64 vcc, exec, s[0:1]
	v_pk_mul_f32 v[122:123], v[112:113], v[170:171]
	global_store_dwordx4 v[174:175], v[124:127], off
	s_cbranch_vccnz .LBB0_284
	v_and_b32_e32 v113, 0x7fffffff, v117
	v_and_b32_e32 v112, 0x7fffffff, v116
	v_pk_fma_f32 v[112:113], v[112:113], s[28:29], 1.0 op_sel_hi:[1,0,0]
	s_mov_b32 s0, 0xbf3a00e3
	v_rcp_f32_e32 v124, v112
	v_rcp_f32_e32 v125, v113
	v_mov_b64_e32 v[112:113], s[0:1]
	v_pk_mul_f32 v[170:171], v[116:117], v[116:117]
	s_mov_b32 s0, 0xbf38aa3b
	v_pk_fma_f32 v[126:127], v[124:125], s[30:31], v[112:113] op_sel_hi:[1,0,0]
	v_pk_mul_f32 v[170:171], v[170:171], s[0:1] op_sel_hi:[1,0]
	v_pk_fma_f32 v[126:127], v[124:125], v[126:127], s[36:37] op_sel_hi:[1,1,0]
	v_exp_f32_e32 v170, v170
	v_exp_f32_e32 v171, v171
	v_pk_fma_f32 v[126:127], v[124:125], v[126:127], s[80:81] op_sel_hi:[1,1,0]
	v_cmp_gt_f32_e32 vcc, 0, v116
	v_pk_fma_f32 v[126:127], v[124:125], v[126:127], s[64:65] op_sel_hi:[1,1,0]
	v_pk_mul_f32 v[124:125], v[124:125], v[126:127]
	v_pk_mul_f32 v[126:127], v[118:119], v[118:119]
	v_pk_mul_f32 v[124:125], v[170:171], v[124:125]
	v_pk_mul_f32 v[126:127], v[126:127], s[0:1] op_sel_hi:[1,0]
	v_pk_mul_f32 v[170:171], v[116:117], v[124:125]
	v_pk_fma_f32 v[124:125], v[116:117], v[124:125], v[116:117] neg_lo:[1,0,0] neg_hi:[1,0,0]
	v_exp_f32_e32 v126, v126
	v_cndmask_b32_e32 v116, v124, v170, vcc
	v_cmp_gt_f32_e32 vcc, 0, v117
	v_and_b32_e32 v124, 0x7fffffff, v118
	v_exp_f32_e32 v127, v127
	v_cndmask_b32_e32 v117, v125, v171, vcc
	v_and_b32_e32 v125, 0x7fffffff, v119
	v_pk_fma_f32 v[124:125], v[124:125], s[28:29], 1.0 op_sel_hi:[1,0,0]
	v_cmp_gt_f32_e32 vcc, 0, v118
	v_rcp_f32_e32 v124, v124
	v_rcp_f32_e32 v125, v125
	s_nop 0
	v_pk_fma_f32 v[170:171], v[124:125], s[30:31], v[112:113] op_sel_hi:[1,0,0]
	v_pk_fma_f32 v[170:171], v[124:125], v[170:171], s[36:37] op_sel_hi:[1,1,0]
	v_pk_fma_f32 v[170:171], v[124:125], v[170:171], s[80:81] op_sel_hi:[1,1,0]
	v_pk_fma_f32 v[170:171], v[124:125], v[170:171], s[64:65] op_sel_hi:[1,1,0]
	v_pk_mul_f32 v[124:125], v[124:125], v[170:171]
	v_pk_mul_f32 v[170:171], v[122:123], v[122:123]
	v_pk_mul_f32 v[124:125], v[126:127], v[124:125]
	v_pk_mul_f32 v[170:171], v[170:171], s[0:1] op_sel_hi:[1,0]
	v_pk_mul_f32 v[126:127], v[118:119], v[124:125]
	v_pk_fma_f32 v[124:125], v[118:119], v[124:125], v[118:119] neg_lo:[1,0,0] neg_hi:[1,0,0]
	v_exp_f32_e32 v170, v170
	v_cndmask_b32_e32 v118, v124, v126, vcc
	v_cmp_gt_f32_e32 vcc, 0, v119
	v_and_b32_e32 v124, 0x7fffffff, v122
	v_exp_f32_e32 v171, v171
	v_cndmask_b32_e32 v119, v125, v127, vcc
	v_and_b32_e32 v125, 0x7fffffff, v123
	v_pk_fma_f32 v[124:125], v[124:125], s[28:29], 1.0 op_sel_hi:[1,0,0]
	v_cmp_gt_f32_e32 vcc, 0, v122
	v_rcp_f32_e32 v124, v124
	v_rcp_f32_e32 v125, v125
	s_nop 0
	v_pk_fma_f32 v[126:127], v[124:125], s[30:31], v[112:113] op_sel_hi:[1,0,0]
	v_pk_fma_f32 v[126:127], v[124:125], v[126:127], s[36:37] op_sel_hi:[1,1,0]
	v_pk_fma_f32 v[126:127], v[124:125], v[126:127], s[80:81] op_sel_hi:[1,1,0]
	v_pk_fma_f32 v[126:127], v[124:125], v[126:127], s[64:65] op_sel_hi:[1,1,0]
	v_pk_mul_f32 v[124:125], v[124:125], v[126:127]
	v_pk_mul_f32 v[126:127], v[114:115], v[114:115]
	v_pk_mul_f32 v[124:125], v[170:171], v[124:125]
	v_pk_mul_f32 v[170:171], v[122:123], v[124:125]
	v_pk_fma_f32 v[124:125], v[122:123], v[124:125], v[122:123] neg_lo:[1,0,0] neg_hi:[1,0,0]
	v_cndmask_b32_e32 v122, v124, v170, vcc
	v_cmp_gt_f32_e32 vcc, 0, v123
	v_and_b32_e32 v124, 0x7fffffff, v114
	s_nop 0
	v_cndmask_b32_e32 v123, v125, v171, vcc
	v_and_b32_e32 v125, 0x7fffffff, v115
	v_pk_fma_f32 v[124:125], v[124:125], s[28:29], 1.0 op_sel_hi:[1,0,0]
	v_cmp_gt_f32_e32 vcc, 0, v114
	v_rcp_f32_e32 v124, v124
	v_rcp_f32_e32 v125, v125
	s_nop 0
	v_pk_fma_f32 v[112:113], v[124:125], s[30:31], v[112:113] op_sel_hi:[1,0,0]
	v_pk_fma_f32 v[112:113], v[124:125], v[112:113], s[36:37] op_sel_hi:[1,1,0]
	v_pk_fma_f32 v[112:113], v[124:125], v[112:113], s[80:81] op_sel_hi:[1,1,0]
	v_pk_fma_f32 v[112:113], v[124:125], v[112:113], s[64:65] op_sel_hi:[1,1,0]
	v_pk_mul_f32 v[112:113], v[124:125], v[112:113]
	v_pk_mul_f32 v[124:125], v[126:127], s[0:1] op_sel_hi:[1,0]
	v_exp_f32_e32 v124, v124
	v_exp_f32_e32 v125, v125
	s_nop 0
	v_pk_mul_f32 v[112:113], v[124:125], v[112:113]
	v_pk_mul_f32 v[124:125], v[114:115], v[112:113]
	v_pk_fma_f32 v[112:113], v[114:115], v[112:113], v[114:115] neg_lo:[1,0,0] neg_hi:[1,0,0]
	s_nop 0
	v_cndmask_b32_e32 v114, v112, v124, vcc
	v_cmp_gt_f32_e32 vcc, 0, v115
	s_nop 1
	v_cndmask_b32_e32 v115, v113, v125, vcc
.LBB0_284:
	s_and_b64 vcc, exec, s[92:93]
	s_cbranch_vccz .LBB0_286
	v_mul_f32_e32 v113, v116, v116
	v_mul_f32_e32 v125, v117, v117
	v_mul_f32_e32 v127, v118, v118
	v_mul_f32_e32 v171, v119, v119
	v_mov_b32_e32 v112, v116
	v_mov_b32_e32 v124, v117
	v_mov_b32_e32 v126, v118
	v_mov_b32_e32 v170, v119
	v_mul_f32_e32 v173, v122, v122
	v_mul_f32_e32 v181, v123, v123
	v_mul_f32_e32 v183, v114, v114
	v_mul_f32_e32 v185, v115, v115
	v_pk_add_f32 v[112:113], v[112:113], v[124:125]
	v_pk_add_f32 v[124:125], v[126:127], v[170:171]
	v_mov_b32_e32 v172, v122
	v_mov_b32_e32 v180, v123
	v_mov_b32_e32 v182, v114
	v_mov_b32_e32 v184, v115
	v_pk_add_f32 v[112:113], v[112:113], v[124:125]
	v_pk_add_f32 v[124:125], v[172:173], v[180:181]
	v_pk_add_f32 v[126:127], v[182:183], v[184:185]
	v_pk_add_f32 v[124:125], v[124:125], v[126:127]
	s_nop 0
	v_pk_add_f32 v[112:113], v[124:125], v[112:113]
	s_nop 0
	v_pk_add_f32 v[124:125], v[120:121], v[112:113]
	s_cbranch_execz .LBB0_287
	s_branch .LBB0_288

; __device__ __forceinline__ f32x2 gelu_pk(f32x2 v) {
;     const f32x2 av = __builtin_elementwise_abs(v), d = av * 0.2316418882f + 1.0f;
;     f32x2 t; t.x = __builtin_amdgcn_rcpf(d.x); t.y = __builtin_amdgcn_rcpf(d.y);
;     f32x2 q = t * 0.5307027145f + (-0.7265760135f); q = q * t + 0.7107068705f; q = q * t + (-0.142248368f); q = q * t + 0.127414796f; q = q * t;
;     const f32x2 s = (v * v) * (-0.72134752044f);
;     f32x2 e; e.x = __builtin_amdgcn_exp2f(s.x); e.y = __builtin_amdgcn_exp2f(s.y);
;     const f32x2 m = v * (q * e), r = v - m;
;     f32x2 o; o.x = v.x < 0.f ? m.x : r.x; o.y = v.y < 0.f ? m.y : r.y; return o;
; }
;     __device__ __forceinline__ void operator()(const f32x4 (&acc)[2][2][4][2], const Unit& u, int wr, int wc, int fr, int fq) const {
;     ...
;                 for (int bj = 0; bj < 2; ++bj) { f32x4 v0 = acc[ai][bj][m][0] * sc, v1 = acc[ai][bj][m][1] * sc;
;                     if (do_gelu) { f32x2 a = gelu_pk((f32x2){v0[0], v0[1]}), b = gelu_pk((f32x2){v0[2], v0[3]}), c = gelu_pk((f32x2){v1[0], v1[1]}), d = gelu_pk((f32x2){v1[2], v1[3]});
;                         v0 = (f32x4){a.x, a.y, b.x, b.y}; v1 = (f32x4){c.x, c.y, d.x, d.y}; }
.LBB0_292:
	s_waitcnt lgkmcnt(0)
	v_pk_mul_f32 v[110:111], v[110:111], v[168:169] op_sel_hi:[1,0]
	v_pk_mul_f32 v[108:109], v[108:109], v[168:169] op_sel_hi:[1,0]
	v_pk_mul_f32 v[114:115], v[106:107], v[168:169] op_sel_hi:[1,0]
	s_and_b64 vcc, exec, s[42:43]
	v_pk_mul_f32 v[116:117], v[104:105], v[168:169] op_sel_hi:[1,0]
	s_cbranch_vccnz .LBB0_294
	v_and_b32_e32 v105, 0x7fffffff, v109
	v_and_b32_e32 v104, 0x7fffffff, v108
	v_pk_fma_f32 v[104:105], v[104:105], s[28:29], 1.0 op_sel_hi:[1,0,0]
	s_mov_b32 s0, 0xbf3a00e3
	v_rcp_f32_e32 v106, v104
	v_rcp_f32_e32 v107, v105
	v_mov_b64_e32 v[104:105], s[0:1]
	v_pk_mul_f32 v[124:125], v[108:109], v[108:109]
	s_mov_b32 s0, 0xbf38aa3b
	v_pk_fma_f32 v[122:123], v[106:107], s[30:31], v[104:105] op_sel_hi:[1,0,0]
	v_pk_mul_f32 v[124:125], v[124:125], s[0:1] op_sel_hi:[1,0]
	v_pk_fma_f32 v[122:123], v[106:107], v[122:123], s[36:37] op_sel_hi:[1,1,0]
	v_exp_f32_e32 v124, v124
	v_exp_f32_e32 v125, v125
	v_pk_fma_f32 v[122:123], v[106:107], v[122:123], s[80:81] op_sel_hi:[1,1,0]
	v_cmp_gt_f32_e32 vcc, 0, v108
	v_pk_fma_f32 v[122:123], v[106:107], v[122:123], s[64:65] op_sel_hi:[1,1,0]
	v_pk_mul_f32 v[106:107], v[106:107], v[122:123]
	v_pk_mul_f32 v[122:123], v[110:111], v[110:111]
	v_pk_mul_f32 v[106:107], v[124:125], v[106:107]
	v_pk_mul_f32 v[122:123], v[122:123], s[0:1] op_sel_hi:[1,0]
	v_pk_mul_f32 v[124:125], v[108:109], v[106:107]
	v_pk_fma_f32 v[106:107], v[108:109], v[106:107], v[108:109] neg_lo:[1,0,0] neg_hi:[1,0,0]
	v_exp_f32_e32 v122, v122
	v_cndmask_b32_e32 v108, v106, v124, vcc
	v_cmp_gt_f32_e32 vcc, 0, v109
	v_and_b32_e32 v106, 0x7fffffff, v110
	v_exp_f32_e32 v123, v123
	v_cndmask_b32_e32 v109, v107, v125, vcc
	v_and_b32_e32 v107, 0x7fffffff, v111
	v_pk_fma_f32 v[106:107], v[106:107], s[28:29], 1.0 op_sel_hi:[1,0,0]
	v_cmp_gt_f32_e32 vcc, 0, v110
	v_rcp_f32_e32 v106, v106
	v_rcp_f32_e32 v107, v107
	s_nop 0
	v_pk_fma_f32 v[124:125], v[106:107], s[30:31], v[104:105] op_sel_hi:[1,0,0]
	v_pk_fma_f32 v[124:125], v[106:107], v[124:125], s[36:37] op_sel_hi:[1,1,0]
	v_pk_fma_f32 v[124:125], v[106:107], v[124:125], s[80:81] op_sel_hi:[1,1,0]
	v_pk_fma_f32 v[124:125], v[106:107], v[124:125], s[64:65] op_sel_hi:[1,1,0]
	v_pk_mul_f32 v[106:107], v[106:107], v[124:125]
	v_pk_mul_f32 v[124:125], v[116:117], v[116:117]
	v_pk_mul_f32 v[106:107], v[122:123], v[106:107]
	v_pk_mul_f32 v[124:125], v[124:125], s[0:1] op_sel_hi:[1,0]
	v_pk_mul_f32 v[122:123], v[110:111], v[106:107]
	v_pk_fma_f32 v[106:107], v[110:111], v[106:107], v[110:111] neg_lo:[1,0,0] neg_hi:[1,0,0]
	v_exp_f32_e32 v124, v124
	v_cndmask_b32_e32 v110, v106, v122, vcc
	v_cmp_gt_f32_e32 vcc, 0, v111
	v_and_b32_e32 v106, 0x7fffffff, v116
	v_exp_f32_e32 v125, v125
	v_cndmask_b32_e32 v111, v107, v123, vcc
	v_and_b32_e32 v107, 0x7fffffff, v117
	v_pk_fma_f32 v[106:107], v[106:107], s[28:29], 1.0 op_sel_hi:[1,0,0]
	v_cmp_gt_f32_e32 vcc, 0, v116
	v_rcp_f32_e32 v106, v106
	v_rcp_f32_e32 v107, v107
	s_nop 0
	v_pk_fma_f32 v[122:123], v[106:107], s[30:31], v[104:105] op_sel_hi:[1,0,0]
	v_pk_fma_f32 v[122:123], v[106:107], v[122:123], s[36:37] op_sel_hi:[1,1,0]
	v_pk_fma_f32 v[122:123], v[106:107], v[122:123], s[80:81] op_sel_hi:[1,1,0]
	v_pk_fma_f32 v[122:123], v[106:107], v[122:123], s[64:65] op_sel_hi:[1,1,0]
	v_pk_mul_f32 v[106:107], v[106:107], v[122:123]
	v_pk_mul_f32 v[122:123], v[114:115], v[114:115]
	v_pk_mul_f32 v[106:107], v[124:125], v[106:107]
	v_pk_mul_f32 v[124:125], v[116:117], v[106:107]
	v_pk_fma_f32 v[106:107], v[116:117], v[106:107], v[116:117] neg_lo:[1,0,0] neg_hi:[1,0,0]
	v_cndmask_b32_e32 v116, v106, v124, vcc
	v_cmp_gt_f32_e32 vcc, 0, v117
	v_and_b32_e32 v106, 0x7fffffff, v114
	s_nop 0
	v_cndmask_b32_e32 v117, v107, v125, vcc
	v_and_b32_e32 v107, 0x7fffffff, v115
	v_pk_fma_f32 v[106:107], v[106:107], s[28:29], 1.0 op_sel_hi:[1,0,0]
	v_cmp_gt_f32_e32 vcc, 0, v114
	v_rcp_f32_e32 v106, v106
	v_rcp_f32_e32 v107, v107
	s_nop 0
	v_pk_fma_f32 v[104:105], v[106:107], s[30:31], v[104:105] op_sel_hi:[1,0,0]
	v_pk_fma_f32 v[104:105], v[106:107], v[104:105], s[36:37] op_sel_hi:[1,1,0]
	v_pk_fma_f32 v[104:105], v[106:107], v[104:105], s[80:81] op_sel_hi:[1,1,0]
	v_pk_fma_f32 v[104:105], v[106:107], v[104:105], s[64:65] op_sel_hi:[1,1,0]
	v_pk_mul_f32 v[104:105], v[106:107], v[104:105]
	v_pk_mul_f32 v[106:107], v[122:123], s[0:1] op_sel_hi:[1,0]
	v_exp_f32_e32 v106, v106
	v_exp_f32_e32 v107, v107
	s_nop 0
	v_pk_mul_f32 v[104:105], v[106:107], v[104:105]
	v_pk_mul_f32 v[106:107], v[114:115], v[104:105]
	v_pk_fma_f32 v[104:105], v[114:115], v[104:105], v[114:115] neg_lo:[1,0,0] neg_hi:[1,0,0]
	s_nop 0
	v_cndmask_b32_e32 v114, v104, v106, vcc
	v_cmp_gt_f32_e32 vcc, 0, v115
	s_nop 1
	v_cndmask_b32_e32 v115, v105, v107, vcc

; __device__ __forceinline__ unsigned cvt_pk_bf16(float lo, float hi) { unsigned r; asm volatile("v_cvt_pk_bf16_f32 %0, %1, %2" : "=v"(r) : "v"(lo), "v"(hi)); return r; }
; __device__ __forceinline__ f32x2 gelu_pk(f32x2 v) {
;     const f32x2 av = __builtin_elementwise_abs(v), d = av * 0.2316418882f + 1.0f;
;     f32x2 t; t.x = __builtin_amdgcn_rcpf(d.x); t.y = __builtin_amdgcn_rcpf(d.y);
;     f32x2 q = t * 0.5307027145f + (-0.7265760135f); q = q * t + 0.7107068705f; q = q * t + (-0.142248368f); q = q * t + 0.127414796f; q = q * t;
;     const f32x2 s = (v * v) * (-0.72134752044f);
;     f32x2 e; e.x = __builtin_amdgcn_exp2f(s.x); e.y = __builtin_amdgcn_exp2f(s.y);
;     const f32x2 m = v * (q * e), r = v - m;
;     f32x2 o; o.x = v.x < 0.f ? m.x : r.x; o.y = v.y < 0.f ? m.y : r.y; return o;
; }
;     __device__ __forceinline__ void operator()(const f32x4 (&acc)[2][2][4][2], const Unit& u, int wr, int wc, int fr, int fq) const {
;     ...
;                 for (int bj = 0; bj < 2; ++bj) { f32x4 v0 = acc[ai][bj][m][0] * sc, v1 = acc[ai][bj][m][1] * sc;
;                     if (do_gelu) { f32x2 a = gelu_pk((f32x2){v0[0], v0[1]}), b = gelu_pk((f32x2){v0[2], v0[3]}), c = gelu_pk((f32x2){v1[0], v1[1]}), d = gelu_pk((f32x2){v1[2], v1[3]});
;                         v0 = (f32x4){a.x, a.y, b.x, b.y}; v1 = (f32x4){c.x, c.y, d.x, d.y}; }
;                     if (do_stat) { s1 += ((v0[0] + v0[1]) + (v0[2] + v0[3])) + ((v1[0] + v1[1]) + (v1[2] + v1[3]));
;                         s2 += ((v0[0] * v0[0] + v0[1] * v0[1]) + (v0[2] * v0[2] + v0[3] * v0[3])) + ((v1[0] * v1[0] + v1[1] * v1[1]) + (v1[2] * v1[2] + v1[3] * v1[3])); }
;                     u32x4 w; w.x = cvt_pk_bf16(v0[0], v0[1]); w.y = cvt_pk_bf16(v0[2], v0[3]); w.z = cvt_pk_bf16(v1[0], v1[1]); w.w = cvt_pk_bf16(v1[2], v1[3]);
;                     *(u32x4*)(rowp + bj * HALF) = w; }
.LBB0_298:
	v_lshl_add_u64 v[106:107], s[16:17], 0, v[138:139]
	v_lshl_add_u64 v[106:107], v[106:107], 0, s[86:87]
	v_lshl_add_u64 v[106:107], v[106:107], 0, v[192:193]
	v_cvt_pk_bf16_f32 v108, v108, v109
	v_cvt_pk_bf16_f32 v109, v110, v111
	v_mov_b32_e32 v169, v168
	v_cvt_pk_bf16_f32 v110, v116, v117
	v_cvt_pk_bf16_f32 v111, v114, v115
	global_store_dwordx4 v[106:107], v[108:111], off
	v_pk_mul_f32 v[100:101], v[100:101], v[168:169]
	s_and_b64 vcc, exec, s[42:43]
	v_mov_b32_e32 v108, v168
	v_mov_b32_e32 v109, v168
	v_pk_mul_f32 v[102:103], v[102:103], v[108:109]
	v_pk_mul_f32 v[98:99], v[98:99], v[108:109]
	v_pk_mul_f32 v[96:97], v[96:97], v[168:169]
	s_cbranch_vccnz .LBB0_300
	v_and_b32_e32 v109, 0x7fffffff, v101
	v_and_b32_e32 v108, 0x7fffffff, v100
	v_pk_fma_f32 v[108:109], v[108:109], s[28:29], 1.0 op_sel_hi:[1,0,0]
	s_mov_b32 s0, 0xbf3a00e3
	v_rcp_f32_e32 v110, v108
	v_rcp_f32_e32 v111, v109
	v_mov_b64_e32 v[108:109], s[0:1]
	v_pk_mul_f32 v[116:117], v[100:101], v[100:101]
	s_mov_b32 s0, 0xbf38aa3b
	v_pk_fma_f32 v[114:115], v[110:111], s[30:31], v[108:109] op_sel_hi:[1,0,0]
	v_pk_mul_f32 v[116:117], v[116:117], s[0:1] op_sel_hi:[1,0]
	v_pk_fma_f32 v[114:115], v[110:111], v[114:115], s[36:37] op_sel_hi:[1,1,0]
	v_exp_f32_e32 v116, v116
	v_exp_f32_e32 v117, v117
	v_pk_fma_f32 v[114:115], v[110:111], v[114:115], s[80:81] op_sel_hi:[1,1,0]
	v_cmp_gt_f32_e32 vcc, 0, v100
	v_pk_fma_f32 v[114:115], v[110:111], v[114:115], s[64:65] op_sel_hi:[1,1,0]
	v_pk_mul_f32 v[110:111], v[110:111], v[114:115]
	v_pk_mul_f32 v[114:115], v[102:103], v[102:103]
	v_pk_mul_f32 v[110:111], v[116:117], v[110:111]
	v_pk_mul_f32 v[114:115], v[114:115], s[0:1] op_sel_hi:[1,0]
	v_pk_mul_f32 v[116:117], v[100:101], v[110:111]
	v_pk_fma_f32 v[110:111], v[100:101], v[110:111], v[100:101] neg_lo:[1,0,0] neg_hi:[1,0,0]
	v_exp_f32_e32 v114, v114
	v_cndmask_b32_e32 v100, v110, v116, vcc
	v_cmp_gt_f32_e32 vcc, 0, v101
	v_and_b32_e32 v110, 0x7fffffff, v102
	v_exp_f32_e32 v115, v115
	v_cndmask_b32_e32 v101, v111, v117, vcc
	v_and_b32_e32 v111, 0x7fffffff, v103
	v_pk_fma_f32 v[110:111], v[110:111], s[28:29], 1.0 op_sel_hi:[1,0,0]
	v_cmp_gt_f32_e32 vcc, 0, v102
	v_rcp_f32_e32 v110, v110
	v_rcp_f32_e32 v111, v111
	s_nop 0
	v_pk_fma_f32 v[116:117], v[110:111], s[30:31], v[108:109] op_sel_hi:[1,0,0]
	v_pk_fma_f32 v[116:117], v[110:111], v[116:117], s[36:37] op_sel_hi:[1,1,0]
	v_pk_fma_f32 v[116:117], v[110:111], v[116:117], s[80:81] op_sel_hi:[1,1,0]
	v_pk_fma_f32 v[116:117], v[110:111], v[116:117], s[64:65] op_sel_hi:[1,1,0]
	v_pk_mul_f32 v[110:111], v[110:111], v[116:117]
	v_pk_mul_f32 v[116:117], v[96:97], v[96:97]
	v_pk_mul_f32 v[110:111], v[114:115], v[110:111]
	v_pk_mul_f32 v[116:117], v[116:117], s[0:1] op_sel_hi:[1,0]
	v_pk_mul_f32 v[114:115], v[102:103], v[110:111]
	v_pk_fma_f32 v[110:111], v[102:103], v[110:111], v[102:103] neg_lo:[1,0,0] neg_hi:[1,0,0]
	v_exp_f32_e32 v116, v116
	v_cndmask_b32_e32 v102, v110, v114, vcc
	v_cmp_gt_f32_e32 vcc, 0, v103
	v_and_b32_e32 v110, 0x7fffffff, v96
	v_exp_f32_e32 v117, v117
	v_cndmask_b32_e32 v103, v111, v115, vcc
	v_and_b32_e32 v111, 0x7fffffff, v97
	v_pk_fma_f32 v[110:111], v[110:111], s[28:29], 1.0 op_sel_hi:[1,0,0]
	v_cmp_gt_f32_e32 vcc, 0, v96
	v_rcp_f32_e32 v110, v110
	v_rcp_f32_e32 v111, v111
	s_nop 0
	v_pk_fma_f32 v[114:115], v[110:111], s[30:31], v[108:109] op_sel_hi:[1,0,0]
	v_pk_fma_f32 v[114:115], v[110:111], v[114:115], s[36:37] op_sel_hi:[1,1,0]
	v_pk_fma_f32 v[114:115], v[110:111], v[114:115], s[80:81] op_sel_hi:[1,1,0]
	v_pk_fma_f32 v[114:115], v[110:111], v[114:115], s[64:65] op_sel_hi:[1,1,0]
	v_pk_mul_f32 v[110:111], v[110:111], v[114:115]
	v_pk_mul_f32 v[114:115], v[98:99], v[98:99]
	v_pk_mul_f32 v[110:111], v[116:117], v[110:111]
	v_pk_mul_f32 v[116:117], v[96:97], v[110:111]
	v_pk_fma_f32 v[110:111], v[96:97], v[110:111], v[96:97] neg_lo:[1,0,0] neg_hi:[1,0,0]
	v_cndmask_b32_e32 v96, v110, v116, vcc
	v_cmp_gt_f32_e32 vcc, 0, v97
	v_and_b32_e32 v110, 0x7fffffff, v98
	s_nop 0
	v_cndmask_b32_e32 v97, v111, v117, vcc
	v_and_b32_e32 v111, 0x7fffffff, v99
	v_pk_fma_f32 v[110:111], v[110:111], s[28:29], 1.0 op_sel_hi:[1,0,0]
	v_cmp_gt_f32_e32 vcc, 0, v98
	v_rcp_f32_e32 v110, v110
	v_rcp_f32_e32 v111, v111
	s_nop 0
	v_pk_fma_f32 v[108:109], v[110:111], s[30:31], v[108:109] op_sel_hi:[1,0,0]
	v_pk_fma_f32 v[108:109], v[110:111], v[108:109], s[36:37] op_sel_hi:[1,1,0]
	v_pk_fma_f32 v[108:109], v[110:111], v[108:109], s[80:81] op_sel_hi:[1,1,0]
	v_pk_fma_f32 v[108:109], v[110:111], v[108:109], s[64:65] op_sel_hi:[1,1,0]
	v_pk_mul_f32 v[108:109], v[110:111], v[108:109]
	v_pk_mul_f32 v[110:111], v[114:115], s[0:1] op_sel_hi:[1,0]
	v_exp_f32_e32 v110, v110
	v_exp_f32_e32 v111, v111
	s_nop 0
	v_pk_mul_f32 v[108:109], v[110:111], v[108:109]
	v_pk_mul_f32 v[110:111], v[98:99], v[108:109]
	v_pk_fma_f32 v[108:109], v[98:99], v[108:109], v[98:99] neg_lo:[1,0,0] neg_hi:[1,0,0]
	s_nop 0
	v_cndmask_b32_e32 v98, v108, v110, vcc
	v_cmp_gt_f32_e32 vcc, 0, v99
	s_nop 1
	v_cndmask_b32_e32 v99, v109, v111, vcc
.LBB0_300:
	s_and_b64 vcc, exec, s[92:93]
	s_cbranch_vccz .LBB0_302
	v_mul_f32_e32 v109, v100, v100
	v_mul_f32_e32 v111, v101, v101
	v_mul_f32_e32 v115, v102, v102
	v_mul_f32_e32 v117, v103, v103
	v_mov_b32_e32 v108, v100
	v_mov_b32_e32 v110, v101
	v_mov_b32_e32 v114, v102
	v_mov_b32_e32 v116, v103
	v_mul_f32_e32 v123, v96, v96
	v_mul_f32_e32 v125, v97, v97
	v_mul_f32_e32 v127, v98, v98
	v_mul_f32_e32 v169, v99, v99
	v_pk_add_f32 v[108:109], v[108:109], v[110:111]
	v_pk_add_f32 v[110:111], v[114:115], v[116:117]
	v_mov_b32_e32 v122, v96
	v_mov_b32_e32 v124, v97
	v_mov_b32_e32 v126, v98
	v_mov_b32_e32 v168, v99
	v_pk_add_f32 v[108:109], v[108:109], v[110:111]
	v_pk_add_f32 v[110:111], v[122:123], v[124:125]
	v_pk_add_f32 v[114:115], v[126:127], v[168:169]
	v_pk_add_f32 v[110:111], v[110:111], v[114:115]
	s_nop 0
	v_pk_add_f32 v[108:109], v[110:111], v[108:109]
	s_nop 0
	v_pk_add_f32 v[108:109], v[104:105], v[108:109]
	s_cbranch_execz .LBB0_303
	s_branch .LBB0_304

; __device__ __forceinline__ f32x2 gelu_pk(f32x2 v) {
;     const f32x2 av = __builtin_elementwise_abs(v), d = av * 0.2316418882f + 1.0f;
;     f32x2 t; t.x = __builtin_amdgcn_rcpf(d.x); t.y = __builtin_amdgcn_rcpf(d.y);
;     f32x2 q = t * 0.5307027145f + (-0.7265760135f); q = q * t + 0.7107068705f; q = q * t + (-0.142248368f); q = q * t + 0.127414796f; q = q * t;
;     const f32x2 s = (v * v) * (-0.72134752044f);
;     f32x2 e; e.x = __builtin_amdgcn_exp2f(s.x); e.y = __builtin_amdgcn_exp2f(s.y);
;     const f32x2 m = v * (q * e), r = v - m;
;     f32x2 o; o.x = v.x < 0.f ? m.x : r.x; o.y = v.y < 0.f ? m.y : r.y; return o;
; }
;     __device__ __forceinline__ void operator()(const f32x4 (&acc)[2][2][4][2], const Unit& u, int wr, int wc, int fr, int fq) const {
;     ...
;                 for (int bj = 0; bj < 2; ++bj) { f32x4 v0 = acc[ai][bj][m][0] * sc, v1 = acc[ai][bj][m][1] * sc;
;                     if (do_gelu) { f32x2 a = gelu_pk((f32x2){v0[0], v0[1]}), b = gelu_pk((f32x2){v0[2], v0[3]}), c = gelu_pk((f32x2){v1[0], v1[1]}), d = gelu_pk((f32x2){v1[2], v1[3]});
;                         v0 = (f32x4){a.x, a.y, b.x, b.y}; v1 = (f32x4){c.x, c.y, d.x, d.y}; }
.LBB0_308:
	v_pk_mul_f32 v[94:95], v[94:95], v[166:167] op_sel_hi:[1,0]
	v_pk_mul_f32 v[92:93], v[92:93], v[166:167] op_sel_hi:[1,0]
	v_pk_mul_f32 v[96:97], v[90:91], v[166:167] op_sel_hi:[1,0]
	s_and_b64 vcc, exec, s[42:43]
	s_waitcnt lgkmcnt(0)
	v_pk_mul_f32 v[98:99], v[88:89], v[166:167] op_sel_hi:[1,0]
	s_cbranch_vccnz .LBB0_310
	v_and_b32_e32 v89, 0x7fffffff, v93
	v_and_b32_e32 v88, 0x7fffffff, v92
	v_pk_fma_f32 v[88:89], v[88:89], s[28:29], 1.0 op_sel_hi:[1,0,0]
	s_mov_b32 s0, 0xbf3a00e3
	v_rcp_f32_e32 v90, v88
	v_rcp_f32_e32 v91, v89
	v_mov_b64_e32 v[88:89], s[0:1]
	v_pk_mul_f32 v[102:103], v[92:93], v[92:93]
	s_mov_b32 s0, 0xbf38aa3b
	v_pk_fma_f32 v[100:101], v[90:91], s[30:31], v[88:89] op_sel_hi:[1,0,0]
	v_pk_mul_f32 v[102:103], v[102:103], s[0:1] op_sel_hi:[1,0]
	v_pk_fma_f32 v[100:101], v[90:91], v[100:101], s[36:37] op_sel_hi:[1,1,0]
	v_exp_f32_e32 v102, v102
	v_exp_f32_e32 v103, v103
	v_pk_fma_f32 v[100:101], v[90:91], v[100:101], s[80:81] op_sel_hi:[1,1,0]
	v_cmp_gt_f32_e32 vcc, 0, v92
	v_pk_fma_f32 v[100:101], v[90:91], v[100:101], s[64:65] op_sel_hi:[1,1,0]
	v_pk_mul_f32 v[90:91], v[90:91], v[100:101]
	v_pk_mul_f32 v[100:101], v[94:95], v[94:95]
	v_pk_mul_f32 v[90:91], v[102:103], v[90:91]
	v_pk_mul_f32 v[100:101], v[100:101], s[0:1] op_sel_hi:[1,0]
	v_pk_mul_f32 v[102:103], v[92:93], v[90:91]
	v_pk_fma_f32 v[90:91], v[92:93], v[90:91], v[92:93] neg_lo:[1,0,0] neg_hi:[1,0,0]
	v_exp_f32_e32 v100, v100
	v_cndmask_b32_e32 v92, v90, v102, vcc
	v_cmp_gt_f32_e32 vcc, 0, v93
	v_and_b32_e32 v90, 0x7fffffff, v94
	v_exp_f32_e32 v101, v101
	v_cndmask_b32_e32 v93, v91, v103, vcc
	v_and_b32_e32 v91, 0x7fffffff, v95
	v_pk_fma_f32 v[90:91], v[90:91], s[28:29], 1.0 op_sel_hi:[1,0,0]
	v_cmp_gt_f32_e32 vcc, 0, v94
	v_rcp_f32_e32 v90, v90
	v_rcp_f32_e32 v91, v91
	s_nop 0
	v_pk_fma_f32 v[102:103], v[90:91], s[30:31], v[88:89] op_sel_hi:[1,0,0]
	v_pk_fma_f32 v[102:103], v[90:91], v[102:103], s[36:37] op_sel_hi:[1,1,0]
	v_pk_fma_f32 v[102:103], v[90:91], v[102:103], s[80:81] op_sel_hi:[1,1,0]
	v_pk_fma_f32 v[102:103], v[90:91], v[102:103], s[64:65] op_sel_hi:[1,1,0]
	v_pk_mul_f32 v[90:91], v[90:91], v[102:103]
	v_pk_mul_f32 v[102:103], v[98:99], v[98:99]
	v_pk_mul_f32 v[90:91], v[100:101], v[90:91]
	v_pk_mul_f32 v[102:103], v[102:103], s[0:1] op_sel_hi:[1,0]
	v_pk_mul_f32 v[100:101], v[94:95], v[90:91]
	v_pk_fma_f32 v[90:91], v[94:95], v[90:91], v[94:95] neg_lo:[1,0,0] neg_hi:[1,0,0]
	v_exp_f32_e32 v102, v102
	v_cndmask_b32_e32 v94, v90, v100, vcc
	v_cmp_gt_f32_e32 vcc, 0, v95
	v_and_b32_e32 v90, 0x7fffffff, v98
	v_exp_f32_e32 v103, v103
	v_cndmask_b32_e32 v95, v91, v101, vcc
	v_and_b32_e32 v91, 0x7fffffff, v99
	v_pk_fma_f32 v[90:91], v[90:91], s[28:29], 1.0 op_sel_hi:[1,0,0]
	v_cmp_gt_f32_e32 vcc, 0, v98
	v_rcp_f32_e32 v90, v90
	v_rcp_f32_e32 v91, v91
	s_nop 0
	v_pk_fma_f32 v[100:101], v[90:91], s[30:31], v[88:89] op_sel_hi:[1,0,0]
	v_pk_fma_f32 v[100:101], v[90:91], v[100:101], s[36:37] op_sel_hi:[1,1,0]
	v_pk_fma_f32 v[100:101], v[90:91], v[100:101], s[80:81] op_sel_hi:[1,1,0]
	v_pk_fma_f32 v[100:101], v[90:91], v[100:101], s[64:65] op_sel_hi:[1,1,0]
	v_pk_mul_f32 v[90:91], v[90:91], v[100:101]
	v_pk_mul_f32 v[100:101], v[96:97], v[96:97]
	v_pk_mul_f32 v[90:91], v[102:103], v[90:91]
	v_pk_mul_f32 v[102:103], v[98:99], v[90:91]
	v_pk_fma_f32 v[90:91], v[98:99], v[90:91], v[98:99] neg_lo:[1,0,0] neg_hi:[1,0,0]
	v_cndmask_b32_e32 v98, v90, v102, vcc
	v_cmp_gt_f32_e32 vcc, 0, v99
	v_and_b32_e32 v90, 0x7fffffff, v96
	s_nop 0
	v_cndmask_b32_e32 v99, v91, v103, vcc
	v_and_b32_e32 v91, 0x7fffffff, v97
	v_pk_fma_f32 v[90:91], v[90:91], s[28:29], 1.0 op_sel_hi:[1,0,0]
	v_cmp_gt_f32_e32 vcc, 0, v96
	v_rcp_f32_e32 v90, v90
	v_rcp_f32_e32 v91, v91
	s_nop 0
	v_pk_fma_f32 v[88:89], v[90:91], s[30:31], v[88:89] op_sel_hi:[1,0,0]
	v_pk_fma_f32 v[88:89], v[90:91], v[88:89], s[36:37] op_sel_hi:[1,1,0]
	v_pk_fma_f32 v[88:89], v[90:91], v[88:89], s[80:81] op_sel_hi:[1,1,0]
	v_pk_fma_f32 v[88:89], v[90:91], v[88:89], s[64:65] op_sel_hi:[1,1,0]
	v_pk_mul_f32 v[88:89], v[90:91], v[88:89]
	v_pk_mul_f32 v[90:91], v[100:101], s[0:1] op_sel_hi:[1,0]
	v_exp_f32_e32 v90, v90
	v_exp_f32_e32 v91, v91
	s_nop 0
	v_pk_mul_f32 v[88:89], v[90:91], v[88:89]
	v_pk_mul_f32 v[90:91], v[96:97], v[88:89]
	v_pk_fma_f32 v[88:89], v[96:97], v[88:89], v[96:97] neg_lo:[1,0,0] neg_hi:[1,0,0]
	s_nop 0
	v_cndmask_b32_e32 v96, v88, v90, vcc
	v_cmp_gt_f32_e32 vcc, 0, v97
	s_nop 1
	v_cndmask_b32_e32 v97, v89, v91, vcc

; __device__ __forceinline__ unsigned cvt_pk_bf16(float lo, float hi) { unsigned r; asm volatile("v_cvt_pk_bf16_f32 %0, %1, %2" : "=v"(r) : "v"(lo), "v"(hi)); return r; }
; __device__ __forceinline__ f32x2 gelu_pk(f32x2 v) {
;     const f32x2 av = __builtin_elementwise_abs(v), d = av * 0.2316418882f + 1.0f;
;     f32x2 t; t.x = __builtin_amdgcn_rcpf(d.x); t.y = __builtin_amdgcn_rcpf(d.y);
;     f32x2 q = t * 0.5307027145f + (-0.7265760135f); q = q * t + 0.7107068705f; q = q * t + (-0.142248368f); q = q * t + 0.127414796f; q = q * t;
;     const f32x2 s = (v * v) * (-0.72134752044f);
;     f32x2 e; e.x = __builtin_amdgcn_exp2f(s.x); e.y = __builtin_amdgcn_exp2f(s.y);
;     const f32x2 m = v * (q * e), r = v - m;
;     f32x2 o; o.x = v.x < 0.f ? m.x : r.x; o.y = v.y < 0.f ? m.y : r.y; return o;
; }
;     __device__ __forceinline__ void operator()(const f32x4 (&acc)[2][2][4][2], const Unit& u, int wr, int wc, int fr, int fq) const {
;     ...
;                 for (int bj = 0; bj < 2; ++bj) { f32x4 v0 = acc[ai][bj][m][0] * sc, v1 = acc[ai][bj][m][1] * sc;
;                     if (do_gelu) { f32x2 a = gelu_pk((f32x2){v0[0], v0[1]}), b = gelu_pk((f32x2){v0[2], v0[3]}), c = gelu_pk((f32x2){v1[0], v1[1]}), d = gelu_pk((f32x2){v1[2], v1[3]});
;                         v0 = (f32x4){a.x, a.y, b.x, b.y}; v1 = (f32x4){c.x, c.y, d.x, d.y}; }
;                     if (do_stat) { s1 += ((v0[0] + v0[1]) + (v0[2] + v0[3])) + ((v1[0] + v1[1]) + (v1[2] + v1[3]));
;                         s2 += ((v0[0] * v0[0] + v0[1] * v0[1]) + (v0[2] * v0[2] + v0[3] * v0[3])) + ((v1[0] * v1[0] + v1[1] * v1[1]) + (v1[2] * v1[2] + v1[3] * v1[3])); }
;                     u32x4 w; w.x = cvt_pk_bf16(v0[0], v0[1]); w.y = cvt_pk_bf16(v0[2], v0[3]); w.z = cvt_pk_bf16(v1[0], v1[1]); w.w = cvt_pk_bf16(v1[2], v1[3]);
;                     *(u32x4*)(rowp + bj * HALF) = w; }
.LBB0_314:
	v_lshl_add_u64 v[90:91], s[16:17], 0, v[140:141]
	v_lshl_add_u64 v[90:91], v[90:91], 0, s[86:87]
	v_lshl_add_u64 v[90:91], v[90:91], 0, v[192:193]
	v_cvt_pk_bf16_f32 v92, v92, v93
	v_cvt_pk_bf16_f32 v93, v94, v95
	v_mov_b32_e32 v167, v166
	v_cvt_pk_bf16_f32 v94, v98, v99
	v_cvt_pk_bf16_f32 v95, v96, v97
	global_store_dwordx4 v[90:91], v[92:95], off
	v_pk_mul_f32 v[84:85], v[84:85], v[166:167]
	s_and_b64 vcc, exec, s[42:43]
	v_mov_b32_e32 v92, v166
	v_mov_b32_e32 v93, v166
	v_pk_mul_f32 v[86:87], v[86:87], v[92:93]
	v_pk_mul_f32 v[82:83], v[82:83], v[92:93]
	v_pk_mul_f32 v[80:81], v[80:81], v[166:167]
	s_cbranch_vccnz .LBB0_316
	v_and_b32_e32 v93, 0x7fffffff, v85
	v_and_b32_e32 v92, 0x7fffffff, v84
	v_pk_fma_f32 v[92:93], v[92:93], s[28:29], 1.0 op_sel_hi:[1,0,0]
	s_mov_b32 s0, 0xbf3a00e3
	v_rcp_f32_e32 v94, v92
	v_rcp_f32_e32 v95, v93
	v_mov_b64_e32 v[92:93], s[0:1]
	v_pk_mul_f32 v[98:99], v[84:85], v[84:85]
	s_mov_b32 s0, 0xbf38aa3b
	v_pk_fma_f32 v[96:97], v[94:95], s[30:31], v[92:93] op_sel_hi:[1,0,0]
	v_pk_mul_f32 v[98:99], v[98:99], s[0:1] op_sel_hi:[1,0]
	v_pk_fma_f32 v[96:97], v[94:95], v[96:97], s[36:37] op_sel_hi:[1,1,0]
	v_exp_f32_e32 v98, v98
	v_exp_f32_e32 v99, v99
	v_pk_fma_f32 v[96:97], v[94:95], v[96:97], s[80:81] op_sel_hi:[1,1,0]
	v_cmp_gt_f32_e32 vcc, 0, v84
	v_pk_fma_f32 v[96:97], v[94:95], v[96:97], s[64:65] op_sel_hi:[1,1,0]
	v_pk_mul_f32 v[94:95], v[94:95], v[96:97]
	v_pk_mul_f32 v[96:97], v[86:87], v[86:87]
	v_pk_mul_f32 v[94:95], v[98:99], v[94:95]
	v_pk_mul_f32 v[96:97], v[96:97], s[0:1] op_sel_hi:[1,0]
	v_pk_mul_f32 v[98:99], v[84:85], v[94:95]
	v_pk_fma_f32 v[94:95], v[84:85], v[94:95], v[84:85] neg_lo:[1,0,0] neg_hi:[1,0,0]
	v_exp_f32_e32 v96, v96
	v_cndmask_b32_e32 v84, v94, v98, vcc
	v_cmp_gt_f32_e32 vcc, 0, v85
	v_and_b32_e32 v94, 0x7fffffff, v86
	v_exp_f32_e32 v97, v97
	v_cndmask_b32_e32 v85, v95, v99, vcc
	v_and_b32_e32 v95, 0x7fffffff, v87
	v_pk_fma_f32 v[94:95], v[94:95], s[28:29], 1.0 op_sel_hi:[1,0,0]
	v_cmp_gt_f32_e32 vcc, 0, v86
	v_rcp_f32_e32 v94, v94
	v_rcp_f32_e32 v95, v95
	s_nop 0
	v_pk_fma_f32 v[98:99], v[94:95], s[30:31], v[92:93] op_sel_hi:[1,0,0]
	v_pk_fma_f32 v[98:99], v[94:95], v[98:99], s[36:37] op_sel_hi:[1,1,0]
	v_pk_fma_f32 v[98:99], v[94:95], v[98:99], s[80:81] op_sel_hi:[1,1,0]
	v_pk_fma_f32 v[98:99], v[94:95], v[98:99], s[64:65] op_sel_hi:[1,1,0]
	v_pk_mul_f32 v[94:95], v[94:95], v[98:99]
	v_pk_mul_f32 v[98:99], v[80:81], v[80:81]
	v_pk_mul_f32 v[94:95], v[96:97], v[94:95]
	v_pk_mul_f32 v[98:99], v[98:99], s[0:1] op_sel_hi:[1,0]
	v_pk_mul_f32 v[96:97], v[86:87], v[94:95]
	v_pk_fma_f32 v[94:95], v[86:87], v[94:95], v[86:87] neg_lo:[1,0,0] neg_hi:[1,0,0]
	v_exp_f32_e32 v98, v98
	v_cndmask_b32_e32 v86, v94, v96, vcc
	v_cmp_gt_f32_e32 vcc, 0, v87
	v_and_b32_e32 v94, 0x7fffffff, v80
	v_exp_f32_e32 v99, v99
	v_cndmask_b32_e32 v87, v95, v97, vcc
	v_and_b32_e32 v95, 0x7fffffff, v81
	v_pk_fma_f32 v[94:95], v[94:95], s[28:29], 1.0 op_sel_hi:[1,0,0]
	v_cmp_gt_f32_e32 vcc, 0, v80
	v_rcp_f32_e32 v94, v94
	v_rcp_f32_e32 v95, v95
	s_nop 0
	v_pk_fma_f32 v[96:97], v[94:95], s[30:31], v[92:93] op_sel_hi:[1,0,0]
	v_pk_fma_f32 v[96:97], v[94:95], v[96:97], s[36:37] op_sel_hi:[1,1,0]
	v_pk_fma_f32 v[96:97], v[94:95], v[96:97], s[80:81] op_sel_hi:[1,1,0]
	v_pk_fma_f32 v[96:97], v[94:95], v[96:97], s[64:65] op_sel_hi:[1,1,0]
	v_pk_mul_f32 v[94:95], v[94:95], v[96:97]
	v_pk_mul_f32 v[96:97], v[82:83], v[82:83]
	v_pk_mul_f32 v[94:95], v[98:99], v[94:95]
	v_pk_mul_f32 v[98:99], v[80:81], v[94:95]
	v_pk_fma_f32 v[94:95], v[80:81], v[94:95], v[80:81] neg_lo:[1,0,0] neg_hi:[1,0,0]
	v_cndmask_b32_e32 v80, v94, v98, vcc
	v_cmp_gt_f32_e32 vcc, 0, v81
	v_and_b32_e32 v94, 0x7fffffff, v82
	s_nop 0
	v_cndmask_b32_e32 v81, v95, v99, vcc
	v_and_b32_e32 v95, 0x7fffffff, v83
	v_pk_fma_f32 v[94:95], v[94:95], s[28:29], 1.0 op_sel_hi:[1,0,0]
	v_cmp_gt_f32_e32 vcc, 0, v82
	v_rcp_f32_e32 v94, v94
	v_rcp_f32_e32 v95, v95
	s_nop 0
	v_pk_fma_f32 v[92:93], v[94:95], s[30:31], v[92:93] op_sel_hi:[1,0,0]
	v_pk_fma_f32 v[92:93], v[94:95], v[92:93], s[36:37] op_sel_hi:[1,1,0]
	v_pk_fma_f32 v[92:93], v[94:95], v[92:93], s[80:81] op_sel_hi:[1,1,0]
	v_pk_fma_f32 v[92:93], v[94:95], v[92:93], s[64:65] op_sel_hi:[1,1,0]
	v_pk_mul_f32 v[92:93], v[94:95], v[92:93]
	v_pk_mul_f32 v[94:95], v[96:97], s[0:1] op_sel_hi:[1,0]
	v_exp_f32_e32 v94, v94
	v_exp_f32_e32 v95, v95
	s_nop 0
	v_pk_mul_f32 v[92:93], v[94:95], v[92:93]
	v_pk_mul_f32 v[94:95], v[82:83], v[92:93]
	v_pk_fma_f32 v[92:93], v[82:83], v[92:93], v[82:83] neg_lo:[1,0,0] neg_hi:[1,0,0]
	s_nop 0
	v_cndmask_b32_e32 v82, v92, v94, vcc
	v_cmp_gt_f32_e32 vcc, 0, v83
	s_nop 1
	v_cndmask_b32_e32 v83, v93, v95, vcc
.LBB0_316:
	s_and_b64 vcc, exec, s[92:93]
	s_cbranch_vccz .LBB0_318
	v_mul_f32_e32 v93, v84, v84
	v_mul_f32_e32 v95, v85, v85
	v_mul_f32_e32 v97, v86, v86
	v_mul_f32_e32 v99, v87, v87
	v_mov_b32_e32 v92, v84
	v_mov_b32_e32 v94, v85
	v_mov_b32_e32 v96, v86
	v_mov_b32_e32 v98, v87
	v_mul_f32_e32 v101, v80, v80
	v_mul_f32_e32 v103, v81, v81
	v_mul_f32_e32 v105, v82, v82
	v_mul_f32_e32 v107, v83, v83
	v_pk_add_f32 v[92:93], v[92:93], v[94:95]
	v_pk_add_f32 v[94:95], v[96:97], v[98:99]
	v_mov_b32_e32 v100, v80
	v_mov_b32_e32 v102, v81
	v_mov_b32_e32 v104, v82
	v_mov_b32_e32 v106, v83
	v_pk_add_f32 v[92:93], v[92:93], v[94:95]
	v_pk_add_f32 v[94:95], v[100:101], v[102:103]
	v_pk_add_f32 v[96:97], v[104:105], v[106:107]
	v_pk_add_f32 v[94:95], v[94:95], v[96:97]
	s_nop 0
	v_pk_add_f32 v[92:93], v[94:95], v[92:93]
	s_nop 0
	v_pk_add_f32 v[92:93], v[88:89], v[92:93]
	s_cbranch_execz .LBB0_319
	s_branch .LBB0_320

; __device__ __forceinline__ f32x2 gelu_pk(f32x2 v) {
;     const f32x2 av = __builtin_elementwise_abs(v), d = av * 0.2316418882f + 1.0f;
;     f32x2 t; t.x = __builtin_amdgcn_rcpf(d.x); t.y = __builtin_amdgcn_rcpf(d.y);
;     f32x2 q = t * 0.5307027145f + (-0.7265760135f); q = q * t + 0.7107068705f; q = q * t + (-0.142248368f); q = q * t + 0.127414796f; q = q * t;
;     const f32x2 s = (v * v) * (-0.72134752044f);
;     f32x2 e; e.x = __builtin_amdgcn_exp2f(s.x); e.y = __builtin_amdgcn_exp2f(s.y);
;     const f32x2 m = v * (q * e), r = v - m;
;     f32x2 o; o.x = v.x < 0.f ? m.x : r.x; o.y = v.y < 0.f ? m.y : r.y; return o;
;     __device__ __forceinline__ void operator()(const f32x4 (&acc)[2][2][4][2], const Unit& u, int wr, int wc, int fr, int fq) const {
;     ...
;                 for (int bj = 0; bj < 2; ++bj) { f32x4 v0 = acc[ai][bj][m][0] * sc, v1 = acc[ai][bj][m][1] * sc;
;                     if (do_gelu) { f32x2 a = gelu_pk((f32x2){v0[0], v0[1]}), b = gelu_pk((f32x2){v0[2], v0[3]}), c = gelu_pk((f32x2){v1[0], v1[1]}), d = gelu_pk((f32x2){v1[2], v1[3]});
;                         v0 = (f32x4){a.x, a.y, b.x, b.y}; v1 = (f32x4){c.x, c.y, d.x, d.y}; }
.LBB0_324:
	v_pk_mul_f32 v[78:79], v[78:79], v[164:165] op_sel_hi:[1,0]
	v_pk_mul_f32 v[76:77], v[76:77], v[164:165] op_sel_hi:[1,0]
	v_pk_mul_f32 v[80:81], v[74:75], v[164:165] op_sel_hi:[1,0]
	s_and_b64 vcc, exec, s[42:43]
	s_waitcnt lgkmcnt(0)
	v_pk_mul_f32 v[82:83], v[72:73], v[164:165] op_sel_hi:[1,0]
	s_cbranch_vccnz .LBB0_326
	v_and_b32_e32 v73, 0x7fffffff, v77
	v_and_b32_e32 v72, 0x7fffffff, v76
	v_pk_fma_f32 v[72:73], v[72:73], s[28:29], 1.0 op_sel_hi:[1,0,0]
	s_mov_b32 s0, 0xbf3a00e3
	v_rcp_f32_e32 v74, v72
	v_rcp_f32_e32 v75, v73
	v_mov_b64_e32 v[72:73], s[0:1]
	v_pk_mul_f32 v[86:87], v[76:77], v[76:77]
	s_mov_b32 s0, 0xbf38aa3b
	v_pk_fma_f32 v[84:85], v[74:75], s[30:31], v[72:73] op_sel_hi:[1,0,0]
	v_pk_mul_f32 v[86:87], v[86:87], s[0:1] op_sel_hi:[1,0]
	v_pk_fma_f32 v[84:85], v[74:75], v[84:85], s[36:37] op_sel_hi:[1,1,0]
	v_exp_f32_e32 v86, v86
	v_exp_f32_e32 v87, v87
	v_pk_fma_f32 v[84:85], v[74:75], v[84:85], s[80:81] op_sel_hi:[1,1,0]
	v_cmp_gt_f32_e32 vcc, 0, v76
	v_pk_fma_f32 v[84:85], v[74:75], v[84:85], s[64:65] op_sel_hi:[1,1,0]
	v_pk_mul_f32 v[74:75], v[74:75], v[84:85]
	v_pk_mul_f32 v[84:85], v[78:79], v[78:79]
	v_pk_mul_f32 v[74:75], v[86:87], v[74:75]
	v_pk_mul_f32 v[84:85], v[84:85], s[0:1] op_sel_hi:[1,0]
	v_pk_mul_f32 v[86:87], v[76:77], v[74:75]
	v_pk_fma_f32 v[74:75], v[76:77], v[74:75], v[76:77] neg_lo:[1,0,0] neg_hi:[1,0,0]
	v_exp_f32_e32 v84, v84
	v_cndmask_b32_e32 v76, v74, v86, vcc
	v_cmp_gt_f32_e32 vcc, 0, v77
	v_and_b32_e32 v74, 0x7fffffff, v78
	v_exp_f32_e32 v85, v85
	v_cndmask_b32_e32 v77, v75, v87, vcc
	v_and_b32_e32 v75, 0x7fffffff, v79
	v_pk_fma_f32 v[74:75], v[74:75], s[28:29], 1.0 op_sel_hi:[1,0,0]
	v_cmp_gt_f32_e32 vcc, 0, v78
	v_rcp_f32_e32 v74, v74
	v_rcp_f32_e32 v75, v75
	s_nop 0
	v_pk_fma_f32 v[86:87], v[74:75], s[30:31], v[72:73] op_sel_hi:[1,0,0]
	v_pk_fma_f32 v[86:87], v[74:75], v[86:87], s[36:37] op_sel_hi:[1,1,0]
	v_pk_fma_f32 v[86:87], v[74:75], v[86:87], s[80:81] op_sel_hi:[1,1,0]
	v_pk_fma_f32 v[86:87], v[74:75], v[86:87], s[64:65] op_sel_hi:[1,1,0]
	v_pk_mul_f32 v[74:75], v[74:75], v[86:87]
	v_pk_mul_f32 v[86:87], v[82:83], v[82:83]
	v_pk_mul_f32 v[74:75], v[84:85], v[74:75]
	v_pk_mul_f32 v[86:87], v[86:87], s[0:1] op_sel_hi:[1,0]
	v_pk_mul_f32 v[84:85], v[78:79], v[74:75]
	v_pk_fma_f32 v[74:75], v[78:79], v[74:75], v[78:79] neg_lo:[1,0,0] neg_hi:[1,0,0]
	v_exp_f32_e32 v86, v86
	v_cndmask_b32_e32 v78, v74, v84, vcc
	v_cmp_gt_f32_e32 vcc, 0, v79
	v_and_b32_e32 v74, 0x7fffffff, v82
	v_exp_f32_e32 v87, v87
	v_cndmask_b32_e32 v79, v75, v85, vcc
	v_and_b32_e32 v75, 0x7fffffff, v83
	v_pk_fma_f32 v[74:75], v[74:75], s[28:29], 1.0 op_sel_hi:[1,0,0]
	v_cmp_gt_f32_e32 vcc, 0, v82
	v_rcp_f32_e32 v74, v74
	v_rcp_f32_e32 v75, v75
	s_nop 0
	v_pk_fma_f32 v[84:85], v[74:75], s[30:31], v[72:73] op_sel_hi:[1,0,0]
	v_pk_fma_f32 v[84:85], v[74:75], v[84:85], s[36:37] op_sel_hi:[1,1,0]
	v_pk_fma_f32 v[84:85], v[74:75], v[84:85], s[80:81] op_sel_hi:[1,1,0]
	v_pk_fma_f32 v[84:85], v[74:75], v[84:85], s[64:65] op_sel_hi:[1,1,0]
	v_pk_mul_f32 v[74:75], v[74:75], v[84:85]
	v_pk_mul_f32 v[84:85], v[80:81], v[80:81]
	v_pk_mul_f32 v[74:75], v[86:87], v[74:75]
	v_pk_mul_f32 v[86:87], v[82:83], v[74:75]
	v_pk_fma_f32 v[74:75], v[82:83], v[74:75], v[82:83] neg_lo:[1,0,0] neg_hi:[1,0,0]
	v_cndmask_b32_e32 v82, v74, v86, vcc
	v_cmp_gt_f32_e32 vcc, 0, v83
	v_and_b32_e32 v74, 0x7fffffff, v80
	s_nop 0
	v_cndmask_b32_e32 v83, v75, v87, vcc
	v_and_b32_e32 v75, 0x7fffffff, v81
	v_pk_fma_f32 v[74:75], v[74:75], s[28:29], 1.0 op_sel_hi:[1,0,0]
	v_cmp_gt_f32_e32 vcc, 0, v80
	v_rcp_f32_e32 v74, v74
	v_rcp_f32_e32 v75, v75
	s_nop 0
	v_pk_fma_f32 v[72:73], v[74:75], s[30:31], v[72:73] op_sel_hi:[1,0,0]
	v_pk_fma_f32 v[72:73], v[74:75], v[72:73], s[36:37] op_sel_hi:[1,1,0]
	v_pk_fma_f32 v[72:73], v[74:75], v[72:73], s[80:81] op_sel_hi:[1,1,0]
	v_pk_fma_f32 v[72:73], v[74:75], v[72:73], s[64:65] op_sel_hi:[1,1,0]
	v_pk_mul_f32 v[72:73], v[74:75], v[72:73]
	v_pk_mul_f32 v[74:75], v[84:85], s[0:1] op_sel_hi:[1,0]
	v_exp_f32_e32 v74, v74
	v_exp_f32_e32 v75, v75
	s_nop 0
	v_pk_mul_f32 v[72:73], v[74:75], v[72:73]
	v_pk_mul_f32 v[74:75], v[80:81], v[72:73]
	v_pk_fma_f32 v[72:73], v[80:81], v[72:73], v[80:81] neg_lo:[1,0,0] neg_hi:[1,0,0]
	s_nop 0
	v_cndmask_b32_e32 v80, v72, v74, vcc
	v_cmp_gt_f32_e32 vcc, 0, v81
	s_nop 1
	v_cndmask_b32_e32 v81, v73, v75, vcc

; __device__ __forceinline__ unsigned cvt_pk_bf16(float lo, float hi) { unsigned r; asm volatile("v_cvt_pk_bf16_f32 %0, %1, %2" : "=v"(r) : "v"(lo), "v"(hi)); return r; }
; __device__ __forceinline__ f32x2 gelu_pk(f32x2 v) {
;     const f32x2 av = __builtin_elementwise_abs(v), d = av * 0.2316418882f + 1.0f;
;     f32x2 t; t.x = __builtin_amdgcn_rcpf(d.x); t.y = __builtin_amdgcn_rcpf(d.y);
;     f32x2 q = t * 0.5307027145f + (-0.7265760135f); q = q * t + 0.7107068705f; q = q * t + (-0.142248368f); q = q * t + 0.127414796f; q = q * t;
;     const f32x2 s = (v * v) * (-0.72134752044f);
;     f32x2 e; e.x = __builtin_amdgcn_exp2f(s.x); e.y = __builtin_amdgcn_exp2f(s.y);
;     const f32x2 m = v * (q * e), r = v - m;
;     f32x2 o; o.x = v.x < 0.f ? m.x : r.x; o.y = v.y < 0.f ? m.y : r.y; return o;
;     __device__ __forceinline__ void operator()(const f32x4 (&acc)[2][2][4][2], const Unit& u, int wr, int wc, int fr, int fq) const {
;     ...
;             for (int m = 0; m < 4; ++m) { bf16_t* rowp = O + (size_t)(u.pm >> 5) * bgap + (size_t)u.pm * sm + (size_t)u.pn * sn + (size_t)(wr * 64 + fr + ai * HALF + m * 16) * ldc + wc * 32 + 8 * fq; const float sc = rs[ai][m]; float s1 = 0.f, s2 = 0.f;
; #pragma unroll
;                 for (int bj = 0; bj < 2; ++bj) { f32x4 v0 = acc[ai][bj][m][0] * sc, v1 = acc[ai][bj][m][1] * sc;
;                     if (do_gelu) { f32x2 a = gelu_pk((f32x2){v0[0], v0[1]}), b = gelu_pk((f32x2){v0[2], v0[3]}), c = gelu_pk((f32x2){v1[0], v1[1]}), d = gelu_pk((f32x2){v1[2], v1[3]});
;                         v0 = (f32x4){a.x, a.y, b.x, b.y}; v1 = (f32x4){c.x, c.y, d.x, d.y}; }
;                     if (do_stat) { s1 += ((v0[0] + v0[1]) + (v0[2] + v0[3])) + ((v1[0] + v1[1]) + (v1[2] + v1[3]));
;                         s2 += ((v0[0] * v0[0] + v0[1] * v0[1]) + (v0[2] * v0[2] + v0[3] * v0[3])) + ((v1[0] * v1[0] + v1[1] * v1[1]) + (v1[2] * v1[2] + v1[3] * v1[3])); }
;                     u32x4 w; w.x = cvt_pk_bf16(v0[0], v0[1]); w.y = cvt_pk_bf16(v0[2], v0[3]); w.z = cvt_pk_bf16(v1[0], v1[1]); w.w = cvt_pk_bf16(v1[2], v1[3]);
;                     *(u32x4*)(rowp + bj * HALF) = w; }
.LBB0_330:
	v_lshl_add_u64 v[74:75], s[16:17], 0, v[142:143]
	v_lshl_add_u64 v[74:75], v[74:75], 0, s[86:87]
	v_lshl_add_u64 v[74:75], v[74:75], 0, v[192:193]
	v_cvt_pk_bf16_f32 v76, v76, v77
	v_cvt_pk_bf16_f32 v77, v78, v79
	v_mov_b32_e32 v165, v164
	v_cvt_pk_bf16_f32 v78, v82, v83
	v_cvt_pk_bf16_f32 v79, v80, v81
	global_store_dwordx4 v[74:75], v[76:79], off
	v_pk_mul_f32 v[68:69], v[68:69], v[164:165]
	s_and_b64 vcc, exec, s[42:43]
	v_mov_b32_e32 v76, v164
	v_mov_b32_e32 v77, v164
	v_pk_mul_f32 v[70:71], v[70:71], v[76:77]
	v_pk_mul_f32 v[66:67], v[66:67], v[76:77]
	v_pk_mul_f32 v[64:65], v[64:65], v[164:165]
	s_cbranch_vccnz .LBB0_332
	v_and_b32_e32 v77, 0x7fffffff, v69
	v_and_b32_e32 v76, 0x7fffffff, v68
	v_pk_fma_f32 v[76:77], v[76:77], s[28:29], 1.0 op_sel_hi:[1,0,0]
	s_mov_b32 s0, 0xbf3a00e3
	v_rcp_f32_e32 v78, v76
	v_rcp_f32_e32 v79, v77
	v_mov_b64_e32 v[76:77], s[0:1]
	v_pk_mul_f32 v[82:83], v[68:69], v[68:69]
	s_mov_b32 s0, 0xbf38aa3b
	v_pk_fma_f32 v[80:81], v[78:79], s[30:31], v[76:77] op_sel_hi:[1,0,0]
	v_pk_mul_f32 v[82:83], v[82:83], s[0:1] op_sel_hi:[1,0]
	v_pk_fma_f32 v[80:81], v[78:79], v[80:81], s[36:37] op_sel_hi:[1,1,0]
	v_exp_f32_e32 v82, v82
	v_exp_f32_e32 v83, v83
	v_pk_fma_f32 v[80:81], v[78:79], v[80:81], s[80:81] op_sel_hi:[1,1,0]
	v_cmp_gt_f32_e32 vcc, 0, v68
	v_pk_fma_f32 v[80:81], v[78:79], v[80:81], s[64:65] op_sel_hi:[1,1,0]
	v_pk_mul_f32 v[78:79], v[78:79], v[80:81]
	v_pk_mul_f32 v[80:81], v[70:71], v[70:71]
	v_pk_mul_f32 v[78:79], v[82:83], v[78:79]
	v_pk_mul_f32 v[80:81], v[80:81], s[0:1] op_sel_hi:[1,0]
	v_pk_mul_f32 v[82:83], v[68:69], v[78:79]
	v_pk_fma_f32 v[78:79], v[68:69], v[78:79], v[68:69] neg_lo:[1,0,0] neg_hi:[1,0,0]
	v_exp_f32_e32 v80, v80
	v_cndmask_b32_e32 v68, v78, v82, vcc
	v_cmp_gt_f32_e32 vcc, 0, v69
	v_and_b32_e32 v78, 0x7fffffff, v70
	v_exp_f32_e32 v81, v81
	v_cndmask_b32_e32 v69, v79, v83, vcc
	v_and_b32_e32 v79, 0x7fffffff, v71
	v_pk_fma_f32 v[78:79], v[78:79], s[28:29], 1.0 op_sel_hi:[1,0,0]
	v_cmp_gt_f32_e32 vcc, 0, v70
	v_rcp_f32_e32 v78, v78
	v_rcp_f32_e32 v79, v79
	s_nop 0
	v_pk_fma_f32 v[82:83], v[78:79], s[30:31], v[76:77] op_sel_hi:[1,0,0]
	v_pk_fma_f32 v[82:83], v[78:79], v[82:83], s[36:37] op_sel_hi:[1,1,0]
	v_pk_fma_f32 v[82:83], v[78:79], v[82:83], s[80:81] op_sel_hi:[1,1,0]
	v_pk_fma_f32 v[82:83], v[78:79], v[82:83], s[64:65] op_sel_hi:[1,1,0]
	v_pk_mul_f32 v[78:79], v[78:79], v[82:83]
	v_pk_mul_f32 v[82:83], v[64:65], v[64:65]
	v_pk_mul_f32 v[78:79], v[80:81], v[78:79]
	v_pk_mul_f32 v[82:83], v[82:83], s[0:1] op_sel_hi:[1,0]
	v_pk_mul_f32 v[80:81], v[70:71], v[78:79]
	v_pk_fma_f32 v[78:79], v[70:71], v[78:79], v[70:71] neg_lo:[1,0,0] neg_hi:[1,0,0]
	v_exp_f32_e32 v82, v82
	v_cndmask_b32_e32 v70, v78, v80, vcc
	v_cmp_gt_f32_e32 vcc, 0, v71
	v_and_b32_e32 v78, 0x7fffffff, v64
	v_exp_f32_e32 v83, v83
	v_cndmask_b32_e32 v71, v79, v81, vcc
	v_and_b32_e32 v79, 0x7fffffff, v65
	v_pk_fma_f32 v[78:79], v[78:79], s[28:29], 1.0 op_sel_hi:[1,0,0]
	v_cmp_gt_f32_e32 vcc, 0, v64
	v_rcp_f32_e32 v78, v78
	v_rcp_f32_e32 v79, v79
	s_nop 0
	v_pk_fma_f32 v[80:81], v[78:79], s[30:31], v[76:77] op_sel_hi:[1,0,0]
	v_pk_fma_f32 v[80:81], v[78:79], v[80:81], s[36:37] op_sel_hi:[1,1,0]
	v_pk_fma_f32 v[80:81], v[78:79], v[80:81], s[80:81] op_sel_hi:[1,1,0]
	v_pk_fma_f32 v[80:81], v[78:79], v[80:81], s[64:65] op_sel_hi:[1,1,0]
	v_pk_mul_f32 v[78:79], v[78:79], v[80:81]
	v_pk_mul_f32 v[80:81], v[66:67], v[66:67]
	v_pk_mul_f32 v[78:79], v[82:83], v[78:79]
	v_pk_mul_f32 v[82:83], v[64:65], v[78:79]
	v_pk_fma_f32 v[78:79], v[64:65], v[78:79], v[64:65] neg_lo:[1,0,0] neg_hi:[1,0,0]
	v_cndmask_b32_e32 v64, v78, v82, vcc
	v_cmp_gt_f32_e32 vcc, 0, v65
	v_and_b32_e32 v78, 0x7fffffff, v66
	s_nop 0
	v_cndmask_b32_e32 v65, v79, v83, vcc
	v_and_b32_e32 v79, 0x7fffffff, v67
	v_pk_fma_f32 v[78:79], v[78:79], s[28:29], 1.0 op_sel_hi:[1,0,0]
	v_cmp_gt_f32_e32 vcc, 0, v66
	v_rcp_f32_e32 v78, v78
	v_rcp_f32_e32 v79, v79
	s_nop 0
	v_pk_fma_f32 v[76:77], v[78:79], s[30:31], v[76:77] op_sel_hi:[1,0,0]
	v_pk_fma_f32 v[76:77], v[78:79], v[76:77], s[36:37] op_sel_hi:[1,1,0]
	v_pk_fma_f32 v[76:77], v[78:79], v[76:77], s[80:81] op_sel_hi:[1,1,0]
	v_pk_fma_f32 v[76:77], v[78:79], v[76:77], s[64:65] op_sel_hi:[1,1,0]
	v_pk_mul_f32 v[76:77], v[78:79], v[76:77]
	v_pk_mul_f32 v[78:79], v[80:81], s[0:1] op_sel_hi:[1,0]
	v_exp_f32_e32 v78, v78
	v_exp_f32_e32 v79, v79
	s_nop 0
	v_pk_mul_f32 v[76:77], v[78:79], v[76:77]
	v_pk_mul_f32 v[78:79], v[66:67], v[76:77]
	v_pk_fma_f32 v[76:77], v[66:67], v[76:77], v[66:67] neg_lo:[1,0,0] neg_hi:[1,0,0]
	s_nop 0
	v_cndmask_b32_e32 v66, v76, v78, vcc
	v_cmp_gt_f32_e32 vcc, 0, v67
	s_nop 1
	v_cndmask_b32_e32 v67, v77, v79, vcc
.LBB0_332:
	s_and_b64 vcc, exec, s[92:93]
	s_cbranch_vccz .LBB0_334
	v_mul_f32_e32 v77, v68, v68
	v_mul_f32_e32 v79, v69, v69
	v_mul_f32_e32 v81, v70, v70
	v_mul_f32_e32 v83, v71, v71
	v_mov_b32_e32 v76, v68
	v_mov_b32_e32 v78, v69
	v_mov_b32_e32 v80, v70
	v_mov_b32_e32 v82, v71
	v_mul_f32_e32 v85, v64, v64
	v_mul_f32_e32 v87, v65, v65
	v_mul_f32_e32 v89, v66, v66
	v_mul_f32_e32 v91, v67, v67
	v_pk_add_f32 v[76:77], v[76:77], v[78:79]
	v_pk_add_f32 v[78:79], v[80:81], v[82:83]
	v_mov_b32_e32 v84, v64
	v_mov_b32_e32 v86, v65
	v_mov_b32_e32 v88, v66
	v_mov_b32_e32 v90, v67
	v_pk_add_f32 v[76:77], v[76:77], v[78:79]
	v_pk_add_f32 v[78:79], v[84:85], v[86:87]
	v_pk_add_f32 v[80:81], v[88:89], v[90:91]
	v_pk_add_f32 v[78:79], v[78:79], v[80:81]
	s_nop 0
	v_pk_add_f32 v[76:77], v[78:79], v[76:77]
	s_nop 0
	v_pk_add_f32 v[76:77], v[72:73], v[76:77]
	s_cbranch_execz .LBB0_335
	s_branch .LBB0_336

; __device__ __forceinline__ f32x2 gelu_pk(f32x2 v) {
;     const f32x2 av = __builtin_elementwise_abs(v), d = av * 0.2316418882f + 1.0f;
;     f32x2 t; t.x = __builtin_amdgcn_rcpf(d.x); t.y = __builtin_amdgcn_rcpf(d.y);
;     f32x2 q = t * 0.5307027145f + (-0.7265760135f); q = q * t + 0.7107068705f; q = q * t + (-0.142248368f); q = q * t + 0.127414796f; q = q * t;
;     const f32x2 s = (v * v) * (-0.72134752044f);
;     f32x2 e; e.x = __builtin_amdgcn_exp2f(s.x); e.y = __builtin_amdgcn_exp2f(s.y);
;     const f32x2 m = v * (q * e), r = v - m;
;     f32x2 o; o.x = v.x < 0.f ? m.x : r.x; o.y = v.y < 0.f ? m.y : r.y; return o;
;     __device__ __forceinline__ void operator()(const f32x4 (&acc)[2][2][4][2], const Unit& u, int wr, int wc, int fr, int fq) const {
;     ...
;                 for (int bj = 0; bj < 2; ++bj) { f32x4 v0 = acc[ai][bj][m][0] * sc, v1 = acc[ai][bj][m][1] * sc;
;                     if (do_gelu) { f32x2 a = gelu_pk((f32x2){v0[0], v0[1]}), b = gelu_pk((f32x2){v0[2], v0[3]}), c = gelu_pk((f32x2){v1[0], v1[1]}), d = gelu_pk((f32x2){v1[2], v1[3]});
;                         v0 = (f32x4){a.x, a.y, b.x, b.y}; v1 = (f32x4){c.x, c.y, d.x, d.y}; }
.LBB0_340:
	v_pk_mul_f32 v[62:63], v[62:63], v[162:163] op_sel_hi:[1,0]
	v_pk_mul_f32 v[60:61], v[60:61], v[162:163] op_sel_hi:[1,0]
	v_pk_mul_f32 v[64:65], v[58:59], v[162:163] op_sel_hi:[1,0]
	s_and_b64 vcc, exec, s[42:43]
	s_waitcnt lgkmcnt(0)
	v_pk_mul_f32 v[66:67], v[56:57], v[162:163] op_sel_hi:[1,0]
	s_cbranch_vccnz .LBB0_342
	v_and_b32_e32 v57, 0x7fffffff, v61
	v_and_b32_e32 v56, 0x7fffffff, v60
	v_pk_fma_f32 v[56:57], v[56:57], s[28:29], 1.0 op_sel_hi:[1,0,0]
	s_mov_b32 s0, 0xbf3a00e3
	v_rcp_f32_e32 v58, v56
	v_rcp_f32_e32 v59, v57
	v_mov_b64_e32 v[56:57], s[0:1]
	v_pk_mul_f32 v[70:71], v[60:61], v[60:61]
	s_mov_b32 s0, 0xbf38aa3b
	v_pk_fma_f32 v[68:69], v[58:59], s[30:31], v[56:57] op_sel_hi:[1,0,0]
	v_pk_mul_f32 v[70:71], v[70:71], s[0:1] op_sel_hi:[1,0]
	v_pk_fma_f32 v[68:69], v[58:59], v[68:69], s[36:37] op_sel_hi:[1,1,0]
	v_exp_f32_e32 v70, v70
	v_exp_f32_e32 v71, v71
	v_pk_fma_f32 v[68:69], v[58:59], v[68:69], s[80:81] op_sel_hi:[1,1,0]
	v_cmp_gt_f32_e32 vcc, 0, v60
	v_pk_fma_f32 v[68:69], v[58:59], v[68:69], s[64:65] op_sel_hi:[1,1,0]
	v_pk_mul_f32 v[58:59], v[58:59], v[68:69]
	v_pk_mul_f32 v[68:69], v[62:63], v[62:63]
	v_pk_mul_f32 v[58:59], v[70:71], v[58:59]
	v_pk_mul_f32 v[68:69], v[68:69], s[0:1] op_sel_hi:[1,0]
	v_pk_mul_f32 v[70:71], v[60:61], v[58:59]
	v_pk_fma_f32 v[58:59], v[60:61], v[58:59], v[60:61] neg_lo:[1,0,0] neg_hi:[1,0,0]
	v_exp_f32_e32 v68, v68
	v_cndmask_b32_e32 v60, v58, v70, vcc
	v_cmp_gt_f32_e32 vcc, 0, v61
	v_and_b32_e32 v58, 0x7fffffff, v62
	v_exp_f32_e32 v69, v69
	v_cndmask_b32_e32 v61, v59, v71, vcc
	v_and_b32_e32 v59, 0x7fffffff, v63
	v_pk_fma_f32 v[58:59], v[58:59], s[28:29], 1.0 op_sel_hi:[1,0,0]
	v_cmp_gt_f32_e32 vcc, 0, v62
	v_rcp_f32_e32 v58, v58
	v_rcp_f32_e32 v59, v59
	s_nop 0
	v_pk_fma_f32 v[70:71], v[58:59], s[30:31], v[56:57] op_sel_hi:[1,0,0]
	v_pk_fma_f32 v[70:71], v[58:59], v[70:71], s[36:37] op_sel_hi:[1,1,0]
	v_pk_fma_f32 v[70:71], v[58:59], v[70:71], s[80:81] op_sel_hi:[1,1,0]
	v_pk_fma_f32 v[70:71], v[58:59], v[70:71], s[64:65] op_sel_hi:[1,1,0]
	v_pk_mul_f32 v[58:59], v[58:59], v[70:71]
	v_pk_mul_f32 v[70:71], v[66:67], v[66:67]
	v_pk_mul_f32 v[58:59], v[68:69], v[58:59]
	v_pk_mul_f32 v[70:71], v[70:71], s[0:1] op_sel_hi:[1,0]
	v_pk_mul_f32 v[68:69], v[62:63], v[58:59]
	v_pk_fma_f32 v[58:59], v[62:63], v[58:59], v[62:63] neg_lo:[1,0,0] neg_hi:[1,0,0]
	v_exp_f32_e32 v70, v70
	v_cndmask_b32_e32 v62, v58, v68, vcc
	v_cmp_gt_f32_e32 vcc, 0, v63
	v_and_b32_e32 v58, 0x7fffffff, v66
	v_exp_f32_e32 v71, v71
	v_cndmask_b32_e32 v63, v59, v69, vcc
	v_and_b32_e32 v59, 0x7fffffff, v67
	v_pk_fma_f32 v[58:59], v[58:59], s[28:29], 1.0 op_sel_hi:[1,0,0]
	v_cmp_gt_f32_e32 vcc, 0, v66
	v_rcp_f32_e32 v58, v58
	v_rcp_f32_e32 v59, v59
	s_nop 0
	v_pk_fma_f32 v[68:69], v[58:59], s[30:31], v[56:57] op_sel_hi:[1,0,0]
	v_pk_fma_f32 v[68:69], v[58:59], v[68:69], s[36:37] op_sel_hi:[1,1,0]
	v_pk_fma_f32 v[68:69], v[58:59], v[68:69], s[80:81] op_sel_hi:[1,1,0]
	v_pk_fma_f32 v[68:69], v[58:59], v[68:69], s[64:65] op_sel_hi:[1,1,0]
	v_pk_mul_f32 v[58:59], v[58:59], v[68:69]
	v_pk_mul_f32 v[68:69], v[64:65], v[64:65]
	v_pk_mul_f32 v[58:59], v[70:71], v[58:59]
	v_pk_mul_f32 v[70:71], v[66:67], v[58:59]
	v_pk_fma_f32 v[58:59], v[66:67], v[58:59], v[66:67] neg_lo:[1,0,0] neg_hi:[1,0,0]
	v_cndmask_b32_e32 v66, v58, v70, vcc
	v_cmp_gt_f32_e32 vcc, 0, v67
	v_and_b32_e32 v58, 0x7fffffff, v64
	s_nop 0
	v_cndmask_b32_e32 v67, v59, v71, vcc
	v_and_b32_e32 v59, 0x7fffffff, v65
	v_pk_fma_f32 v[58:59], v[58:59], s[28:29], 1.0 op_sel_hi:[1,0,0]
	v_cmp_gt_f32_e32 vcc, 0, v64
	v_rcp_f32_e32 v58, v58
	v_rcp_f32_e32 v59, v59
	s_nop 0
	v_pk_fma_f32 v[56:57], v[58:59], s[30:31], v[56:57] op_sel_hi:[1,0,0]
	v_pk_fma_f32 v[56:57], v[58:59], v[56:57], s[36:37] op_sel_hi:[1,1,0]
	v_pk_fma_f32 v[56:57], v[58:59], v[56:57], s[80:81] op_sel_hi:[1,1,0]
	v_pk_fma_f32 v[56:57], v[58:59], v[56:57], s[64:65] op_sel_hi:[1,1,0]
	v_pk_mul_f32 v[56:57], v[58:59], v[56:57]
	v_pk_mul_f32 v[58:59], v[68:69], s[0:1] op_sel_hi:[1,0]
	v_exp_f32_e32 v58, v58
	v_exp_f32_e32 v59, v59
	s_nop 0
	v_pk_mul_f32 v[56:57], v[58:59], v[56:57]
	v_pk_mul_f32 v[58:59], v[64:65], v[56:57]
	v_pk_fma_f32 v[56:57], v[64:65], v[56:57], v[64:65] neg_lo:[1,0,0] neg_hi:[1,0,0]
	s_nop 0
	v_cndmask_b32_e32 v64, v56, v58, vcc
	v_cmp_gt_f32_e32 vcc, 0, v65
	s_nop 1
	v_cndmask_b32_e32 v65, v57, v59, vcc

; __device__ __forceinline__ unsigned cvt_pk_bf16(float lo, float hi) { unsigned r; asm volatile("v_cvt_pk_bf16_f32 %0, %1, %2" : "=v"(r) : "v"(lo), "v"(hi)); return r; }
; __device__ __forceinline__ f32x2 gelu_pk(f32x2 v) {
;     const f32x2 av = __builtin_elementwise_abs(v), d = av * 0.2316418882f + 1.0f;
;     f32x2 t; t.x = __builtin_amdgcn_rcpf(d.x); t.y = __builtin_amdgcn_rcpf(d.y);
;     f32x2 q = t * 0.5307027145f + (-0.7265760135f); q = q * t + 0.7107068705f; q = q * t + (-0.142248368f); q = q * t + 0.127414796f; q = q * t;
;     const f32x2 s = (v * v) * (-0.72134752044f);
;     f32x2 e; e.x = __builtin_amdgcn_exp2f(s.x); e.y = __builtin_amdgcn_exp2f(s.y);
;     const f32x2 m = v * (q * e), r = v - m;
;     f32x2 o; o.x = v.x < 0.f ? m.x : r.x; o.y = v.y < 0.f ? m.y : r.y; return o;
;     __device__ __forceinline__ void operator()(const f32x4 (&acc)[2][2][4][2], const Unit& u, int wr, int wc, int fr, int fq) const {
;     ...
;             for (int m = 0; m < 4; ++m) { bf16_t* rowp = O + (size_t)(u.pm >> 5) * bgap + (size_t)u.pm * sm + (size_t)u.pn * sn + (size_t)(wr * 64 + fr + ai * HALF + m * 16) * ldc + wc * 32 + 8 * fq; const float sc = rs[ai][m]; float s1 = 0.f, s2 = 0.f;
; #pragma unroll
;                 for (int bj = 0; bj < 2; ++bj) { f32x4 v0 = acc[ai][bj][m][0] * sc, v1 = acc[ai][bj][m][1] * sc;
;                     if (do_gelu) { f32x2 a = gelu_pk((f32x2){v0[0], v0[1]}), b = gelu_pk((f32x2){v0[2], v0[3]}), c = gelu_pk((f32x2){v1[0], v1[1]}), d = gelu_pk((f32x2){v1[2], v1[3]});
;                         v0 = (f32x4){a.x, a.y, b.x, b.y}; v1 = (f32x4){c.x, c.y, d.x, d.y}; }
;                     if (do_stat) { s1 += ((v0[0] + v0[1]) + (v0[2] + v0[3])) + ((v1[0] + v1[1]) + (v1[2] + v1[3]));
;                         s2 += ((v0[0] * v0[0] + v0[1] * v0[1]) + (v0[2] * v0[2] + v0[3] * v0[3])) + ((v1[0] * v1[0] + v1[1] * v1[1]) + (v1[2] * v1[2] + v1[3] * v1[3])); }
;                     u32x4 w; w.x = cvt_pk_bf16(v0[0], v0[1]); w.y = cvt_pk_bf16(v0[2], v0[3]); w.z = cvt_pk_bf16(v1[0], v1[1]); w.w = cvt_pk_bf16(v1[2], v1[3]);
;                     *(u32x4*)(rowp + bj * HALF) = w; }
.LBB0_346:
	v_lshl_add_u64 v[58:59], s[16:17], 0, v[144:145]
	v_lshl_add_u64 v[58:59], v[58:59], 0, s[86:87]
	v_lshl_add_u64 v[58:59], v[58:59], 0, v[192:193]
	v_cvt_pk_bf16_f32 v60, v60, v61
	v_cvt_pk_bf16_f32 v61, v62, v63
	v_mov_b32_e32 v163, v162
	v_cvt_pk_bf16_f32 v62, v66, v67
	v_cvt_pk_bf16_f32 v63, v64, v65
	global_store_dwordx4 v[58:59], v[60:63], off
	v_pk_mul_f32 v[52:53], v[52:53], v[162:163]
	s_and_b64 vcc, exec, s[42:43]
	v_mov_b32_e32 v60, v162
	v_mov_b32_e32 v61, v162
	v_pk_mul_f32 v[54:55], v[54:55], v[60:61]
	v_pk_mul_f32 v[50:51], v[50:51], v[60:61]
	v_pk_mul_f32 v[48:49], v[48:49], v[162:163]
	s_cbranch_vccnz .LBB0_348
	v_and_b32_e32 v61, 0x7fffffff, v53
	v_and_b32_e32 v60, 0x7fffffff, v52
	v_pk_fma_f32 v[60:61], v[60:61], s[28:29], 1.0 op_sel_hi:[1,0,0]
	s_mov_b32 s0, 0xbf3a00e3
	v_rcp_f32_e32 v62, v60
	v_rcp_f32_e32 v63, v61
	v_mov_b64_e32 v[60:61], s[0:1]
	v_pk_mul_f32 v[66:67], v[52:53], v[52:53]
	s_mov_b32 s0, 0xbf38aa3b
	v_pk_fma_f32 v[64:65], v[62:63], s[30:31], v[60:61] op_sel_hi:[1,0,0]
	v_pk_mul_f32 v[66:67], v[66:67], s[0:1] op_sel_hi:[1,0]
	v_pk_fma_f32 v[64:65], v[62:63], v[64:65], s[36:37] op_sel_hi:[1,1,0]
	v_exp_f32_e32 v66, v66
	v_exp_f32_e32 v67, v67
	v_pk_fma_f32 v[64:65], v[62:63], v[64:65], s[80:81] op_sel_hi:[1,1,0]
	v_cmp_gt_f32_e32 vcc, 0, v52
	v_pk_fma_f32 v[64:65], v[62:63], v[64:65], s[64:65] op_sel_hi:[1,1,0]
	v_pk_mul_f32 v[62:63], v[62:63], v[64:65]
	v_pk_mul_f32 v[64:65], v[54:55], v[54:55]
	v_pk_mul_f32 v[62:63], v[66:67], v[62:63]
	v_pk_mul_f32 v[64:65], v[64:65], s[0:1] op_sel_hi:[1,0]
	v_pk_mul_f32 v[66:67], v[52:53], v[62:63]
	v_pk_fma_f32 v[62:63], v[52:53], v[62:63], v[52:53] neg_lo:[1,0,0] neg_hi:[1,0,0]
	v_exp_f32_e32 v64, v64
	v_cndmask_b32_e32 v52, v62, v66, vcc
	v_cmp_gt_f32_e32 vcc, 0, v53
	v_and_b32_e32 v62, 0x7fffffff, v54
	v_exp_f32_e32 v65, v65
	v_cndmask_b32_e32 v53, v63, v67, vcc
	v_and_b32_e32 v63, 0x7fffffff, v55
	v_pk_fma_f32 v[62:63], v[62:63], s[28:29], 1.0 op_sel_hi:[1,0,0]
	v_cmp_gt_f32_e32 vcc, 0, v54
	v_rcp_f32_e32 v62, v62
	v_rcp_f32_e32 v63, v63
	s_nop 0
	v_pk_fma_f32 v[66:67], v[62:63], s[30:31], v[60:61] op_sel_hi:[1,0,0]
	v_pk_fma_f32 v[66:67], v[62:63], v[66:67], s[36:37] op_sel_hi:[1,1,0]
	v_pk_fma_f32 v[66:67], v[62:63], v[66:67], s[80:81] op_sel_hi:[1,1,0]
	v_pk_fma_f32 v[66:67], v[62:63], v[66:67], s[64:65] op_sel_hi:[1,1,0]
	v_pk_mul_f32 v[62:63], v[62:63], v[66:67]
	v_pk_mul_f32 v[66:67], v[48:49], v[48:49]
	v_pk_mul_f32 v[62:63], v[64:65], v[62:63]
	v_pk_mul_f32 v[66:67], v[66:67], s[0:1] op_sel_hi:[1,0]
	v_pk_mul_f32 v[64:65], v[54:55], v[62:63]
	v_pk_fma_f32 v[62:63], v[54:55], v[62:63], v[54:55] neg_lo:[1,0,0] neg_hi:[1,0,0]
	v_exp_f32_e32 v66, v66
	v_cndmask_b32_e32 v54, v62, v64, vcc
	v_cmp_gt_f32_e32 vcc, 0, v55
	v_and_b32_e32 v62, 0x7fffffff, v48
	v_exp_f32_e32 v67, v67
	v_cndmask_b32_e32 v55, v63, v65, vcc
	v_and_b32_e32 v63, 0x7fffffff, v49
	v_pk_fma_f32 v[62:63], v[62:63], s[28:29], 1.0 op_sel_hi:[1,0,0]
	v_cmp_gt_f32_e32 vcc, 0, v48
	v_rcp_f32_e32 v62, v62
	v_rcp_f32_e32 v63, v63
	s_nop 0
	v_pk_fma_f32 v[64:65], v[62:63], s[30:31], v[60:61] op_sel_hi:[1,0,0]
	v_pk_fma_f32 v[64:65], v[62:63], v[64:65], s[36:37] op_sel_hi:[1,1,0]
	v_pk_fma_f32 v[64:65], v[62:63], v[64:65], s[80:81] op_sel_hi:[1,1,0]
	v_pk_fma_f32 v[64:65], v[62:63], v[64:65], s[64:65] op_sel_hi:[1,1,0]
	v_pk_mul_f32 v[62:63], v[62:63], v[64:65]
	v_pk_mul_f32 v[64:65], v[50:51], v[50:51]
	v_pk_mul_f32 v[62:63], v[66:67], v[62:63]
	v_pk_mul_f32 v[66:67], v[48:49], v[62:63]
	v_pk_fma_f32 v[62:63], v[48:49], v[62:63], v[48:49] neg_lo:[1,0,0] neg_hi:[1,0,0]
	v_cndmask_b32_e32 v48, v62, v66, vcc
	v_cmp_gt_f32_e32 vcc, 0, v49
	v_and_b32_e32 v62, 0x7fffffff, v50
	s_nop 0
	v_cndmask_b32_e32 v49, v63, v67, vcc
	v_and_b32_e32 v63, 0x7fffffff, v51
	v_pk_fma_f32 v[62:63], v[62:63], s[28:29], 1.0 op_sel_hi:[1,0,0]
	v_cmp_gt_f32_e32 vcc, 0, v50
	v_rcp_f32_e32 v62, v62
	v_rcp_f32_e32 v63, v63
	s_nop 0
	v_pk_fma_f32 v[60:61], v[62:63], s[30:31], v[60:61] op_sel_hi:[1,0,0]
	v_pk_fma_f32 v[60:61], v[62:63], v[60:61], s[36:37] op_sel_hi:[1,1,0]
	v_pk_fma_f32 v[60:61], v[62:63], v[60:61], s[80:81] op_sel_hi:[1,1,0]
	v_pk_fma_f32 v[60:61], v[62:63], v[60:61], s[64:65] op_sel_hi:[1,1,0]
	v_pk_mul_f32 v[60:61], v[62:63], v[60:61]
	v_pk_mul_f32 v[62:63], v[64:65], s[0:1] op_sel_hi:[1,0]
	v_exp_f32_e32 v62, v62
	v_exp_f32_e32 v63, v63
	s_nop 0
	v_pk_mul_f32 v[60:61], v[62:63], v[60:61]
	v_pk_mul_f32 v[62:63], v[50:51], v[60:61]
	v_pk_fma_f32 v[60:61], v[50:51], v[60:61], v[50:51] neg_lo:[1,0,0] neg_hi:[1,0,0]
	s_nop 0
	v_cndmask_b32_e32 v50, v60, v62, vcc
	v_cmp_gt_f32_e32 vcc, 0, v51
	s_nop 1
	v_cndmask_b32_e32 v51, v61, v63, vcc
.LBB0_348:
	s_and_b64 vcc, exec, s[92:93]
	s_cbranch_vccz .LBB0_350
	v_mul_f32_e32 v61, v52, v52
	v_mul_f32_e32 v63, v53, v53
	v_mul_f32_e32 v65, v54, v54
	v_mul_f32_e32 v67, v55, v55
	v_mov_b32_e32 v60, v52
	v_mov_b32_e32 v62, v53
	v_mov_b32_e32 v64, v54
	v_mov_b32_e32 v66, v55
	v_mul_f32_e32 v69, v48, v48
	v_mul_f32_e32 v71, v49, v49
	v_mul_f32_e32 v73, v50, v50
	v_mul_f32_e32 v75, v51, v51
	v_pk_add_f32 v[60:61], v[60:61], v[62:63]
	v_pk_add_f32 v[62:63], v[64:65], v[66:67]
	v_mov_b32_e32 v68, v48
	v_mov_b32_e32 v70, v49
	v_mov_b32_e32 v72, v50
	v_mov_b32_e32 v74, v51
	v_pk_add_f32 v[60:61], v[60:61], v[62:63]
	v_pk_add_f32 v[62:63], v[68:69], v[70:71]
	v_pk_add_f32 v[64:65], v[72:73], v[74:75]
	v_pk_add_f32 v[62:63], v[62:63], v[64:65]
	s_nop 0
	v_pk_add_f32 v[60:61], v[62:63], v[60:61]
	s_nop 0
	v_pk_add_f32 v[60:61], v[56:57], v[60:61]
	s_cbranch_execz .LBB0_351
	s_branch .LBB0_352

; __device__ __forceinline__ f32x2 gelu_pk(f32x2 v) {
;     const f32x2 av = __builtin_elementwise_abs(v), d = av * 0.2316418882f + 1.0f;
;     f32x2 t; t.x = __builtin_amdgcn_rcpf(d.x); t.y = __builtin_amdgcn_rcpf(d.y);
;     f32x2 q = t * 0.5307027145f + (-0.7265760135f); q = q * t + 0.7107068705f; q = q * t + (-0.142248368f); q = q * t + 0.127414796f; q = q * t;
;     const f32x2 s = (v * v) * (-0.72134752044f);
;     f32x2 e; e.x = __builtin_amdgcn_exp2f(s.x); e.y = __builtin_amdgcn_exp2f(s.y);
;     const f32x2 m = v * (q * e), r = v - m;
;     f32x2 o; o.x = v.x < 0.f ? m.x : r.x; o.y = v.y < 0.f ? m.y : r.y; return o;
;     __device__ __forceinline__ void operator()(const f32x4 (&acc)[2][2][4][2], const Unit& u, int wr, int wc, int fr, int fq) const {
;     ...
;                 for (int bj = 0; bj < 2; ++bj) { f32x4 v0 = acc[ai][bj][m][0] * sc, v1 = acc[ai][bj][m][1] * sc;
;                     if (do_gelu) { f32x2 a = gelu_pk((f32x2){v0[0], v0[1]}), b = gelu_pk((f32x2){v0[2], v0[3]}), c = gelu_pk((f32x2){v1[0], v1[1]}), d = gelu_pk((f32x2){v1[2], v1[3]});
;                         v0 = (f32x4){a.x, a.y, b.x, b.y}; v1 = (f32x4){c.x, c.y, d.x, d.y}; }
.LBB0_356:
	v_pk_mul_f32 v[46:47], v[46:47], v[160:161] op_sel_hi:[1,0]
	v_pk_mul_f32 v[44:45], v[44:45], v[160:161] op_sel_hi:[1,0]
	v_pk_mul_f32 v[48:49], v[42:43], v[160:161] op_sel_hi:[1,0]
	s_and_b64 vcc, exec, s[42:43]
	s_waitcnt lgkmcnt(0)
	v_pk_mul_f32 v[50:51], v[40:41], v[160:161] op_sel_hi:[1,0]
	s_cbranch_vccnz .LBB0_358
	v_and_b32_e32 v41, 0x7fffffff, v45
	v_and_b32_e32 v40, 0x7fffffff, v44
	v_pk_fma_f32 v[40:41], v[40:41], s[28:29], 1.0 op_sel_hi:[1,0,0]
	s_mov_b32 s0, 0xbf3a00e3
	v_rcp_f32_e32 v42, v40
	v_rcp_f32_e32 v43, v41
	v_mov_b64_e32 v[40:41], s[0:1]
	v_pk_mul_f32 v[54:55], v[44:45], v[44:45]
	s_mov_b32 s0, 0xbf38aa3b
	v_pk_fma_f32 v[52:53], v[42:43], s[30:31], v[40:41] op_sel_hi:[1,0,0]
	v_pk_mul_f32 v[54:55], v[54:55], s[0:1] op_sel_hi:[1,0]
	v_pk_fma_f32 v[52:53], v[42:43], v[52:53], s[36:37] op_sel_hi:[1,1,0]
	v_exp_f32_e32 v54, v54
	v_exp_f32_e32 v55, v55
	v_pk_fma_f32 v[52:53], v[42:43], v[52:53], s[80:81] op_sel_hi:[1,1,0]
	v_cmp_gt_f32_e32 vcc, 0, v44
	v_pk_fma_f32 v[52:53], v[42:43], v[52:53], s[64:65] op_sel_hi:[1,1,0]
	v_pk_mul_f32 v[42:43], v[42:43], v[52:53]
	v_pk_mul_f32 v[52:53], v[46:47], v[46:47]
	v_pk_mul_f32 v[42:43], v[54:55], v[42:43]
	v_pk_mul_f32 v[52:53], v[52:53], s[0:1] op_sel_hi:[1,0]
	v_pk_mul_f32 v[54:55], v[44:45], v[42:43]
	v_pk_fma_f32 v[42:43], v[44:45], v[42:43], v[44:45] neg_lo:[1,0,0] neg_hi:[1,0,0]
	v_exp_f32_e32 v52, v52
	v_cndmask_b32_e32 v44, v42, v54, vcc
	v_cmp_gt_f32_e32 vcc, 0, v45
	v_and_b32_e32 v42, 0x7fffffff, v46
	v_exp_f32_e32 v53, v53
	v_cndmask_b32_e32 v45, v43, v55, vcc
	v_and_b32_e32 v43, 0x7fffffff, v47
	v_pk_fma_f32 v[42:43], v[42:43], s[28:29], 1.0 op_sel_hi:[1,0,0]
	v_cmp_gt_f32_e32 vcc, 0, v46
	v_rcp_f32_e32 v42, v42
	v_rcp_f32_e32 v43, v43
	s_nop 0
	v_pk_fma_f32 v[54:55], v[42:43], s[30:31], v[40:41] op_sel_hi:[1,0,0]
	v_pk_fma_f32 v[54:55], v[42:43], v[54:55], s[36:37] op_sel_hi:[1,1,0]
	v_pk_fma_f32 v[54:55], v[42:43], v[54:55], s[80:81] op_sel_hi:[1,1,0]
	v_pk_fma_f32 v[54:55], v[42:43], v[54:55], s[64:65] op_sel_hi:[1,1,0]
	v_pk_mul_f32 v[42:43], v[42:43], v[54:55]
	v_pk_mul_f32 v[54:55], v[50:51], v[50:51]
	v_pk_mul_f32 v[42:43], v[52:53], v[42:43]
	v_pk_mul_f32 v[54:55], v[54:55], s[0:1] op_sel_hi:[1,0]
	v_pk_mul_f32 v[52:53], v[46:47], v[42:43]
	v_pk_fma_f32 v[42:43], v[46:47], v[42:43], v[46:47] neg_lo:[1,0,0] neg_hi:[1,0,0]
	v_exp_f32_e32 v54, v54
	v_cndmask_b32_e32 v46, v42, v52, vcc
	v_cmp_gt_f32_e32 vcc, 0, v47
	v_and_b32_e32 v42, 0x7fffffff, v50
	v_exp_f32_e32 v55, v55
	v_cndmask_b32_e32 v47, v43, v53, vcc
	v_and_b32_e32 v43, 0x7fffffff, v51
	v_pk_fma_f32 v[42:43], v[42:43], s[28:29], 1.0 op_sel_hi:[1,0,0]
	v_cmp_gt_f32_e32 vcc, 0, v50
	v_rcp_f32_e32 v42, v42
	v_rcp_f32_e32 v43, v43
	s_nop 0
	v_pk_fma_f32 v[52:53], v[42:43], s[30:31], v[40:41] op_sel_hi:[1,0,0]
	v_pk_fma_f32 v[52:53], v[42:43], v[52:53], s[36:37] op_sel_hi:[1,1,0]
	v_pk_fma_f32 v[52:53], v[42:43], v[52:53], s[80:81] op_sel_hi:[1,1,0]
	v_pk_fma_f32 v[52:53], v[42:43], v[52:53], s[64:65] op_sel_hi:[1,1,0]
	v_pk_mul_f32 v[42:43], v[42:43], v[52:53]
	v_pk_mul_f32 v[52:53], v[48:49], v[48:49]
	v_pk_mul_f32 v[42:43], v[54:55], v[42:43]
	v_pk_mul_f32 v[54:55], v[50:51], v[42:43]
	v_pk_fma_f32 v[42:43], v[50:51], v[42:43], v[50:51] neg_lo:[1,0,0] neg_hi:[1,0,0]
	v_cndmask_b32_e32 v50, v42, v54, vcc
	v_cmp_gt_f32_e32 vcc, 0, v51
	v_and_b32_e32 v42, 0x7fffffff, v48
	s_nop 0
	v_cndmask_b32_e32 v51, v43, v55, vcc
	v_and_b32_e32 v43, 0x7fffffff, v49
	v_pk_fma_f32 v[42:43], v[42:43], s[28:29], 1.0 op_sel_hi:[1,0,0]
	v_cmp_gt_f32_e32 vcc, 0, v48
	v_rcp_f32_e32 v42, v42
	v_rcp_f32_e32 v43, v43
	s_nop 0
	v_pk_fma_f32 v[40:41], v[42:43], s[30:31], v[40:41] op_sel_hi:[1,0,0]
	v_pk_fma_f32 v[40:41], v[42:43], v[40:41], s[36:37] op_sel_hi:[1,1,0]
	v_pk_fma_f32 v[40:41], v[42:43], v[40:41], s[80:81] op_sel_hi:[1,1,0]
	v_pk_fma_f32 v[40:41], v[42:43], v[40:41], s[64:65] op_sel_hi:[1,1,0]
	v_pk_mul_f32 v[40:41], v[42:43], v[40:41]
	v_pk_mul_f32 v[42:43], v[52:53], s[0:1] op_sel_hi:[1,0]
	v_exp_f32_e32 v42, v42
	v_exp_f32_e32 v43, v43
	s_nop 0
	v_pk_mul_f32 v[40:41], v[42:43], v[40:41]
	v_pk_mul_f32 v[42:43], v[48:49], v[40:41]
	v_pk_fma_f32 v[40:41], v[48:49], v[40:41], v[48:49] neg_lo:[1,0,0] neg_hi:[1,0,0]
	s_nop 0
	v_cndmask_b32_e32 v48, v40, v42, vcc
	v_cmp_gt_f32_e32 vcc, 0, v49
	s_nop 1
	v_cndmask_b32_e32 v49, v41, v43, vcc

; __device__ __forceinline__ unsigned cvt_pk_bf16(float lo, float hi) { unsigned r; asm volatile("v_cvt_pk_bf16_f32 %0, %1, %2" : "=v"(r) : "v"(lo), "v"(hi)); return r; }
; __device__ __forceinline__ f32x2 gelu_pk(f32x2 v) {
;     const f32x2 av = __builtin_elementwise_abs(v), d = av * 0.2316418882f + 1.0f;
;     f32x2 t; t.x = __builtin_amdgcn_rcpf(d.x); t.y = __builtin_amdgcn_rcpf(d.y);
;     f32x2 q = t * 0.5307027145f + (-0.7265760135f); q = q * t + 0.7107068705f; q = q * t + (-0.142248368f); q = q * t + 0.127414796f; q = q * t;
;     const f32x2 s = (v * v) * (-0.72134752044f);
;     f32x2 e; e.x = __builtin_amdgcn_exp2f(s.x); e.y = __builtin_amdgcn_exp2f(s.y);
;     const f32x2 m = v * (q * e), r = v - m;
;     f32x2 o; o.x = v.x < 0.f ? m.x : r.x; o.y = v.y < 0.f ? m.y : r.y; return o;
;     __device__ __forceinline__ void operator()(const f32x4 (&acc)[2][2][4][2], const Unit& u, int wr, int wc, int fr, int fq) const {
;     ...
;             for (int m = 0; m < 4; ++m) { bf16_t* rowp = O + (size_t)(u.pm >> 5) * bgap + (size_t)u.pm * sm + (size_t)u.pn * sn + (size_t)(wr * 64 + fr + ai * HALF + m * 16) * ldc + wc * 32 + 8 * fq; const float sc = rs[ai][m]; float s1 = 0.f, s2 = 0.f;
; #pragma unroll
;                 for (int bj = 0; bj < 2; ++bj) { f32x4 v0 = acc[ai][bj][m][0] * sc, v1 = acc[ai][bj][m][1] * sc;
;                     if (do_gelu) { f32x2 a = gelu_pk((f32x2){v0[0], v0[1]}), b = gelu_pk((f32x2){v0[2], v0[3]}), c = gelu_pk((f32x2){v1[0], v1[1]}), d = gelu_pk((f32x2){v1[2], v1[3]});
;                         v0 = (f32x4){a.x, a.y, b.x, b.y}; v1 = (f32x4){c.x, c.y, d.x, d.y}; }
;                     if (do_stat) { s1 += ((v0[0] + v0[1]) + (v0[2] + v0[3])) + ((v1[0] + v1[1]) + (v1[2] + v1[3]));
;                         s2 += ((v0[0] * v0[0] + v0[1] * v0[1]) + (v0[2] * v0[2] + v0[3] * v0[3])) + ((v1[0] * v1[0] + v1[1] * v1[1]) + (v1[2] * v1[2] + v1[3] * v1[3])); }
;                     u32x4 w; w.x = cvt_pk_bf16(v0[0], v0[1]); w.y = cvt_pk_bf16(v0[2], v0[3]); w.z = cvt_pk_bf16(v1[0], v1[1]); w.w = cvt_pk_bf16(v1[2], v1[3]);
;                     *(u32x4*)(rowp + bj * HALF) = w; }
.LBB0_362:
	v_lshl_add_u64 v[42:43], s[16:17], 0, v[146:147]
	v_lshl_add_u64 v[42:43], v[42:43], 0, s[86:87]
	v_lshl_add_u64 v[42:43], v[42:43], 0, v[192:193]
	v_cvt_pk_bf16_f32 v44, v44, v45
	v_cvt_pk_bf16_f32 v45, v46, v47
	v_mov_b32_e32 v161, v160
	v_cvt_pk_bf16_f32 v46, v50, v51
	v_cvt_pk_bf16_f32 v47, v48, v49
	global_store_dwordx4 v[42:43], v[44:47], off
	v_pk_mul_f32 v[36:37], v[36:37], v[160:161]
	s_and_b64 vcc, exec, s[42:43]
	v_mov_b32_e32 v44, v160
	v_mov_b32_e32 v45, v160
	v_pk_mul_f32 v[38:39], v[38:39], v[44:45]
	v_pk_mul_f32 v[34:35], v[34:35], v[44:45]
	v_pk_mul_f32 v[32:33], v[32:33], v[160:161]
	s_cbranch_vccnz .LBB0_364
	v_and_b32_e32 v45, 0x7fffffff, v37
	v_and_b32_e32 v44, 0x7fffffff, v36
	v_pk_fma_f32 v[44:45], v[44:45], s[28:29], 1.0 op_sel_hi:[1,0,0]
	s_mov_b32 s0, 0xbf3a00e3
	v_rcp_f32_e32 v46, v44
	v_rcp_f32_e32 v47, v45
	v_mov_b64_e32 v[44:45], s[0:1]
	v_pk_mul_f32 v[50:51], v[36:37], v[36:37]
	s_mov_b32 s0, 0xbf38aa3b
	v_pk_fma_f32 v[48:49], v[46:47], s[30:31], v[44:45] op_sel_hi:[1,0,0]
	v_pk_mul_f32 v[50:51], v[50:51], s[0:1] op_sel_hi:[1,0]
	v_pk_fma_f32 v[48:49], v[46:47], v[48:49], s[36:37] op_sel_hi:[1,1,0]
	v_exp_f32_e32 v50, v50
	v_exp_f32_e32 v51, v51
	v_pk_fma_f32 v[48:49], v[46:47], v[48:49], s[80:81] op_sel_hi:[1,1,0]
	v_cmp_gt_f32_e32 vcc, 0, v36
	v_pk_fma_f32 v[48:49], v[46:47], v[48:49], s[64:65] op_sel_hi:[1,1,0]
	v_pk_mul_f32 v[46:47], v[46:47], v[48:49]
	v_pk_mul_f32 v[48:49], v[38:39], v[38:39]
	v_pk_mul_f32 v[46:47], v[50:51], v[46:47]
	v_pk_mul_f32 v[48:49], v[48:49], s[0:1] op_sel_hi:[1,0]
	v_pk_mul_f32 v[50:51], v[36:37], v[46:47]
	v_pk_fma_f32 v[46:47], v[36:37], v[46:47], v[36:37] neg_lo:[1,0,0] neg_hi:[1,0,0]
	v_exp_f32_e32 v48, v48
	v_cndmask_b32_e32 v36, v46, v50, vcc
	v_cmp_gt_f32_e32 vcc, 0, v37
	v_and_b32_e32 v46, 0x7fffffff, v38
	v_exp_f32_e32 v49, v49
	v_cndmask_b32_e32 v37, v47, v51, vcc
	v_and_b32_e32 v47, 0x7fffffff, v39
	v_pk_fma_f32 v[46:47], v[46:47], s[28:29], 1.0 op_sel_hi:[1,0,0]
	v_cmp_gt_f32_e32 vcc, 0, v38
	v_rcp_f32_e32 v46, v46
	v_rcp_f32_e32 v47, v47
	s_nop 0
	v_pk_fma_f32 v[50:51], v[46:47], s[30:31], v[44:45] op_sel_hi:[1,0,0]
	v_pk_fma_f32 v[50:51], v[46:47], v[50:51], s[36:37] op_sel_hi:[1,1,0]
	v_pk_fma_f32 v[50:51], v[46:47], v[50:51], s[80:81] op_sel_hi:[1,1,0]
	v_pk_fma_f32 v[50:51], v[46:47], v[50:51], s[64:65] op_sel_hi:[1,1,0]
	v_pk_mul_f32 v[46:47], v[46:47], v[50:51]
	v_pk_mul_f32 v[50:51], v[32:33], v[32:33]
	v_pk_mul_f32 v[46:47], v[48:49], v[46:47]
	v_pk_mul_f32 v[50:51], v[50:51], s[0:1] op_sel_hi:[1,0]
	v_pk_mul_f32 v[48:49], v[38:39], v[46:47]
	v_pk_fma_f32 v[46:47], v[38:39], v[46:47], v[38:39] neg_lo:[1,0,0] neg_hi:[1,0,0]
	v_exp_f32_e32 v50, v50
	v_cndmask_b32_e32 v38, v46, v48, vcc
	v_cmp_gt_f32_e32 vcc, 0, v39
	v_and_b32_e32 v46, 0x7fffffff, v32
	v_exp_f32_e32 v51, v51
	v_cndmask_b32_e32 v39, v47, v49, vcc
	v_and_b32_e32 v47, 0x7fffffff, v33
	v_pk_fma_f32 v[46:47], v[46:47], s[28:29], 1.0 op_sel_hi:[1,0,0]
	v_cmp_gt_f32_e32 vcc, 0, v32
	v_rcp_f32_e32 v46, v46
	v_rcp_f32_e32 v47, v47
	s_nop 0
	v_pk_fma_f32 v[48:49], v[46:47], s[30:31], v[44:45] op_sel_hi:[1,0,0]
	v_pk_fma_f32 v[48:49], v[46:47], v[48:49], s[36:37] op_sel_hi:[1,1,0]
	v_pk_fma_f32 v[48:49], v[46:47], v[48:49], s[80:81] op_sel_hi:[1,1,0]
	v_pk_fma_f32 v[48:49], v[46:47], v[48:49], s[64:65] op_sel_hi:[1,1,0]
	v_pk_mul_f32 v[46:47], v[46:47], v[48:49]
	v_pk_mul_f32 v[48:49], v[34:35], v[34:35]
	v_pk_mul_f32 v[46:47], v[50:51], v[46:47]
	v_pk_mul_f32 v[50:51], v[32:33], v[46:47]
	v_pk_fma_f32 v[46:47], v[32:33], v[46:47], v[32:33] neg_lo:[1,0,0] neg_hi:[1,0,0]
	v_cndmask_b32_e32 v32, v46, v50, vcc
	v_cmp_gt_f32_e32 vcc, 0, v33
	v_and_b32_e32 v46, 0x7fffffff, v34
	s_nop 0
	v_cndmask_b32_e32 v33, v47, v51, vcc
	v_and_b32_e32 v47, 0x7fffffff, v35
	v_pk_fma_f32 v[46:47], v[46:47], s[28:29], 1.0 op_sel_hi:[1,0,0]
	v_cmp_gt_f32_e32 vcc, 0, v34
	v_rcp_f32_e32 v46, v46
	v_rcp_f32_e32 v47, v47
	s_nop 0
	v_pk_fma_f32 v[44:45], v[46:47], s[30:31], v[44:45] op_sel_hi:[1,0,0]
	v_pk_fma_f32 v[44:45], v[46:47], v[44:45], s[36:37] op_sel_hi:[1,1,0]
	v_pk_fma_f32 v[44:45], v[46:47], v[44:45], s[80:81] op_sel_hi:[1,1,0]
	v_pk_fma_f32 v[44:45], v[46:47], v[44:45], s[64:65] op_sel_hi:[1,1,0]
	v_pk_mul_f32 v[44:45], v[46:47], v[44:45]
	v_pk_mul_f32 v[46:47], v[48:49], s[0:1] op_sel_hi:[1,0]
	v_exp_f32_e32 v46, v46
	v_exp_f32_e32 v47, v47
	s_nop 0
	v_pk_mul_f32 v[44:45], v[46:47], v[44:45]
	v_pk_mul_f32 v[46:47], v[34:35], v[44:45]
	v_pk_fma_f32 v[44:45], v[34:35], v[44:45], v[34:35] neg_lo:[1,0,0] neg_hi:[1,0,0]
	s_nop 0
	v_cndmask_b32_e32 v34, v44, v46, vcc
	v_cmp_gt_f32_e32 vcc, 0, v35
	s_nop 1
	v_cndmask_b32_e32 v35, v45, v47, vcc
.LBB0_364:
	s_and_b64 vcc, exec, s[92:93]
	s_cbranch_vccz .LBB0_366
	v_mul_f32_e32 v45, v36, v36
	v_mul_f32_e32 v47, v37, v37
	v_mul_f32_e32 v49, v38, v38
	v_mul_f32_e32 v51, v39, v39
	v_mov_b32_e32 v44, v36
	v_mov_b32_e32 v46, v37
	v_mov_b32_e32 v48, v38
	v_mov_b32_e32 v50, v39
	v_mul_f32_e32 v53, v32, v32
	v_mul_f32_e32 v55, v33, v33
	v_mul_f32_e32 v57, v34, v34
	v_mul_f32_e32 v59, v35, v35
	v_pk_add_f32 v[44:45], v[44:45], v[46:47]
	v_pk_add_f32 v[46:47], v[48:49], v[50:51]
	v_mov_b32_e32 v52, v32
	v_mov_b32_e32 v54, v33
	v_mov_b32_e32 v56, v34
	v_mov_b32_e32 v58, v35
	v_pk_add_f32 v[44:45], v[44:45], v[46:47]
	v_pk_add_f32 v[46:47], v[52:53], v[54:55]
	v_pk_add_f32 v[48:49], v[56:57], v[58:59]
	v_pk_add_f32 v[46:47], v[46:47], v[48:49]
	s_nop 0
	v_pk_add_f32 v[44:45], v[46:47], v[44:45]
	s_nop 0
	v_pk_add_f32 v[44:45], v[40:41], v[44:45]
	s_cbranch_execz .LBB0_367
	s_branch .LBB0_368

; __device__ __forceinline__ f32x2 gelu_pk(f32x2 v) {
;     const f32x2 av = __builtin_elementwise_abs(v), d = av * 0.2316418882f + 1.0f;
;     f32x2 t; t.x = __builtin_amdgcn_rcpf(d.x); t.y = __builtin_amdgcn_rcpf(d.y);
;     f32x2 q = t * 0.5307027145f + (-0.7265760135f); q = q * t + 0.7107068705f; q = q * t + (-0.142248368f); q = q * t + 0.127414796f; q = q * t;
;     const f32x2 s = (v * v) * (-0.72134752044f);
;     f32x2 e; e.x = __builtin_amdgcn_exp2f(s.x); e.y = __builtin_amdgcn_exp2f(s.y);
;     const f32x2 m = v * (q * e), r = v - m;
;     f32x2 o; o.x = v.x < 0.f ? m.x : r.x; o.y = v.y < 0.f ? m.y : r.y; return o;
;     __device__ __forceinline__ void operator()(const f32x4 (&acc)[2][2][4][2], const Unit& u, int wr, int wc, int fr, int fq) const {
;     ...
;                 for (int bj = 0; bj < 2; ++bj) { f32x4 v0 = acc[ai][bj][m][0] * sc, v1 = acc[ai][bj][m][1] * sc;
;                     if (do_gelu) { f32x2 a = gelu_pk((f32x2){v0[0], v0[1]}), b = gelu_pk((f32x2){v0[2], v0[3]}), c = gelu_pk((f32x2){v1[0], v1[1]}), d = gelu_pk((f32x2){v1[2], v1[3]});
;                         v0 = (f32x4){a.x, a.y, b.x, b.y}; v1 = (f32x4){c.x, c.y, d.x, d.y}; }
.LBB0_372:
	v_pk_mul_f32 v[30:31], v[30:31], v[158:159] op_sel_hi:[1,0]
	v_pk_mul_f32 v[28:29], v[28:29], v[158:159] op_sel_hi:[1,0]
	v_pk_mul_f32 v[32:33], v[26:27], v[158:159] op_sel_hi:[1,0]
	s_and_b64 vcc, exec, s[42:43]
	s_waitcnt lgkmcnt(0)
	v_pk_mul_f32 v[34:35], v[24:25], v[158:159] op_sel_hi:[1,0]
	s_cbranch_vccnz .LBB0_374
	v_and_b32_e32 v25, 0x7fffffff, v29
	v_and_b32_e32 v24, 0x7fffffff, v28
	v_pk_fma_f32 v[24:25], v[24:25], s[28:29], 1.0 op_sel_hi:[1,0,0]
	s_mov_b32 s0, 0xbf3a00e3
	v_rcp_f32_e32 v26, v24
	v_rcp_f32_e32 v27, v25
	v_mov_b64_e32 v[24:25], s[0:1]
	v_pk_mul_f32 v[38:39], v[28:29], v[28:29]
	s_mov_b32 s0, 0xbf38aa3b
	v_pk_fma_f32 v[36:37], v[26:27], s[30:31], v[24:25] op_sel_hi:[1,0,0]
	v_pk_mul_f32 v[38:39], v[38:39], s[0:1] op_sel_hi:[1,0]
	v_pk_fma_f32 v[36:37], v[26:27], v[36:37], s[36:37] op_sel_hi:[1,1,0]
	v_exp_f32_e32 v38, v38
	v_exp_f32_e32 v39, v39
	v_pk_fma_f32 v[36:37], v[26:27], v[36:37], s[80:81] op_sel_hi:[1,1,0]
	v_cmp_gt_f32_e32 vcc, 0, v28
	v_pk_fma_f32 v[36:37], v[26:27], v[36:37], s[64:65] op_sel_hi:[1,1,0]
	v_pk_mul_f32 v[26:27], v[26:27], v[36:37]
	v_pk_mul_f32 v[36:37], v[30:31], v[30:31]
	v_pk_mul_f32 v[26:27], v[38:39], v[26:27]
	v_pk_mul_f32 v[36:37], v[36:37], s[0:1] op_sel_hi:[1,0]
	v_pk_mul_f32 v[38:39], v[28:29], v[26:27]
	v_pk_fma_f32 v[26:27], v[28:29], v[26:27], v[28:29] neg_lo:[1,0,0] neg_hi:[1,0,0]
	v_exp_f32_e32 v36, v36
	v_cndmask_b32_e32 v28, v26, v38, vcc
	v_cmp_gt_f32_e32 vcc, 0, v29
	v_and_b32_e32 v26, 0x7fffffff, v30
	v_exp_f32_e32 v37, v37
	v_cndmask_b32_e32 v29, v27, v39, vcc
	v_and_b32_e32 v27, 0x7fffffff, v31
	v_pk_fma_f32 v[26:27], v[26:27], s[28:29], 1.0 op_sel_hi:[1,0,0]
	v_cmp_gt_f32_e32 vcc, 0, v30
	v_rcp_f32_e32 v26, v26
	v_rcp_f32_e32 v27, v27
	s_nop 0
	v_pk_fma_f32 v[38:39], v[26:27], s[30:31], v[24:25] op_sel_hi:[1,0,0]
	v_pk_fma_f32 v[38:39], v[26:27], v[38:39], s[36:37] op_sel_hi:[1,1,0]
	v_pk_fma_f32 v[38:39], v[26:27], v[38:39], s[80:81] op_sel_hi:[1,1,0]
	v_pk_fma_f32 v[38:39], v[26:27], v[38:39], s[64:65] op_sel_hi:[1,1,0]
	v_pk_mul_f32 v[26:27], v[26:27], v[38:39]
	v_pk_mul_f32 v[38:39], v[34:35], v[34:35]
	v_pk_mul_f32 v[26:27], v[36:37], v[26:27]
	v_pk_mul_f32 v[38:39], v[38:39], s[0:1] op_sel_hi:[1,0]
	v_pk_mul_f32 v[36:37], v[30:31], v[26:27]
	v_pk_fma_f32 v[26:27], v[30:31], v[26:27], v[30:31] neg_lo:[1,0,0] neg_hi:[1,0,0]
	v_exp_f32_e32 v38, v38
	v_cndmask_b32_e32 v30, v26, v36, vcc
	v_cmp_gt_f32_e32 vcc, 0, v31
	v_and_b32_e32 v26, 0x7fffffff, v34
	v_exp_f32_e32 v39, v39
	v_cndmask_b32_e32 v31, v27, v37, vcc
	v_and_b32_e32 v27, 0x7fffffff, v35
	v_pk_fma_f32 v[26:27], v[26:27], s[28:29], 1.0 op_sel_hi:[1,0,0]
	v_cmp_gt_f32_e32 vcc, 0, v34
	v_rcp_f32_e32 v26, v26
	v_rcp_f32_e32 v27, v27
	s_nop 0
	v_pk_fma_f32 v[36:37], v[26:27], s[30:31], v[24:25] op_sel_hi:[1,0,0]
	v_pk_fma_f32 v[36:37], v[26:27], v[36:37], s[36:37] op_sel_hi:[1,1,0]
	v_pk_fma_f32 v[36:37], v[26:27], v[36:37], s[80:81] op_sel_hi:[1,1,0]
	v_pk_fma_f32 v[36:37], v[26:27], v[36:37], s[64:65] op_sel_hi:[1,1,0]
	v_pk_mul_f32 v[26:27], v[26:27], v[36:37]
	v_pk_mul_f32 v[36:37], v[32:33], v[32:33]
	v_pk_mul_f32 v[26:27], v[38:39], v[26:27]
	v_pk_mul_f32 v[38:39], v[34:35], v[26:27]
	v_pk_fma_f32 v[26:27], v[34:35], v[26:27], v[34:35] neg_lo:[1,0,0] neg_hi:[1,0,0]
	v_cndmask_b32_e32 v34, v26, v38, vcc
	v_cmp_gt_f32_e32 vcc, 0, v35
	v_and_b32_e32 v26, 0x7fffffff, v32
	s_nop 0
	v_cndmask_b32_e32 v35, v27, v39, vcc
	v_and_b32_e32 v27, 0x7fffffff, v33
	v_pk_fma_f32 v[26:27], v[26:27], s[28:29], 1.0 op_sel_hi:[1,0,0]
	v_cmp_gt_f32_e32 vcc, 0, v32
	v_rcp_f32_e32 v26, v26
	v_rcp_f32_e32 v27, v27
	s_nop 0
	v_pk_fma_f32 v[24:25], v[26:27], s[30:31], v[24:25] op_sel_hi:[1,0,0]
	v_pk_fma_f32 v[24:25], v[26:27], v[24:25], s[36:37] op_sel_hi:[1,1,0]
	v_pk_fma_f32 v[24:25], v[26:27], v[24:25], s[80:81] op_sel_hi:[1,1,0]
	v_pk_fma_f32 v[24:25], v[26:27], v[24:25], s[64:65] op_sel_hi:[1,1,0]
	v_pk_mul_f32 v[24:25], v[26:27], v[24:25]
	v_pk_mul_f32 v[26:27], v[36:37], s[0:1] op_sel_hi:[1,0]
	v_exp_f32_e32 v26, v26
	v_exp_f32_e32 v27, v27
	s_nop 0
	v_pk_mul_f32 v[24:25], v[26:27], v[24:25]
	v_pk_mul_f32 v[26:27], v[32:33], v[24:25]
	v_pk_fma_f32 v[24:25], v[32:33], v[24:25], v[32:33] neg_lo:[1,0,0] neg_hi:[1,0,0]
	s_nop 0
	v_cndmask_b32_e32 v32, v24, v26, vcc
	v_cmp_gt_f32_e32 vcc, 0, v33
	s_nop 1
	v_cndmask_b32_e32 v33, v25, v27, vcc

; __device__ __forceinline__ unsigned cvt_pk_bf16(float lo, float hi) { unsigned r; asm volatile("v_cvt_pk_bf16_f32 %0, %1, %2" : "=v"(r) : "v"(lo), "v"(hi)); return r; }
; __device__ __forceinline__ f32x2 gelu_pk(f32x2 v) {
;     const f32x2 av = __builtin_elementwise_abs(v), d = av * 0.2316418882f + 1.0f;
;     f32x2 t; t.x = __builtin_amdgcn_rcpf(d.x); t.y = __builtin_amdgcn_rcpf(d.y);
;     f32x2 q = t * 0.5307027145f + (-0.7265760135f); q = q * t + 0.7107068705f; q = q * t + (-0.142248368f); q = q * t + 0.127414796f; q = q * t;
;     const f32x2 s = (v * v) * (-0.72134752044f);
;     f32x2 e; e.x = __builtin_amdgcn_exp2f(s.x); e.y = __builtin_amdgcn_exp2f(s.y);
;     const f32x2 m = v * (q * e), r = v - m;
;     f32x2 o; o.x = v.x < 0.f ? m.x : r.x; o.y = v.y < 0.f ? m.y : r.y; return o;
;     __device__ __forceinline__ void operator()(const f32x4 (&acc)[2][2][4][2], const Unit& u, int wr, int wc, int fr, int fq) const {
;     ...
;             for (int m = 0; m < 4; ++m) { bf16_t* rowp = O + (size_t)(u.pm >> 5) * bgap + (size_t)u.pm * sm + (size_t)u.pn * sn + (size_t)(wr * 64 + fr + ai * HALF + m * 16) * ldc + wc * 32 + 8 * fq; const float sc = rs[ai][m]; float s1 = 0.f, s2 = 0.f;
; #pragma unroll
;                 for (int bj = 0; bj < 2; ++bj) { f32x4 v0 = acc[ai][bj][m][0] * sc, v1 = acc[ai][bj][m][1] * sc;
;                     if (do_gelu) { f32x2 a = gelu_pk((f32x2){v0[0], v0[1]}), b = gelu_pk((f32x2){v0[2], v0[3]}), c = gelu_pk((f32x2){v1[0], v1[1]}), d = gelu_pk((f32x2){v1[2], v1[3]});
;                         v0 = (f32x4){a.x, a.y, b.x, b.y}; v1 = (f32x4){c.x, c.y, d.x, d.y}; }
;                     if (do_stat) { s1 += ((v0[0] + v0[1]) + (v0[2] + v0[3])) + ((v1[0] + v1[1]) + (v1[2] + v1[3]));
;                         s2 += ((v0[0] * v0[0] + v0[1] * v0[1]) + (v0[2] * v0[2] + v0[3] * v0[3])) + ((v1[0] * v1[0] + v1[1] * v1[1]) + (v1[2] * v1[2] + v1[3] * v1[3])); }
;                     u32x4 w; w.x = cvt_pk_bf16(v0[0], v0[1]); w.y = cvt_pk_bf16(v0[2], v0[3]); w.z = cvt_pk_bf16(v1[0], v1[1]); w.w = cvt_pk_bf16(v1[2], v1[3]);
;                     *(u32x4*)(rowp + bj * HALF) = w; }
.LBB0_378:
	v_lshl_add_u64 v[26:27], s[16:17], 0, v[148:149]
	v_lshl_add_u64 v[26:27], v[26:27], 0, s[86:87]
	v_lshl_add_u64 v[26:27], v[26:27], 0, v[192:193]
	v_cvt_pk_bf16_f32 v28, v28, v29
	v_cvt_pk_bf16_f32 v29, v30, v31
	v_mov_b32_e32 v159, v158
	v_cvt_pk_bf16_f32 v30, v34, v35
	v_cvt_pk_bf16_f32 v31, v32, v33
	global_store_dwordx4 v[26:27], v[28:31], off
	v_pk_mul_f32 v[20:21], v[20:21], v[158:159]
	s_and_b64 vcc, exec, s[42:43]
	v_mov_b32_e32 v28, v158
	v_mov_b32_e32 v29, v158
	v_pk_mul_f32 v[22:23], v[22:23], v[28:29]
	v_pk_mul_f32 v[18:19], v[18:19], v[28:29]
	v_pk_mul_f32 v[16:17], v[16:17], v[158:159]
	s_cbranch_vccnz .LBB0_380
	v_and_b32_e32 v29, 0x7fffffff, v21
	v_and_b32_e32 v28, 0x7fffffff, v20
	v_pk_fma_f32 v[28:29], v[28:29], s[28:29], 1.0 op_sel_hi:[1,0,0]
	s_mov_b32 s0, 0xbf3a00e3
	v_rcp_f32_e32 v30, v28
	v_rcp_f32_e32 v31, v29
	v_mov_b64_e32 v[28:29], s[0:1]
	v_pk_mul_f32 v[34:35], v[20:21], v[20:21]
	s_mov_b32 s0, 0xbf38aa3b
	v_pk_fma_f32 v[32:33], v[30:31], s[30:31], v[28:29] op_sel_hi:[1,0,0]
	v_pk_mul_f32 v[34:35], v[34:35], s[0:1] op_sel_hi:[1,0]
	v_pk_fma_f32 v[32:33], v[30:31], v[32:33], s[36:37] op_sel_hi:[1,1,0]
	v_exp_f32_e32 v34, v34
	v_exp_f32_e32 v35, v35
	v_pk_fma_f32 v[32:33], v[30:31], v[32:33], s[80:81] op_sel_hi:[1,1,0]
	v_cmp_gt_f32_e32 vcc, 0, v20
	v_pk_fma_f32 v[32:33], v[30:31], v[32:33], s[64:65] op_sel_hi:[1,1,0]
	v_pk_mul_f32 v[30:31], v[30:31], v[32:33]
	v_pk_mul_f32 v[32:33], v[22:23], v[22:23]
	v_pk_mul_f32 v[30:31], v[34:35], v[30:31]
	v_pk_mul_f32 v[32:33], v[32:33], s[0:1] op_sel_hi:[1,0]
	v_pk_mul_f32 v[34:35], v[20:21], v[30:31]
	v_pk_fma_f32 v[30:31], v[20:21], v[30:31], v[20:21] neg_lo:[1,0,0] neg_hi:[1,0,0]
	v_exp_f32_e32 v32, v32
	v_cndmask_b32_e32 v20, v30, v34, vcc
	v_cmp_gt_f32_e32 vcc, 0, v21
	v_and_b32_e32 v30, 0x7fffffff, v22
	v_exp_f32_e32 v33, v33
	v_cndmask_b32_e32 v21, v31, v35, vcc
	v_and_b32_e32 v31, 0x7fffffff, v23
	v_pk_fma_f32 v[30:31], v[30:31], s[28:29], 1.0 op_sel_hi:[1,0,0]
	v_cmp_gt_f32_e32 vcc, 0, v22
	v_rcp_f32_e32 v30, v30
	v_rcp_f32_e32 v31, v31
	s_nop 0
	v_pk_fma_f32 v[34:35], v[30:31], s[30:31], v[28:29] op_sel_hi:[1,0,0]
	v_pk_fma_f32 v[34:35], v[30:31], v[34:35], s[36:37] op_sel_hi:[1,1,0]
	v_pk_fma_f32 v[34:35], v[30:31], v[34:35], s[80:81] op_sel_hi:[1,1,0]
	v_pk_fma_f32 v[34:35], v[30:31], v[34:35], s[64:65] op_sel_hi:[1,1,0]
	v_pk_mul_f32 v[30:31], v[30:31], v[34:35]
	v_pk_mul_f32 v[34:35], v[16:17], v[16:17]
	v_pk_mul_f32 v[30:31], v[32:33], v[30:31]
	v_pk_mul_f32 v[34:35], v[34:35], s[0:1] op_sel_hi:[1,0]
	v_pk_mul_f32 v[32:33], v[22:23], v[30:31]
	v_pk_fma_f32 v[30:31], v[22:23], v[30:31], v[22:23] neg_lo:[1,0,0] neg_hi:[1,0,0]
	v_exp_f32_e32 v34, v34
	v_cndmask_b32_e32 v22, v30, v32, vcc
	v_cmp_gt_f32_e32 vcc, 0, v23
	v_and_b32_e32 v30, 0x7fffffff, v16
	v_exp_f32_e32 v35, v35
	v_cndmask_b32_e32 v23, v31, v33, vcc
	v_and_b32_e32 v31, 0x7fffffff, v17
	v_pk_fma_f32 v[30:31], v[30:31], s[28:29], 1.0 op_sel_hi:[1,0,0]
	v_cmp_gt_f32_e32 vcc, 0, v16
	v_rcp_f32_e32 v30, v30
	v_rcp_f32_e32 v31, v31
	s_nop 0
	v_pk_fma_f32 v[32:33], v[30:31], s[30:31], v[28:29] op_sel_hi:[1,0,0]
	v_pk_fma_f32 v[32:33], v[30:31], v[32:33], s[36:37] op_sel_hi:[1,1,0]
	v_pk_fma_f32 v[32:33], v[30:31], v[32:33], s[80:81] op_sel_hi:[1,1,0]
	v_pk_fma_f32 v[32:33], v[30:31], v[32:33], s[64:65] op_sel_hi:[1,1,0]
	v_pk_mul_f32 v[30:31], v[30:31], v[32:33]
	v_pk_mul_f32 v[32:33], v[18:19], v[18:19]
	v_pk_mul_f32 v[30:31], v[34:35], v[30:31]
	v_pk_mul_f32 v[34:35], v[16:17], v[30:31]
	v_pk_fma_f32 v[30:31], v[16:17], v[30:31], v[16:17] neg_lo:[1,0,0] neg_hi:[1,0,0]
	v_cndmask_b32_e32 v16, v30, v34, vcc
	v_cmp_gt_f32_e32 vcc, 0, v17
	v_and_b32_e32 v30, 0x7fffffff, v18
	s_nop 0
	v_cndmask_b32_e32 v17, v31, v35, vcc
	v_and_b32_e32 v31, 0x7fffffff, v19
	v_pk_fma_f32 v[30:31], v[30:31], s[28:29], 1.0 op_sel_hi:[1,0,0]
	v_cmp_gt_f32_e32 vcc, 0, v18
	v_rcp_f32_e32 v30, v30
	v_rcp_f32_e32 v31, v31
	s_nop 0
	v_pk_fma_f32 v[28:29], v[30:31], s[30:31], v[28:29] op_sel_hi:[1,0,0]
	v_pk_fma_f32 v[28:29], v[30:31], v[28:29], s[36:37] op_sel_hi:[1,1,0]
	v_pk_fma_f32 v[28:29], v[30:31], v[28:29], s[80:81] op_sel_hi:[1,1,0]
	v_pk_fma_f32 v[28:29], v[30:31], v[28:29], s[64:65] op_sel_hi:[1,1,0]
	v_pk_mul_f32 v[28:29], v[30:31], v[28:29]
	v_pk_mul_f32 v[30:31], v[32:33], s[0:1] op_sel_hi:[1,0]
	v_exp_f32_e32 v30, v30
	v_exp_f32_e32 v31, v31
	s_nop 0
	v_pk_mul_f32 v[28:29], v[30:31], v[28:29]
	v_pk_mul_f32 v[30:31], v[18:19], v[28:29]
	v_pk_fma_f32 v[28:29], v[18:19], v[28:29], v[18:19] neg_lo:[1,0,0] neg_hi:[1,0,0]
	s_nop 0
	v_cndmask_b32_e32 v18, v28, v30, vcc
	v_cmp_gt_f32_e32 vcc, 0, v19
	s_nop 1
	v_cndmask_b32_e32 v19, v29, v31, vcc
.LBB0_380:
	s_and_b64 vcc, exec, s[92:93]
	s_cbranch_vccz .LBB0_382
	v_mul_f32_e32 v29, v20, v20
	v_mul_f32_e32 v31, v21, v21
	v_mul_f32_e32 v33, v22, v22
	v_mul_f32_e32 v35, v23, v23
	v_mov_b32_e32 v28, v20
	v_mov_b32_e32 v30, v21
	v_mov_b32_e32 v32, v22
	v_mov_b32_e32 v34, v23
	v_mul_f32_e32 v37, v16, v16
	v_mul_f32_e32 v39, v17, v17
	v_mul_f32_e32 v41, v18, v18
	v_mul_f32_e32 v43, v19, v19
	v_pk_add_f32 v[28:29], v[28:29], v[30:31]
	v_pk_add_f32 v[30:31], v[32:33], v[34:35]
	v_mov_b32_e32 v36, v16
	v_mov_b32_e32 v38, v17
	v_mov_b32_e32 v40, v18
	v_mov_b32_e32 v42, v19
	v_pk_add_f32 v[28:29], v[28:29], v[30:31]
	v_pk_add_f32 v[30:31], v[36:37], v[38:39]
	v_pk_add_f32 v[32:33], v[40:41], v[42:43]
	v_pk_add_f32 v[30:31], v[30:31], v[32:33]
	s_nop 0
	v_pk_add_f32 v[28:29], v[30:31], v[28:29]
	s_nop 0
	v_pk_add_f32 v[28:29], v[24:25], v[28:29]
	s_cbranch_execz .LBB0_383
	s_branch .LBB0_384

; __device__ __forceinline__ f32x2 gelu_pk(f32x2 v) {
;     const f32x2 av = __builtin_elementwise_abs(v), d = av * 0.2316418882f + 1.0f;
;     f32x2 t; t.x = __builtin_amdgcn_rcpf(d.x); t.y = __builtin_amdgcn_rcpf(d.y);
;     f32x2 q = t * 0.5307027145f + (-0.7265760135f); q = q * t + 0.7107068705f; q = q * t + (-0.142248368f); q = q * t + 0.127414796f; q = q * t;
;     const f32x2 s = (v * v) * (-0.72134752044f);
;     f32x2 e; e.x = __builtin_amdgcn_exp2f(s.x); e.y = __builtin_amdgcn_exp2f(s.y);
;     const f32x2 m = v * (q * e), r = v - m;
;     f32x2 o; o.x = v.x < 0.f ? m.x : r.x; o.y = v.y < 0.f ? m.y : r.y; return o;
;     __device__ __forceinline__ void operator()(const f32x4 (&acc)[2][2][4][2], const Unit& u, int wr, int wc, int fr, int fq) const {
;     ...
;                 for (int bj = 0; bj < 2; ++bj) { f32x4 v0 = acc[ai][bj][m][0] * sc, v1 = acc[ai][bj][m][1] * sc;
;                     if (do_gelu) { f32x2 a = gelu_pk((f32x2){v0[0], v0[1]}), b = gelu_pk((f32x2){v0[2], v0[3]}), c = gelu_pk((f32x2){v1[0], v1[1]}), d = gelu_pk((f32x2){v1[2], v1[3]});
;                         v0 = (f32x4){a.x, a.y, b.x, b.y}; v1 = (f32x4){c.x, c.y, d.x, d.y}; }
.LBB0_388:
	v_pk_mul_f32 v[14:15], v[14:15], v[156:157] op_sel_hi:[1,0]
	v_pk_mul_f32 v[12:13], v[12:13], v[156:157] op_sel_hi:[1,0]
	v_pk_mul_f32 v[16:17], v[10:11], v[156:157] op_sel_hi:[1,0]
	s_and_b64 vcc, exec, s[42:43]
	s_waitcnt lgkmcnt(0)
	v_pk_mul_f32 v[18:19], v[8:9], v[156:157] op_sel_hi:[1,0]
	s_cbranch_vccnz .LBB0_390
	v_and_b32_e32 v9, 0x7fffffff, v13
	v_and_b32_e32 v8, 0x7fffffff, v12
	v_pk_fma_f32 v[8:9], v[8:9], s[28:29], 1.0 op_sel_hi:[1,0,0]
	s_mov_b32 s0, 0xbf3a00e3
	v_rcp_f32_e32 v10, v8
	v_rcp_f32_e32 v11, v9
	v_mov_b64_e32 v[8:9], s[0:1]
	v_pk_mul_f32 v[22:23], v[12:13], v[12:13]
	s_mov_b32 s0, 0xbf38aa3b
	v_pk_fma_f32 v[20:21], v[10:11], s[30:31], v[8:9] op_sel_hi:[1,0,0]
	v_pk_mul_f32 v[22:23], v[22:23], s[0:1] op_sel_hi:[1,0]
	v_pk_fma_f32 v[20:21], v[10:11], v[20:21], s[36:37] op_sel_hi:[1,1,0]
	v_exp_f32_e32 v22, v22
	v_exp_f32_e32 v23, v23
	v_pk_fma_f32 v[20:21], v[10:11], v[20:21], s[80:81] op_sel_hi:[1,1,0]
	v_cmp_gt_f32_e32 vcc, 0, v12
	v_pk_fma_f32 v[20:21], v[10:11], v[20:21], s[64:65] op_sel_hi:[1,1,0]
	v_pk_mul_f32 v[10:11], v[10:11], v[20:21]
	v_pk_mul_f32 v[20:21], v[14:15], v[14:15]
	v_pk_mul_f32 v[10:11], v[22:23], v[10:11]
	v_pk_mul_f32 v[20:21], v[20:21], s[0:1] op_sel_hi:[1,0]
	v_pk_mul_f32 v[22:23], v[12:13], v[10:11]
	v_pk_fma_f32 v[10:11], v[12:13], v[10:11], v[12:13] neg_lo:[1,0,0] neg_hi:[1,0,0]
	v_exp_f32_e32 v20, v20
	v_cndmask_b32_e32 v12, v10, v22, vcc
	v_cmp_gt_f32_e32 vcc, 0, v13
	v_and_b32_e32 v10, 0x7fffffff, v14
	v_exp_f32_e32 v21, v21
	v_cndmask_b32_e32 v13, v11, v23, vcc
	v_and_b32_e32 v11, 0x7fffffff, v15
	v_pk_fma_f32 v[10:11], v[10:11], s[28:29], 1.0 op_sel_hi:[1,0,0]
	v_cmp_gt_f32_e32 vcc, 0, v14
	v_rcp_f32_e32 v10, v10
	v_rcp_f32_e32 v11, v11
	s_nop 0
	v_pk_fma_f32 v[22:23], v[10:11], s[30:31], v[8:9] op_sel_hi:[1,0,0]
	v_pk_fma_f32 v[22:23], v[10:11], v[22:23], s[36:37] op_sel_hi:[1,1,0]
	v_pk_fma_f32 v[22:23], v[10:11], v[22:23], s[80:81] op_sel_hi:[1,1,0]
	v_pk_fma_f32 v[22:23], v[10:11], v[22:23], s[64:65] op_sel_hi:[1,1,0]
	v_pk_mul_f32 v[10:11], v[10:11], v[22:23]
	v_pk_mul_f32 v[22:23], v[18:19], v[18:19]
	v_pk_mul_f32 v[10:11], v[20:21], v[10:11]
	v_pk_mul_f32 v[22:23], v[22:23], s[0:1] op_sel_hi:[1,0]
	v_pk_mul_f32 v[20:21], v[14:15], v[10:11]
	v_pk_fma_f32 v[10:11], v[14:15], v[10:11], v[14:15] neg_lo:[1,0,0] neg_hi:[1,0,0]
	v_exp_f32_e32 v22, v22
	v_cndmask_b32_e32 v14, v10, v20, vcc
	v_cmp_gt_f32_e32 vcc, 0, v15
	v_and_b32_e32 v10, 0x7fffffff, v18
	v_exp_f32_e32 v23, v23
	v_cndmask_b32_e32 v15, v11, v21, vcc
	v_and_b32_e32 v11, 0x7fffffff, v19
	v_pk_fma_f32 v[10:11], v[10:11], s[28:29], 1.0 op_sel_hi:[1,0,0]
	v_cmp_gt_f32_e32 vcc, 0, v18
	v_rcp_f32_e32 v10, v10
	v_rcp_f32_e32 v11, v11
	s_nop 0
	v_pk_fma_f32 v[20:21], v[10:11], s[30:31], v[8:9] op_sel_hi:[1,0,0]
	v_pk_fma_f32 v[20:21], v[10:11], v[20:21], s[36:37] op_sel_hi:[1,1,0]
	v_pk_fma_f32 v[20:21], v[10:11], v[20:21], s[80:81] op_sel_hi:[1,1,0]
	v_pk_fma_f32 v[20:21], v[10:11], v[20:21], s[64:65] op_sel_hi:[1,1,0]
	v_pk_mul_f32 v[10:11], v[10:11], v[20:21]
	v_pk_mul_f32 v[20:21], v[16:17], v[16:17]
	v_pk_mul_f32 v[10:11], v[22:23], v[10:11]
	v_pk_mul_f32 v[22:23], v[18:19], v[10:11]
	v_pk_fma_f32 v[10:11], v[18:19], v[10:11], v[18:19] neg_lo:[1,0,0] neg_hi:[1,0,0]
	v_cndmask_b32_e32 v18, v10, v22, vcc
	v_cmp_gt_f32_e32 vcc, 0, v19
	v_and_b32_e32 v10, 0x7fffffff, v16
	s_nop 0
	v_cndmask_b32_e32 v19, v11, v23, vcc
	v_and_b32_e32 v11, 0x7fffffff, v17
	v_pk_fma_f32 v[10:11], v[10:11], s[28:29], 1.0 op_sel_hi:[1,0,0]
	v_cmp_gt_f32_e32 vcc, 0, v16
	v_rcp_f32_e32 v10, v10
	v_rcp_f32_e32 v11, v11
	s_nop 0
	v_pk_fma_f32 v[8:9], v[10:11], s[30:31], v[8:9] op_sel_hi:[1,0,0]
	v_pk_fma_f32 v[8:9], v[10:11], v[8:9], s[36:37] op_sel_hi:[1,1,0]
	v_pk_fma_f32 v[8:9], v[10:11], v[8:9], s[80:81] op_sel_hi:[1,1,0]
	v_pk_fma_f32 v[8:9], v[10:11], v[8:9], s[64:65] op_sel_hi:[1,1,0]
	v_pk_mul_f32 v[8:9], v[10:11], v[8:9]
	v_pk_mul_f32 v[10:11], v[20:21], s[0:1] op_sel_hi:[1,0]
	v_exp_f32_e32 v10, v10
	v_exp_f32_e32 v11, v11
	s_nop 0
	v_pk_mul_f32 v[8:9], v[10:11], v[8:9]
	v_pk_mul_f32 v[10:11], v[16:17], v[8:9]
	v_pk_fma_f32 v[8:9], v[16:17], v[8:9], v[16:17] neg_lo:[1,0,0] neg_hi:[1,0,0]
	s_nop 0
	v_cndmask_b32_e32 v16, v8, v10, vcc
	v_cmp_gt_f32_e32 vcc, 0, v17
	s_nop 1
	v_cndmask_b32_e32 v17, v9, v11, vcc

; __device__ __forceinline__ unsigned cvt_pk_bf16(float lo, float hi) { unsigned r; asm volatile("v_cvt_pk_bf16_f32 %0, %1, %2" : "=v"(r) : "v"(lo), "v"(hi)); return r; }
; __device__ __forceinline__ f32x2 gelu_pk(f32x2 v) {
;     const f32x2 av = __builtin_elementwise_abs(v), d = av * 0.2316418882f + 1.0f;
;     f32x2 t; t.x = __builtin_amdgcn_rcpf(d.x); t.y = __builtin_amdgcn_rcpf(d.y);
;     f32x2 q = t * 0.5307027145f + (-0.7265760135f); q = q * t + 0.7107068705f; q = q * t + (-0.142248368f); q = q * t + 0.127414796f; q = q * t;
;     const f32x2 s = (v * v) * (-0.72134752044f);
;     f32x2 e; e.x = __builtin_amdgcn_exp2f(s.x); e.y = __builtin_amdgcn_exp2f(s.y);
;     const f32x2 m = v * (q * e), r = v - m;
;     f32x2 o; o.x = v.x < 0.f ? m.x : r.x; o.y = v.y < 0.f ? m.y : r.y; return o;
;     __device__ __forceinline__ void operator()(const f32x4 (&acc)[2][2][4][2], const Unit& u, int wr, int wc, int fr, int fq) const {
;     ...
;             for (int m = 0; m < 4; ++m) { bf16_t* rowp = O + (size_t)(u.pm >> 5) * bgap + (size_t)u.pm * sm + (size_t)u.pn * sn + (size_t)(wr * 64 + fr + ai * HALF + m * 16) * ldc + wc * 32 + 8 * fq; const float sc = rs[ai][m]; float s1 = 0.f, s2 = 0.f;
; #pragma unroll
;                 for (int bj = 0; bj < 2; ++bj) { f32x4 v0 = acc[ai][bj][m][0] * sc, v1 = acc[ai][bj][m][1] * sc;
;                     if (do_gelu) { f32x2 a = gelu_pk((f32x2){v0[0], v0[1]}), b = gelu_pk((f32x2){v0[2], v0[3]}), c = gelu_pk((f32x2){v1[0], v1[1]}), d = gelu_pk((f32x2){v1[2], v1[3]});
;                         v0 = (f32x4){a.x, a.y, b.x, b.y}; v1 = (f32x4){c.x, c.y, d.x, d.y}; }
;                     if (do_stat) { s1 += ((v0[0] + v0[1]) + (v0[2] + v0[3])) + ((v1[0] + v1[1]) + (v1[2] + v1[3]));
;                         s2 += ((v0[0] * v0[0] + v0[1] * v0[1]) + (v0[2] * v0[2] + v0[3] * v0[3])) + ((v1[0] * v1[0] + v1[1] * v1[1]) + (v1[2] * v1[2] + v1[3] * v1[3])); }
;                     u32x4 w; w.x = cvt_pk_bf16(v0[0], v0[1]); w.y = cvt_pk_bf16(v0[2], v0[3]); w.z = cvt_pk_bf16(v1[0], v1[1]); w.w = cvt_pk_bf16(v1[2], v1[3]);
;                     *(u32x4*)(rowp + bj * HALF) = w; }
.LBB0_394:
	v_lshl_add_u64 v[10:11], s[16:17], 0, v[150:151]
	v_lshl_add_u64 v[10:11], v[10:11], 0, s[86:87]
	v_lshl_add_u64 v[10:11], v[10:11], 0, v[192:193]
	v_cvt_pk_bf16_f32 v12, v12, v13
	v_cvt_pk_bf16_f32 v13, v14, v15
	v_mov_b32_e32 v157, v156
	v_cvt_pk_bf16_f32 v14, v18, v19
	v_cvt_pk_bf16_f32 v15, v16, v17
	global_store_dwordx4 v[10:11], v[12:15], off
	v_pk_mul_f32 v[4:5], v[4:5], v[156:157]
	s_and_b64 vcc, exec, s[42:43]
	v_mov_b32_e32 v12, v156
	v_mov_b32_e32 v13, v156
	v_pk_mul_f32 v[6:7], v[6:7], v[12:13]
	v_pk_mul_f32 v[2:3], v[2:3], v[12:13]
	v_pk_mul_f32 v[0:1], v[0:1], v[156:157]
	s_cbranch_vccnz .LBB0_396
	v_and_b32_e32 v13, 0x7fffffff, v5
	v_and_b32_e32 v12, 0x7fffffff, v4
	v_pk_fma_f32 v[12:13], v[12:13], s[28:29], 1.0 op_sel_hi:[1,0,0]
	s_mov_b32 s0, 0xbf3a00e3
	v_rcp_f32_e32 v14, v12
	v_rcp_f32_e32 v15, v13
	v_mov_b64_e32 v[12:13], s[0:1]
	v_pk_mul_f32 v[18:19], v[4:5], v[4:5]
	s_mov_b32 s0, 0xbf38aa3b
	v_pk_fma_f32 v[16:17], v[14:15], s[30:31], v[12:13] op_sel_hi:[1,0,0]
	v_pk_mul_f32 v[18:19], v[18:19], s[0:1] op_sel_hi:[1,0]
	v_pk_fma_f32 v[16:17], v[14:15], v[16:17], s[36:37] op_sel_hi:[1,1,0]
	v_exp_f32_e32 v18, v18
	v_exp_f32_e32 v19, v19
	v_pk_fma_f32 v[16:17], v[14:15], v[16:17], s[80:81] op_sel_hi:[1,1,0]
	v_cmp_gt_f32_e32 vcc, 0, v4
	v_pk_fma_f32 v[16:17], v[14:15], v[16:17], s[64:65] op_sel_hi:[1,1,0]
	v_pk_mul_f32 v[14:15], v[14:15], v[16:17]
	v_pk_mul_f32 v[16:17], v[6:7], v[6:7]
	v_pk_mul_f32 v[14:15], v[18:19], v[14:15]
	v_pk_mul_f32 v[16:17], v[16:17], s[0:1] op_sel_hi:[1,0]
	v_pk_mul_f32 v[18:19], v[4:5], v[14:15]
	v_pk_fma_f32 v[14:15], v[4:5], v[14:15], v[4:5] neg_lo:[1,0,0] neg_hi:[1,0,0]
	v_exp_f32_e32 v16, v16
	v_cndmask_b32_e32 v4, v14, v18, vcc
	v_cmp_gt_f32_e32 vcc, 0, v5
	v_and_b32_e32 v14, 0x7fffffff, v6
	v_exp_f32_e32 v17, v17
	v_cndmask_b32_e32 v5, v15, v19, vcc
	v_and_b32_e32 v15, 0x7fffffff, v7
	v_pk_fma_f32 v[14:15], v[14:15], s[28:29], 1.0 op_sel_hi:[1,0,0]
	v_cmp_gt_f32_e32 vcc, 0, v6
	v_rcp_f32_e32 v14, v14
	v_rcp_f32_e32 v15, v15
	s_nop 0
	v_pk_fma_f32 v[18:19], v[14:15], s[30:31], v[12:13] op_sel_hi:[1,0,0]
	v_pk_fma_f32 v[18:19], v[14:15], v[18:19], s[36:37] op_sel_hi:[1,1,0]
	v_pk_fma_f32 v[18:19], v[14:15], v[18:19], s[80:81] op_sel_hi:[1,1,0]
	v_pk_fma_f32 v[18:19], v[14:15], v[18:19], s[64:65] op_sel_hi:[1,1,0]
	v_pk_mul_f32 v[14:15], v[14:15], v[18:19]
	v_pk_mul_f32 v[18:19], v[0:1], v[0:1]
	v_pk_mul_f32 v[14:15], v[16:17], v[14:15]
	v_pk_mul_f32 v[18:19], v[18:19], s[0:1] op_sel_hi:[1,0]
	v_pk_mul_f32 v[16:17], v[6:7], v[14:15]
	v_pk_fma_f32 v[14:15], v[6:7], v[14:15], v[6:7] neg_lo:[1,0,0] neg_hi:[1,0,0]
	v_exp_f32_e32 v18, v18
	v_cndmask_b32_e32 v6, v14, v16, vcc
	v_cmp_gt_f32_e32 vcc, 0, v7
	v_and_b32_e32 v14, 0x7fffffff, v0
	v_exp_f32_e32 v19, v19
	v_cndmask_b32_e32 v7, v15, v17, vcc
	v_and_b32_e32 v15, 0x7fffffff, v1
	v_pk_fma_f32 v[14:15], v[14:15], s[28:29], 1.0 op_sel_hi:[1,0,0]
	v_cmp_gt_f32_e32 vcc, 0, v0
	v_rcp_f32_e32 v14, v14
	v_rcp_f32_e32 v15, v15
	s_nop 0
	v_pk_fma_f32 v[16:17], v[14:15], s[30:31], v[12:13] op_sel_hi:[1,0,0]
	v_pk_fma_f32 v[16:17], v[14:15], v[16:17], s[36:37] op_sel_hi:[1,1,0]
	v_pk_fma_f32 v[16:17], v[14:15], v[16:17], s[80:81] op_sel_hi:[1,1,0]
	v_pk_fma_f32 v[16:17], v[14:15], v[16:17], s[64:65] op_sel_hi:[1,1,0]
	v_pk_mul_f32 v[14:15], v[14:15], v[16:17]
	v_pk_mul_f32 v[16:17], v[2:3], v[2:3]
	v_pk_mul_f32 v[14:15], v[18:19], v[14:15]
	v_pk_mul_f32 v[18:19], v[0:1], v[14:15]
	v_pk_fma_f32 v[14:15], v[0:1], v[14:15], v[0:1] neg_lo:[1,0,0] neg_hi:[1,0,0]
	v_cndmask_b32_e32 v0, v14, v18, vcc
	v_cmp_gt_f32_e32 vcc, 0, v1
	v_and_b32_e32 v14, 0x7fffffff, v2
	s_nop 0
	v_cndmask_b32_e32 v1, v15, v19, vcc
	v_and_b32_e32 v15, 0x7fffffff, v3
	v_pk_fma_f32 v[14:15], v[14:15], s[28:29], 1.0 op_sel_hi:[1,0,0]
	v_cmp_gt_f32_e32 vcc, 0, v2
	v_rcp_f32_e32 v14, v14
	v_rcp_f32_e32 v15, v15
	s_nop 0
	v_pk_fma_f32 v[12:13], v[14:15], s[30:31], v[12:13] op_sel_hi:[1,0,0]
	v_pk_fma_f32 v[12:13], v[14:15], v[12:13], s[36:37] op_sel_hi:[1,1,0]
	v_pk_fma_f32 v[12:13], v[14:15], v[12:13], s[80:81] op_sel_hi:[1,1,0]
	v_pk_fma_f32 v[12:13], v[14:15], v[12:13], s[64:65] op_sel_hi:[1,1,0]
	v_pk_mul_f32 v[12:13], v[14:15], v[12:13]
	v_pk_mul_f32 v[14:15], v[16:17], s[0:1] op_sel_hi:[1,0]
	v_exp_f32_e32 v14, v14
	v_exp_f32_e32 v15, v15
	s_nop 0
	v_pk_mul_f32 v[12:13], v[14:15], v[12:13]
	v_pk_mul_f32 v[14:15], v[2:3], v[12:13]
	v_pk_fma_f32 v[12:13], v[2:3], v[12:13], v[2:3] neg_lo:[1,0,0] neg_hi:[1,0,0]
	s_nop 0
	v_cndmask_b32_e32 v2, v12, v14, vcc
	v_cmp_gt_f32_e32 vcc, 0, v3
	s_nop 1
	v_cndmask_b32_e32 v3, v13, v15, vcc

; #define LAS __attribute__((address_space(3)))
; #define lane (hw_lane())
; __device__ __forceinline__ void sgu_item(LAS unsigned char* wl, const bf16* proj, bf16* ymix, const float* vstat, const float* sgu_g, const bf16* Wm, const float* sgu_b, int chunk, int h, int lane) {
;     ...
;     const int r = lane & 15, q = lane >> 4, c16 = lane & 3, rsub = lane >> 2;
;     LAS f32x2* st = (LAS f32x2*)(wl + 128 * VP2);
; #pragma unroll
;     for (int hh = 0; hh < 2; ++hh) { const f32x4* sp = (const f32x4*)(vstat + (R0 + lane + 64 * hh) * 16);
;         const f32x4 a = sp[0], b = sp[1], c = sp[2], d = sp[3];
;         const float s1 = ((a[0] + a[2]) + (b[0] + b[2])) + ((c[0] + c[2]) + (d[0] + d[2])), s2 = ((a[1] + a[3]) + (b[1] + b[3])) + ((c[1] + c[3]) + (d[1] + d[3]));
;         const float mean = s1 * (1.0f / 512.0f), var = fmaxf(s2 * (1.0f / 512.0f) - mean * mean, 0.f);
;         st[lane + 64 * hh] = (f32x2){mean, __builtin_amdgcn_rsqf(var + EPS)}; }
;     bf16x8 wmf[20];
;     { const bf16* wm = Wm + (size_t)(h * 128 + r) * 128 + q * 8; int f = 0;
; #pragma unroll
;       for (int ks = 0; ks < 4; ++ks)
; #pragma unroll
;         for (int tb = 2 * ks; tb < 8; ++tb) wmf[f++] = *(const bf16x8*)(wm + (size_t)(16 * tb) * 128 + ks * 32); }
;     float bias[8];
; #pragma unroll
;     for (int tb = 0; tb < 8; ++tb) bias[tb] = sgu_b[h * 128 + 16 * tb + r];
.LBB0_510:
	s_ashr_i32 s0, s5, 2
	s_ashr_i32 s1, s0, 31
	s_lshl_b64 s[8:9], s[0:1], 7
	v_mov_b32_e32 v1, s9
	v_or_b32_e32 v0, s8, v140
	v_lshlrev_b64 v[0:1], 6, v[0:1]
	v_lshl_add_u64 v[12:13], s[18:19], 0, v[0:1]
	global_load_dwordx4 v[0:3], v[12:13], off
	global_load_dwordx4 v[4:7], v[12:13], off offset:16
	global_load_dwordx4 v[8:11], v[12:13], off offset:32
	s_nop 0
	global_load_dwordx4 v[12:15], v[12:13], off offset:48
	s_mov_b32 s10, 0x3b000000
	v_mov_b32_e32 v17, s9
	v_or_b32_e32 v16, s8, v142
	s_lshl_b32 s6, s5, 7
	s_and_b32 s6, s6, 0x180
	s_lshl_b64 s[8:9], s[0:1], 18
	s_mov_b64 s[20:21], 0
	s_waitcnt vmcnt(0) lgkmcnt(0)
	v_pk_add_f32 v[0:1], v[0:1], v[2:3]
	v_pk_add_f32 v[2:3], v[4:5], v[6:7]
	v_pk_add_f32 v[4:5], v[8:9], v[10:11]
	v_pk_add_f32 v[6:7], v[12:13], v[14:15]
	v_pk_add_f32 v[0:1], v[0:1], v[2:3]
	v_pk_add_f32 v[2:3], v[4:5], v[6:7]
	v_pk_add_f32 v[0:1], v[0:1], v[2:3]
	v_lshlrev_b64 v[2:3], 6, v[16:17]
	v_pk_mul_f32 v[0:1], v[0:1], s[10:11] op_sel_hi:[1,0]
	v_lshl_add_u64 v[12:13], s[18:19], 0, v[2:3]
	v_fma_f32 v1, -v0, v0, v1
	v_max_f32_e32 v1, 0, v1
	v_add_f32_e32 v1, 0x358637bd, v1
	v_rsq_f32_e32 v1, v1
	v_or_b32_e32 v16, s6, v143
	v_lshlrev_b32_e32 v192, 8, v16
	v_lshlrev_b32_e32 v18, 2, v16
	ds_write_b64 v141, v[0:1] offset:10240
	global_load_dwordx4 v[0:3], v[12:13], off
	global_load_dwordx4 v[4:7], v[12:13], off offset:16
	global_load_dwordx4 v[8:11], v[12:13], off offset:32
	s_nop 0
	global_load_dwordx4 v[12:15], v[12:13], off offset:48
	v_lshl_add_u64 v[16:17], v[144:145], 0, v[192:193]
	s_movk_i32 s6, 0x1000
	global_load_dword v162, v18, s[14:15]
	global_load_dword v164, v18, s[14:15] offset:64
	global_load_dword v166, v18, s[14:15] offset:128
	global_load_dword v168, v18, s[14:15] offset:192
	global_load_dword v170, v18, s[14:15] offset:256
	global_load_dword v172, v18, s[14:15] offset:320
	global_load_dword v174, v18, s[14:15] offset:384
	global_load_dword v176, v18, s[14:15] offset:448
	v_add_co_u32_e32 v18, vcc, s6, v16
	s_movk_i32 s6, 0x2000
	s_nop 0
	v_addc_co_u32_e32 v19, vcc, 0, v17, vcc
	v_add_co_u32_e32 v20, vcc, s6, v16
	s_movk_i32 s6, 0x3000
	s_nop 0
	v_addc_co_u32_e32 v21, vcc, 0, v17, vcc
	v_add_co_u32_e32 v22, vcc, s6, v16
	s_movk_i32 s6, 0x4000
	s_nop 0
	v_addc_co_u32_e32 v23, vcc, 0, v17, vcc
	v_add_co_u32_e32 v52, vcc, s6, v16
	s_movk_i32 s6, 0x5000
	s_nop 0
	v_addc_co_u32_e32 v53, vcc, 0, v17, vcc
	v_add_co_u32_e32 v60, vcc, s6, v16
	s_movk_i32 s6, 0x6000
	s_nop 0
	v_addc_co_u32_e32 v61, vcc, 0, v17, vcc
	v_add_co_u32_e32 v68, vcc, s6, v16
	s_movk_i32 s6, 0x7000
	s_nop 0
	v_addc_co_u32_e32 v69, vcc, 0, v17, vcc
	v_add_co_u32_e32 v76, vcc, s6, v16
	s_lshl_b32 s6, s4, 1
	s_nop 0
	v_addc_co_u32_e32 v77, vcc, 0, v17, vcc
	s_waitcnt vmcnt(0)
	v_mov_b32_e32 v163, v162
	s_waitcnt lgkmcnt(0)
	v_pk_add_f32 v[0:1], v[0:1], v[2:3]
	v_pk_add_f32 v[2:3], v[4:5], v[6:7]
	v_pk_add_f32 v[4:5], v[8:9], v[10:11]
	v_pk_add_f32 v[6:7], v[12:13], v[14:15]
	v_pk_add_f32 v[0:1], v[0:1], v[2:3]
	v_pk_add_f32 v[2:3], v[4:5], v[6:7]
	v_mov_b32_e32 v165, v164
	v_pk_add_f32 v[0:1], v[0:1], v[2:3]
	v_mov_b32_e32 v167, v166
	v_pk_mul_f32 v[0:1], v[0:1], s[10:11] op_sel_hi:[1,0]
	s_and_b32 s10, s6, 0x300
	v_fma_f32 v1, -v0, v0, v1
	v_max_f32_e32 v1, 0, v1
	v_add_f32_e32 v1, 0x358637bd, v1
	v_rsq_f32_e32 v1, v1
	s_lshl_b32 s6, s4, 2
	s_and_b32 s86, s6, 0x600
	s_ashr_i32 s6, s5, 8
	ds_write_b64 v141, v[0:1] offset:10752
	global_load_dwordx4 v[0:3], v[16:17], off
	global_load_dwordx4 v[4:7], v[18:19], off
	global_load_dwordx4 v[8:11], v[20:21], off
	global_load_dwordx4 v[12:15], v[20:21], off offset:64
	s_nop 0
	global_load_dwordx4 v[16:19], v[22:23], off
	s_nop 0
	global_load_dwordx4 v[20:23], v[22:23], off offset:64
	s_nop 0
	global_load_dwordx4 v[24:27], v[52:53], off
	global_load_dwordx4 v[28:31], v[52:53], off offset:64
	global_load_dwordx4 v[32:35], v[68:69], off
	global_load_dwordx4 v[36:39], v[68:69], off offset:64
	global_load_dwordx4 v[40:43], v[76:77], off
	global_load_dwordx4 v[44:47], v[76:77], off offset:64
	global_load_dwordx4 v[48:51], v[60:61], off
	s_nop 0
	global_load_dwordx4 v[52:55], v[52:53], off offset:128
	s_nop 0
	global_load_dwordx4 v[56:59], v[60:61], off offset:64
	s_nop 0
	global_load_dwordx4 v[60:63], v[60:61], off offset:128
	s_nop 0
	global_load_dwordx4 v[64:67], v[68:69], off offset:128
	s_nop 0
	global_load_dwordx4 v[68:71], v[68:69], off offset:192
	s_nop 0
	global_load_dwordx4 v[72:75], v[76:77], off offset:128
	s_nop 0
	global_load_dwordx4 v[76:79], v[76:77], off offset:192
	s_mul_hi_i32 s11, s6, 0x1400000
	s_mul_i32 s12, s6, 0x1400000
	s_mul_hi_i32 s13, s6, 0x1c00000
	s_mul_i32 s6, s6, 0x1c00000
	s_add_u32 s1, s6, s8
	s_addc_u32 s9, s13, s9
	s_or_b32 s8, s1, s10
	s_mul_hi_i32 s1, s0, 0x60000
	s_mul_i32 s0, s0, 0x60000
	s_waitcnt lgkmcnt(0)
	s_add_u32 s0, s12, s0
	s_addc_u32 s1, s11, s1
	s_or_b32 s0, s0, s10
	v_lshl_add_u64 v[178:179], v[160:161], 0, s[86:87]
	v_mov_b32_e32 v169, v168
	v_mov_b32_e32 v171, v170
	v_mov_b32_e32 v173, v172
	v_mov_b32_e32 v175, v174
	v_mov_b32_e32 v177, v176
	v_lshl_add_u64 v[180:181], v[146:147], 0, s[8:9]
	v_lshl_add_u64 v[182:183], v[148:149], 0, s[8:9]
	v_lshl_add_u64 v[184:185], v[150:151], 0, s[8:9]
	v_lshl_add_u64 v[186:187], v[152:153], 0, s[0:1]
	v_lshl_add_u64 v[188:189], v[154:155], 0, s[0:1]
	v_lshl_add_u64 v[190:191], v[156:157], 0, s[0:1]
	v_lshl_add_u64 v[198:199], v[158:159], 0, s[0:1]
; #define LAS __attribute__((address_space(3)))
; __device__ __forceinline__ unsigned pk2(float lo, float hi) { return f2bf(lo) | (f2bf(hi) << 16); }
; __device__ __forceinline__ float bflo(unsigned w) { return __uint_as_float(w << 16); }
; __device__ __forceinline__ float bfhi(unsigned w) { return __uint_as_float(w & 0xffff0000u); }
; __device__ __forceinline__ void sgu_item(LAS unsigned char* wl, const bf16* proj, bf16* ymix, const float* vstat, const float* sgu_g, const bf16* Wm, const float* sgu_b, int chunk, int h, int lane) {
;     ...
;     for (int dq = 0; dq < 4; ++dq) {
;         const int colv = h * 128 + dq * 32;
;         v4u raw[8];
; #pragma unroll
;         for (int i = 0; i < 8; ++i) raw[i] = __builtin_nontemporal_load((const v4u*)(proj + (R0 + rsub + 16 * i) * DIN + 1024 + colv + c16 * 8));
;         const f32x4 g0 = *(const f32x4*)(sgu_g + colv + c16 * 8), g1 = *(const f32x4*)(sgu_g + colv + c16 * 8 + 4);
; #pragma unroll
;         for (int i = 0; i < 8; ++i) { const int s = rsub + 16 * i; const f32x2 ms = st[s]; const v4u w = raw[i];
;             v2u lo, hi; lo.x = pk2((bflo(w.x) - ms.x) * ms.y * g0[0], (bfhi(w.x) - ms.x) * ms.y * g0[1]); lo.y = pk2((bflo(w.y) - ms.x) * ms.y * g0[2], (bfhi(w.y) - ms.x) * ms.y * g0[3]);
;             hi.x = pk2((bflo(w.z) - ms.x) * ms.y * g1[0], (bfhi(w.z) - ms.x) * ms.y * g1[1]); hi.y = pk2((bflo(w.w) - ms.x) * ms.y * g1[2], (bfhi(w.w) - ms.x) * ms.y * g1[3]);
;             *(LAS v2u*)(wl + s * VP2 + (4 * c16) * 2) = lo; *(LAS v2u*)(wl + s * VP2 + (16 + 4 * c16) * 2) = hi; }
.LBB0_511:
	v_lshl_add_u64 v[80:81], v[198:199], 0, s[20:21]
	v_add_co_u32_e32 v82, vcc, 0xf100000, v80
	s_mov_b32 s0, 0xf100000
	s_nop 0
	v_addc_co_u32_e32 v83, vcc, 0, v81, vcc
	global_load_dwordx4 v[118:121], v[82:83], off offset:2048 nt
	v_add_co_u32_e32 v82, vcc, 0xf10c000, v80
	s_waitcnt lgkmcnt(0)
	s_nop 0
	v_addc_co_u32_e32 v83, vcc, 0, v81, vcc
	global_load_dwordx4 v[112:115], v[82:83], off offset:2048 nt
	v_add_co_u32_e32 v82, vcc, 0xf118000, v80
	s_nop 0
	s_nop 0
	v_addc_co_u32_e32 v83, vcc, 0, v81, vcc
	global_load_dwordx4 v[108:111], v[82:83], off offset:2048 nt
	v_add_co_u32_e32 v82, vcc, 0xf124000, v80
	s_nop 0
	s_nop 0
	v_addc_co_u32_e32 v83, vcc, 0, v81, vcc
	global_load_dwordx4 v[104:107], v[82:83], off offset:2048 nt
	v_add_co_u32_e32 v82, vcc, 0xf130000, v80
	s_nop 0
	s_nop 0
	v_addc_co_u32_e32 v83, vcc, 0, v81, vcc
	global_load_dwordx4 v[100:103], v[82:83], off offset:2048 nt
	v_add_co_u32_e32 v82, vcc, 0xf13c000, v80
	s_nop 1
	v_addc_co_u32_e32 v83, vcc, 0, v81, vcc
	global_load_dwordx4 v[96:99], v[82:83], off offset:2048 nt
	v_add_co_u32_e32 v82, vcc, 0xf148000, v80
	s_nop 1
	v_addc_co_u32_e32 v83, vcc, 0, v81, vcc
	v_add_co_u32_e32 v80, vcc, 0xf154000, v80
	global_load_dwordx4 v[84:87], v[82:83], off offset:2048 nt
	s_nop 0
	v_addc_co_u32_e32 v81, vcc, 0, v81, vcc
	global_load_dwordx4 v[80:83], v[80:81], off offset:2048 nt
	s_nop 0
	global_load_dwordx4 v[88:91], v[178:179], off
	global_load_dwordx4 v[92:95], v[178:179], off offset:-16
	s_waitcnt vmcnt(0)
	v_lshlrev_b32_e32 v117, 16, v119
	v_lshlrev_b32_e32 v116, 16, v118
	v_and_b32_e32 v119, 0xffff0000, v119
	v_and_b32_e32 v118, 0xffff0000, v118
	ds_read_b64 v[122:123], v218 offset:10240
	v_lshl_add_u64 v[178:179], v[178:179], 0, s[88:89]
	s_waitcnt lgkmcnt(0)
	v_pk_add_f32 v[116:117], v[116:117], v[122:123] op_sel_hi:[1,0] neg_lo:[0,1] neg_hi:[0,1]
	v_pk_mul_f32 v[124:125], v[122:123], v[116:117] op_sel:[1,0]
	v_pk_add_f32 v[118:119], v[118:119], v[122:123] op_sel_hi:[1,0] neg_lo:[0,1] neg_hi:[0,1]
	s_waitcnt vmcnt(0)
	v_mov_b32_e32 v116, v92
	v_mov_b32_e32 v117, v94
	v_pk_mul_f32 v[124:125], v[116:117], v[124:125]
	v_pk_mul_f32 v[118:119], v[122:123], v[118:119] op_sel:[1,0]
	v_mov_b32_e32 v94, v93
	v_pk_mul_f32 v[92:93], v[94:95], v[118:119]
	v_and_b32_sdwa v118, v125, v245 dst_sel:DWORD dst_unused:UNUSED_PAD src0_sel:WORD_1 src1_sel:DWORD
	v_and_b32_sdwa v119, v124, v245 dst_sel:DWORD dst_unused:UNUSED_PAD src0_sel:WORD_1 src1_sel:DWORD
	v_add3_u32 v124, v124, v119, s68
	v_add3_u32 v118, v125, v118, s68
	v_and_b32_sdwa v119, v93, v245 dst_sel:DWORD dst_unused:UNUSED_PAD src0_sel:WORD_1 src1_sel:DWORD
	v_and_b32_sdwa v125, v92, v245 dst_sel:DWORD dst_unused:UNUSED_PAD src0_sel:WORD_1 src1_sel:DWORD
	v_add3_u32 v93, v93, v119, s68
	v_add3_u32 v92, v92, v125, s68
	v_and_b32_e32 v93, 0xffff0000, v93
	v_and_b32_e32 v92, 0xffff0000, v92
	v_or_b32_sdwa v119, v93, v118 dst_sel:DWORD dst_unused:UNUSED_PAD src0_sel:DWORD src1_sel:WORD_1
	v_or_b32_sdwa v118, v92, v124 dst_sel:DWORD dst_unused:UNUSED_PAD src0_sel:DWORD src1_sel:WORD_1
	v_lshlrev_b32_e32 v93, 16, v121
	v_lshlrev_b32_e32 v92, 16, v120
	v_and_b32_e32 v121, 0xffff0000, v121
	v_and_b32_e32 v120, 0xffff0000, v120
	v_pk_add_f32 v[92:93], v[92:93], v[122:123] op_sel_hi:[1,0] neg_lo:[0,1] neg_hi:[0,1]
	v_pk_add_f32 v[120:121], v[120:121], v[122:123] op_sel_hi:[1,0] neg_lo:[0,1] neg_hi:[0,1]
	v_pk_mul_f32 v[124:125], v[122:123], v[92:93] op_sel:[1,0]
	v_mov_b32_e32 v93, v90
	v_pk_mul_f32 v[120:121], v[122:123], v[120:121] op_sel:[1,0]
	v_mov_b32_e32 v90, v89
	v_mov_b32_e32 v92, v88
	v_pk_mul_f32 v[88:89], v[90:91], v[120:121]
	v_pk_mul_f32 v[124:125], v[92:93], v[124:125]
	v_and_b32_sdwa v122, v89, v245 dst_sel:DWORD dst_unused:UNUSED_PAD src0_sel:WORD_1 src1_sel:DWORD
	v_and_b32_sdwa v123, v88, v245 dst_sel:DWORD dst_unused:UNUSED_PAD src0_sel:WORD_1 src1_sel:DWORD
	v_and_b32_sdwa v120, v125, v245 dst_sel:DWORD dst_unused:UNUSED_PAD src0_sel:WORD_1 src1_sel:DWORD
	v_and_b32_sdwa v121, v124, v245 dst_sel:DWORD dst_unused:UNUSED_PAD src0_sel:WORD_1 src1_sel:DWORD
	v_add3_u32 v89, v89, v122, s68
	v_add3_u32 v88, v88, v123, s68
	v_add3_u32 v121, v124, v121, s68
	v_add3_u32 v120, v125, v120, s68
	v_and_b32_e32 v89, 0xffff0000, v89
	v_and_b32_e32 v88, 0xffff0000, v88
	v_or_b32_sdwa v89, v89, v120 dst_sel:DWORD dst_unused:UNUSED_PAD src0_sel:DWORD src1_sel:WORD_1
	v_or_b32_sdwa v88, v88, v121 dst_sel:DWORD dst_unused:UNUSED_PAD src0_sel:DWORD src1_sel:WORD_1
	ds_write2_b64 v219, v[118:119], v[88:89] offset1:4
	ds_read_b64 v[88:89], v218 offset:10368
	v_lshlrev_b32_e32 v119, 16, v113
	v_lshlrev_b32_e32 v118, 16, v112
	v_and_b32_e32 v113, 0xffff0000, v113
	v_and_b32_e32 v112, 0xffff0000, v112
	s_waitcnt lgkmcnt(0)
; #define LAS __attribute__((address_space(3)))
; __device__ __forceinline__ unsigned pk2(float lo, float hi) { return f2bf(lo) | (f2bf(hi) << 16); }
; __device__ __forceinline__ float bflo(unsigned w) { return __uint_as_float(w << 16); }
; __device__ __forceinline__ float bfhi(unsigned w) { return __uint_as_float(w & 0xffff0000u); }
; __device__ __forceinline__ void sgu_item(LAS unsigned char* wl, const bf16* proj, bf16* ymix, const float* vstat, const float* sgu_g, const bf16* Wm, const float* sgu_b, int chunk, int h, int lane) {
;     ...
;         for (int i = 0; i < 8; ++i) { const int s = rsub + 16 * i; const f32x2 ms = st[s]; const v4u w = raw[i];
;             v2u lo, hi; lo.x = pk2((bflo(w.x) - ms.x) * ms.y * g0[0], (bfhi(w.x) - ms.x) * ms.y * g0[1]); lo.y = pk2((bflo(w.y) - ms.x) * ms.y * g0[2], (bfhi(w.y) - ms.x) * ms.y * g0[3]);
;             hi.x = pk2((bflo(w.z) - ms.x) * ms.y * g1[0], (bfhi(w.z) - ms.x) * ms.y * g1[1]); hi.y = pk2((bflo(w.w) - ms.x) * ms.y * g1[2], (bfhi(w.w) - ms.x) * ms.y * g1[3]);
;             *(LAS v2u*)(wl + s * VP2 + (4 * c16) * 2) = lo; *(LAS v2u*)(wl + s * VP2 + (16 + 4 * c16) * 2) = hi; }
	v_pk_add_f32 v[118:119], v[118:119], v[88:89] op_sel_hi:[1,0] neg_lo:[0,1] neg_hi:[0,1]
	v_pk_add_f32 v[112:113], v[112:113], v[88:89] op_sel_hi:[1,0] neg_lo:[0,1] neg_hi:[0,1]
	v_pk_mul_f32 v[118:119], v[88:89], v[118:119] op_sel:[1,0]
	v_pk_mul_f32 v[112:113], v[88:89], v[112:113] op_sel:[1,0]
	v_pk_mul_f32 v[118:119], v[116:117], v[118:119]
	v_pk_mul_f32 v[112:113], v[94:95], v[112:113]
	v_and_b32_sdwa v120, v119, v245 dst_sel:DWORD dst_unused:UNUSED_PAD src0_sel:WORD_1 src1_sel:DWORD
	v_and_b32_sdwa v121, v118, v245 dst_sel:DWORD dst_unused:UNUSED_PAD src0_sel:WORD_1 src1_sel:DWORD
	v_add3_u32 v118, v118, v121, s68
	v_add3_u32 v119, v119, v120, s68
	v_and_b32_sdwa v120, v113, v245 dst_sel:DWORD dst_unused:UNUSED_PAD src0_sel:WORD_1 src1_sel:DWORD
	v_and_b32_sdwa v121, v112, v245 dst_sel:DWORD dst_unused:UNUSED_PAD src0_sel:WORD_1 src1_sel:DWORD
	v_add3_u32 v113, v113, v120, s68
	v_add3_u32 v112, v112, v121, s68
	v_and_b32_e32 v113, 0xffff0000, v113
	v_and_b32_e32 v112, 0xffff0000, v112
	v_or_b32_sdwa v113, v113, v119 dst_sel:DWORD dst_unused:UNUSED_PAD src0_sel:DWORD src1_sel:WORD_1
	v_or_b32_sdwa v112, v112, v118 dst_sel:DWORD dst_unused:UNUSED_PAD src0_sel:DWORD src1_sel:WORD_1
	v_lshlrev_b32_e32 v119, 16, v115
	v_lshlrev_b32_e32 v118, 16, v114
	v_pk_add_f32 v[118:119], v[118:119], v[88:89] op_sel_hi:[1,0] neg_lo:[0,1] neg_hi:[0,1]
	v_and_b32_e32 v115, 0xffff0000, v115
	v_and_b32_e32 v114, 0xffff0000, v114
	v_pk_mul_f32 v[118:119], v[88:89], v[118:119] op_sel:[1,0]
	v_pk_add_f32 v[114:115], v[114:115], v[88:89] op_sel_hi:[1,0] neg_lo:[0,1] neg_hi:[0,1]
	v_pk_mul_f32 v[118:119], v[92:93], v[118:119]
	v_pk_mul_f32 v[88:89], v[88:89], v[114:115] op_sel:[1,0]
	v_and_b32_sdwa v114, v119, v245 dst_sel:DWORD dst_unused:UNUSED_PAD src0_sel:WORD_1 src1_sel:DWORD
	v_pk_mul_f32 v[88:89], v[90:91], v[88:89]
	v_and_b32_sdwa v115, v118, v245 dst_sel:DWORD dst_unused:UNUSED_PAD src0_sel:WORD_1 src1_sel:DWORD
	v_add3_u32 v115, v118, v115, s68
	v_add3_u32 v114, v119, v114, s68
	v_and_b32_sdwa v118, v89, v245 dst_sel:DWORD dst_unused:UNUSED_PAD src0_sel:WORD_1 src1_sel:DWORD
	v_and_b32_sdwa v119, v88, v245 dst_sel:DWORD dst_unused:UNUSED_PAD src0_sel:WORD_1 src1_sel:DWORD
	v_add3_u32 v89, v89, v118, s68
	v_add3_u32 v88, v88, v119, s68
	v_and_b32_e32 v89, 0xffff0000, v89
	v_and_b32_e32 v88, 0xffff0000, v88
	v_or_b32_sdwa v89, v89, v114 dst_sel:DWORD dst_unused:UNUSED_PAD src0_sel:DWORD src1_sel:WORD_1
	v_or_b32_sdwa v88, v88, v115 dst_sel:DWORD dst_unused:UNUSED_PAD src0_sel:DWORD src1_sel:WORD_1
	ds_write2_b64 v219, v[112:113], v[88:89] offset0:160 offset1:164
	ds_read_b64 v[112:113], v218 offset:10496
	v_lshlrev_b32_e32 v89, 16, v109
	v_lshlrev_b32_e32 v88, 16, v108
	v_and_b32_e32 v109, 0xffff0000, v109
	v_and_b32_e32 v108, 0xffff0000, v108
	s_waitcnt lgkmcnt(0)
	v_pk_add_f32 v[88:89], v[88:89], v[112:113] op_sel_hi:[1,0] neg_lo:[0,1] neg_hi:[0,1]
	v_pk_add_f32 v[108:109], v[108:109], v[112:113] op_sel_hi:[1,0] neg_lo:[0,1] neg_hi:[0,1]
	v_pk_mul_f32 v[88:89], v[112:113], v[88:89] op_sel:[1,0]
	v_pk_mul_f32 v[108:109], v[112:113], v[108:109] op_sel:[1,0]
	v_pk_mul_f32 v[88:89], v[116:117], v[88:89]
	v_pk_mul_f32 v[108:109], v[94:95], v[108:109]
	v_and_b32_sdwa v114, v89, v245 dst_sel:DWORD dst_unused:UNUSED_PAD src0_sel:WORD_1 src1_sel:DWORD
	v_and_b32_sdwa v115, v88, v245 dst_sel:DWORD dst_unused:UNUSED_PAD src0_sel:WORD_1 src1_sel:DWORD
	v_add3_u32 v88, v88, v115, s68
	v_add3_u32 v89, v89, v114, s68
	v_and_b32_sdwa v114, v109, v245 dst_sel:DWORD dst_unused:UNUSED_PAD src0_sel:WORD_1 src1_sel:DWORD
	v_and_b32_sdwa v115, v108, v245 dst_sel:DWORD dst_unused:UNUSED_PAD src0_sel:WORD_1 src1_sel:DWORD
	v_add3_u32 v109, v109, v114, s68
	v_add3_u32 v108, v108, v115, s68
	v_and_b32_e32 v109, 0xffff0000, v109
	v_and_b32_e32 v108, 0xffff0000, v108
	v_or_b32_sdwa v89, v109, v89 dst_sel:DWORD dst_unused:UNUSED_PAD src0_sel:DWORD src1_sel:WORD_1
	v_or_b32_sdwa v88, v108, v88 dst_sel:DWORD dst_unused:UNUSED_PAD src0_sel:DWORD src1_sel:WORD_1
	v_lshlrev_b32_e32 v109, 16, v111
	v_lshlrev_b32_e32 v108, 16, v110
	v_pk_add_f32 v[108:109], v[108:109], v[112:113] op_sel_hi:[1,0] neg_lo:[0,1] neg_hi:[0,1]
	v_and_b32_e32 v111, 0xffff0000, v111
	v_and_b32_e32 v110, 0xffff0000, v110
	v_pk_mul_f32 v[108:109], v[112:113], v[108:109] op_sel:[1,0]
	v_pk_add_f32 v[110:111], v[110:111], v[112:113] op_sel_hi:[1,0] neg_lo:[0,1] neg_hi:[0,1]
	v_pk_mul_f32 v[108:109], v[92:93], v[108:109]
	v_pk_mul_f32 v[110:111], v[112:113], v[110:111] op_sel:[1,0]
	v_and_b32_sdwa v112, v109, v245 dst_sel:DWORD dst_unused:UNUSED_PAD src0_sel:WORD_1 src1_sel:DWORD
	v_pk_mul_f32 v[110:111], v[90:91], v[110:111]
	v_and_b32_sdwa v113, v108, v245 dst_sel:DWORD dst_unused:UNUSED_PAD src0_sel:WORD_1 src1_sel:DWORD
	v_add3_u32 v108, v108, v113, s68
	v_add3_u32 v109, v109, v112, s68
	v_and_b32_sdwa v112, v111, v245 dst_sel:DWORD dst_unused:UNUSED_PAD src0_sel:WORD_1 src1_sel:DWORD
	v_and_b32_sdwa v113, v110, v245 dst_sel:DWORD dst_unused:UNUSED_PAD src0_sel:WORD_1 src1_sel:DWORD
	v_add3_u32 v111, v111, v112, s68
	v_add3_u32 v110, v110, v113, s68
	v_and_b32_e32 v111, 0xffff0000, v111
	v_and_b32_e32 v110, 0xffff0000, v110
	v_or_b32_sdwa v109, v111, v109 dst_sel:DWORD dst_unused:UNUSED_PAD src0_sel:DWORD src1_sel:WORD_1
	v_or_b32_sdwa v108, v110, v108 dst_sel:DWORD dst_unused:UNUSED_PAD src0_sel:DWORD src1_sel:WORD_1
	v_add_u32_e32 v110, 0x800, v219
	ds_write2_b64 v110, v[88:89], v[108:109] offset0:64 offset1:68
	ds_read_b64 v[88:89], v218 offset:10624
	v_lshlrev_b32_e32 v109, 16, v105
	v_lshlrev_b32_e32 v108, 16, v104
	v_and_b32_e32 v105, 0xffff0000, v105
	v_and_b32_e32 v104, 0xffff0000, v104
	s_waitcnt lgkmcnt(0)
; #define LAS __attribute__((address_space(3)))
; __device__ __forceinline__ unsigned pk2(float lo, float hi) { return f2bf(lo) | (f2bf(hi) << 16); }
; __device__ __forceinline__ float bflo(unsigned w) { return __uint_as_float(w << 16); }
; __device__ __forceinline__ float bfhi(unsigned w) { return __uint_as_float(w & 0xffff0000u); }
; __device__ __forceinline__ void sgu_item(LAS unsigned char* wl, const bf16* proj, bf16* ymix, const float* vstat, const float* sgu_g, const bf16* Wm, const float* sgu_b, int chunk, int h, int lane) {
;     ...
;         for (int i = 0; i < 8; ++i) { const int s = rsub + 16 * i; const f32x2 ms = st[s]; const v4u w = raw[i];
;             v2u lo, hi; lo.x = pk2((bflo(w.x) - ms.x) * ms.y * g0[0], (bfhi(w.x) - ms.x) * ms.y * g0[1]); lo.y = pk2((bflo(w.y) - ms.x) * ms.y * g0[2], (bfhi(w.y) - ms.x) * ms.y * g0[3]);
;             hi.x = pk2((bflo(w.z) - ms.x) * ms.y * g1[0], (bfhi(w.z) - ms.x) * ms.y * g1[1]); hi.y = pk2((bflo(w.w) - ms.x) * ms.y * g1[2], (bfhi(w.w) - ms.x) * ms.y * g1[3]);
;             *(LAS v2u*)(wl + s * VP2 + (4 * c16) * 2) = lo; *(LAS v2u*)(wl + s * VP2 + (16 + 4 * c16) * 2) = hi; }
	v_pk_add_f32 v[108:109], v[108:109], v[88:89] op_sel_hi:[1,0] neg_lo:[0,1] neg_hi:[0,1]
	v_pk_add_f32 v[104:105], v[104:105], v[88:89] op_sel_hi:[1,0] neg_lo:[0,1] neg_hi:[0,1]
	v_pk_mul_f32 v[108:109], v[88:89], v[108:109] op_sel:[1,0]
	v_pk_mul_f32 v[104:105], v[88:89], v[104:105] op_sel:[1,0]
	v_pk_mul_f32 v[108:109], v[116:117], v[108:109]
	v_pk_mul_f32 v[104:105], v[94:95], v[104:105]
	v_and_b32_sdwa v111, v109, v245 dst_sel:DWORD dst_unused:UNUSED_PAD src0_sel:WORD_1 src1_sel:DWORD
	v_and_b32_sdwa v112, v108, v245 dst_sel:DWORD dst_unused:UNUSED_PAD src0_sel:WORD_1 src1_sel:DWORD
	v_add3_u32 v108, v108, v112, s68
	v_add3_u32 v109, v109, v111, s68
	v_and_b32_sdwa v111, v105, v245 dst_sel:DWORD dst_unused:UNUSED_PAD src0_sel:WORD_1 src1_sel:DWORD
	v_and_b32_sdwa v112, v104, v245 dst_sel:DWORD dst_unused:UNUSED_PAD src0_sel:WORD_1 src1_sel:DWORD
	v_add3_u32 v105, v105, v111, s68
	v_add3_u32 v104, v104, v112, s68
	v_and_b32_e32 v105, 0xffff0000, v105
	v_and_b32_e32 v104, 0xffff0000, v104
	v_or_b32_sdwa v105, v105, v109 dst_sel:DWORD dst_unused:UNUSED_PAD src0_sel:DWORD src1_sel:WORD_1
	v_or_b32_sdwa v104, v104, v108 dst_sel:DWORD dst_unused:UNUSED_PAD src0_sel:DWORD src1_sel:WORD_1
	v_lshlrev_b32_e32 v109, 16, v107
	v_lshlrev_b32_e32 v108, 16, v106
	v_pk_add_f32 v[108:109], v[108:109], v[88:89] op_sel_hi:[1,0] neg_lo:[0,1] neg_hi:[0,1]
	v_and_b32_e32 v107, 0xffff0000, v107
	v_and_b32_e32 v106, 0xffff0000, v106
	v_pk_mul_f32 v[108:109], v[88:89], v[108:109] op_sel:[1,0]
	v_pk_add_f32 v[106:107], v[106:107], v[88:89] op_sel_hi:[1,0] neg_lo:[0,1] neg_hi:[0,1]
	v_pk_mul_f32 v[108:109], v[92:93], v[108:109]
	v_pk_mul_f32 v[88:89], v[88:89], v[106:107] op_sel:[1,0]
	v_and_b32_sdwa v106, v109, v245 dst_sel:DWORD dst_unused:UNUSED_PAD src0_sel:WORD_1 src1_sel:DWORD
	v_pk_mul_f32 v[88:89], v[90:91], v[88:89]
	v_and_b32_sdwa v107, v108, v245 dst_sel:DWORD dst_unused:UNUSED_PAD src0_sel:WORD_1 src1_sel:DWORD
	v_add3_u32 v107, v108, v107, s68
	v_add3_u32 v106, v109, v106, s68
	v_and_b32_sdwa v108, v89, v245 dst_sel:DWORD dst_unused:UNUSED_PAD src0_sel:WORD_1 src1_sel:DWORD
	v_and_b32_sdwa v109, v88, v245 dst_sel:DWORD dst_unused:UNUSED_PAD src0_sel:WORD_1 src1_sel:DWORD
	v_add3_u32 v89, v89, v108, s68
	v_add3_u32 v88, v88, v109, s68
	v_and_b32_e32 v89, 0xffff0000, v89
	v_and_b32_e32 v88, 0xffff0000, v88
	v_or_b32_sdwa v89, v89, v106 dst_sel:DWORD dst_unused:UNUSED_PAD src0_sel:DWORD src1_sel:WORD_1
	v_or_b32_sdwa v88, v88, v107 dst_sel:DWORD dst_unused:UNUSED_PAD src0_sel:DWORD src1_sel:WORD_1
	ds_write2_b64 v110, v[104:105], v[88:89] offset0:224 offset1:228
	ds_read_b64 v[104:105], v218 offset:10752
	v_lshlrev_b32_e32 v89, 16, v101
	v_lshlrev_b32_e32 v88, 16, v100
	v_and_b32_e32 v101, 0xffff0000, v101
	v_and_b32_e32 v100, 0xffff0000, v100
	s_waitcnt lgkmcnt(0)
	v_pk_add_f32 v[88:89], v[88:89], v[104:105] op_sel_hi:[1,0] neg_lo:[0,1] neg_hi:[0,1]
	v_pk_add_f32 v[100:101], v[100:101], v[104:105] op_sel_hi:[1,0] neg_lo:[0,1] neg_hi:[0,1]
	v_pk_mul_f32 v[88:89], v[104:105], v[88:89] op_sel:[1,0]
	v_pk_mul_f32 v[100:101], v[104:105], v[100:101] op_sel:[1,0]
	v_pk_mul_f32 v[88:89], v[116:117], v[88:89]
	v_pk_mul_f32 v[100:101], v[94:95], v[100:101]
	v_and_b32_sdwa v106, v89, v245 dst_sel:DWORD dst_unused:UNUSED_PAD src0_sel:WORD_1 src1_sel:DWORD
	v_and_b32_sdwa v107, v88, v245 dst_sel:DWORD dst_unused:UNUSED_PAD src0_sel:WORD_1 src1_sel:DWORD
	v_add3_u32 v88, v88, v107, s68
	v_add3_u32 v89, v89, v106, s68
	v_and_b32_sdwa v106, v101, v245 dst_sel:DWORD dst_unused:UNUSED_PAD src0_sel:WORD_1 src1_sel:DWORD
	v_and_b32_sdwa v107, v100, v245 dst_sel:DWORD dst_unused:UNUSED_PAD src0_sel:WORD_1 src1_sel:DWORD
	v_add3_u32 v101, v101, v106, s68
	v_add3_u32 v100, v100, v107, s68
	v_and_b32_e32 v101, 0xffff0000, v101
	v_and_b32_e32 v100, 0xffff0000, v100
	v_or_b32_sdwa v89, v101, v89 dst_sel:DWORD dst_unused:UNUSED_PAD src0_sel:DWORD src1_sel:WORD_1
	v_or_b32_sdwa v88, v100, v88 dst_sel:DWORD dst_unused:UNUSED_PAD src0_sel:DWORD src1_sel:WORD_1
	v_lshlrev_b32_e32 v101, 16, v103
	v_lshlrev_b32_e32 v100, 16, v102
	v_pk_add_f32 v[100:101], v[100:101], v[104:105] op_sel_hi:[1,0] neg_lo:[0,1] neg_hi:[0,1]
	v_and_b32_e32 v103, 0xffff0000, v103
	v_and_b32_e32 v102, 0xffff0000, v102
	v_pk_mul_f32 v[100:101], v[104:105], v[100:101] op_sel:[1,0]
	v_pk_add_f32 v[102:103], v[102:103], v[104:105] op_sel_hi:[1,0] neg_lo:[0,1] neg_hi:[0,1]
	v_pk_mul_f32 v[100:101], v[92:93], v[100:101]
	v_pk_mul_f32 v[102:103], v[104:105], v[102:103] op_sel:[1,0]
	v_and_b32_sdwa v104, v101, v245 dst_sel:DWORD dst_unused:UNUSED_PAD src0_sel:WORD_1 src1_sel:DWORD
	v_pk_mul_f32 v[102:103], v[90:91], v[102:103]
	v_and_b32_sdwa v105, v100, v245 dst_sel:DWORD dst_unused:UNUSED_PAD src0_sel:WORD_1 src1_sel:DWORD
	v_add3_u32 v100, v100, v105, s68
	v_add3_u32 v101, v101, v104, s68
	v_and_b32_sdwa v104, v103, v245 dst_sel:DWORD dst_unused:UNUSED_PAD src0_sel:WORD_1 src1_sel:DWORD
	v_and_b32_sdwa v105, v102, v245 dst_sel:DWORD dst_unused:UNUSED_PAD src0_sel:WORD_1 src1_sel:DWORD
	v_add3_u32 v103, v103, v104, s68
	v_add3_u32 v102, v102, v105, s68
	v_and_b32_e32 v103, 0xffff0000, v103
	v_and_b32_e32 v102, 0xffff0000, v102
	v_or_b32_sdwa v101, v103, v101 dst_sel:DWORD dst_unused:UNUSED_PAD src0_sel:DWORD src1_sel:WORD_1
	v_or_b32_sdwa v100, v102, v100 dst_sel:DWORD dst_unused:UNUSED_PAD src0_sel:DWORD src1_sel:WORD_1
	v_add_u32_e32 v102, 0x1000, v219
	ds_write2_b64 v102, v[88:89], v[100:101] offset0:128 offset1:132
	ds_read_b64 v[88:89], v218 offset:10880
	v_lshlrev_b32_e32 v101, 16, v97
	v_lshlrev_b32_e32 v100, 16, v96
	v_and_b32_e32 v97, 0xffff0000, v97
	v_and_b32_e32 v96, 0xffff0000, v96
	s_waitcnt lgkmcnt(0)
; #define LAS __attribute__((address_space(3)))
; __device__ __forceinline__ unsigned pk2(float lo, float hi) { return f2bf(lo) | (f2bf(hi) << 16); }
; __device__ __forceinline__ float bflo(unsigned w) { return __uint_as_float(w << 16); }
; __device__ __forceinline__ float bfhi(unsigned w) { return __uint_as_float(w & 0xffff0000u); }
; __device__ __forceinline__ void sgu_item(LAS unsigned char* wl, const bf16* proj, bf16* ymix, const float* vstat, const float* sgu_g, const bf16* Wm, const float* sgu_b, int chunk, int h, int lane) {
;     ...
;         for (int i = 0; i < 8; ++i) { const int s = rsub + 16 * i; const f32x2 ms = st[s]; const v4u w = raw[i];
;             v2u lo, hi; lo.x = pk2((bflo(w.x) - ms.x) * ms.y * g0[0], (bfhi(w.x) - ms.x) * ms.y * g0[1]); lo.y = pk2((bflo(w.y) - ms.x) * ms.y * g0[2], (bfhi(w.y) - ms.x) * ms.y * g0[3]);
;             hi.x = pk2((bflo(w.z) - ms.x) * ms.y * g1[0], (bfhi(w.z) - ms.x) * ms.y * g1[1]); hi.y = pk2((bflo(w.w) - ms.x) * ms.y * g1[2], (bfhi(w.w) - ms.x) * ms.y * g1[3]);
;             *(LAS v2u*)(wl + s * VP2 + (4 * c16) * 2) = lo; *(LAS v2u*)(wl + s * VP2 + (16 + 4 * c16) * 2) = hi; }
	v_pk_add_f32 v[100:101], v[100:101], v[88:89] op_sel_hi:[1,0] neg_lo:[0,1] neg_hi:[0,1]
	v_pk_add_f32 v[96:97], v[96:97], v[88:89] op_sel_hi:[1,0] neg_lo:[0,1] neg_hi:[0,1]
	v_pk_mul_f32 v[100:101], v[88:89], v[100:101] op_sel:[1,0]
	v_pk_mul_f32 v[96:97], v[88:89], v[96:97] op_sel:[1,0]
	v_pk_mul_f32 v[100:101], v[116:117], v[100:101]
	v_pk_mul_f32 v[96:97], v[94:95], v[96:97]
	v_and_b32_sdwa v102, v101, v245 dst_sel:DWORD dst_unused:UNUSED_PAD src0_sel:WORD_1 src1_sel:DWORD
	v_and_b32_sdwa v103, v100, v245 dst_sel:DWORD dst_unused:UNUSED_PAD src0_sel:WORD_1 src1_sel:DWORD
	v_add3_u32 v100, v100, v103, s68
	v_add3_u32 v101, v101, v102, s68
	v_and_b32_sdwa v102, v97, v245 dst_sel:DWORD dst_unused:UNUSED_PAD src0_sel:WORD_1 src1_sel:DWORD
	v_and_b32_sdwa v103, v96, v245 dst_sel:DWORD dst_unused:UNUSED_PAD src0_sel:WORD_1 src1_sel:DWORD
	v_add3_u32 v97, v97, v102, s68
	v_add3_u32 v96, v96, v103, s68
	v_and_b32_e32 v97, 0xffff0000, v97
	v_and_b32_e32 v96, 0xffff0000, v96
	v_or_b32_sdwa v97, v97, v101 dst_sel:DWORD dst_unused:UNUSED_PAD src0_sel:DWORD src1_sel:WORD_1
	v_or_b32_sdwa v96, v96, v100 dst_sel:DWORD dst_unused:UNUSED_PAD src0_sel:DWORD src1_sel:WORD_1
	v_lshlrev_b32_e32 v101, 16, v99
	v_lshlrev_b32_e32 v100, 16, v98
	v_pk_add_f32 v[100:101], v[100:101], v[88:89] op_sel_hi:[1,0] neg_lo:[0,1] neg_hi:[0,1]
	v_and_b32_e32 v99, 0xffff0000, v99
	v_and_b32_e32 v98, 0xffff0000, v98
	v_pk_mul_f32 v[100:101], v[88:89], v[100:101] op_sel:[1,0]
	v_pk_add_f32 v[98:99], v[98:99], v[88:89] op_sel_hi:[1,0] neg_lo:[0,1] neg_hi:[0,1]
	v_pk_mul_f32 v[100:101], v[92:93], v[100:101]
	v_pk_mul_f32 v[88:89], v[88:89], v[98:99] op_sel:[1,0]
	v_and_b32_sdwa v98, v101, v245 dst_sel:DWORD dst_unused:UNUSED_PAD src0_sel:WORD_1 src1_sel:DWORD
	v_pk_mul_f32 v[88:89], v[90:91], v[88:89]
	v_and_b32_sdwa v99, v100, v245 dst_sel:DWORD dst_unused:UNUSED_PAD src0_sel:WORD_1 src1_sel:DWORD
	v_add3_u32 v99, v100, v99, s68
	v_add3_u32 v98, v101, v98, s68
	v_and_b32_sdwa v100, v89, v245 dst_sel:DWORD dst_unused:UNUSED_PAD src0_sel:WORD_1 src1_sel:DWORD
	v_and_b32_sdwa v101, v88, v245 dst_sel:DWORD dst_unused:UNUSED_PAD src0_sel:WORD_1 src1_sel:DWORD
	v_add3_u32 v89, v89, v100, s68
	v_add3_u32 v88, v88, v101, s68
	v_and_b32_e32 v89, 0xffff0000, v89
	v_and_b32_e32 v88, 0xffff0000, v88
	v_or_b32_sdwa v89, v89, v98 dst_sel:DWORD dst_unused:UNUSED_PAD src0_sel:DWORD src1_sel:WORD_1
	v_or_b32_sdwa v88, v88, v99 dst_sel:DWORD dst_unused:UNUSED_PAD src0_sel:DWORD src1_sel:WORD_1
	v_add_u32_e32 v98, 0x1800, v219
	ds_write2_b64 v98, v[96:97], v[88:89] offset0:32 offset1:36
	ds_read_b64 v[88:89], v218 offset:11008
	v_lshlrev_b32_e32 v97, 16, v85
	v_lshlrev_b32_e32 v96, 16, v84
	v_and_b32_e32 v85, 0xffff0000, v85
	v_and_b32_e32 v84, 0xffff0000, v84
	s_waitcnt lgkmcnt(0)
	v_pk_add_f32 v[96:97], v[96:97], v[88:89] op_sel_hi:[1,0] neg_lo:[0,1] neg_hi:[0,1]
	v_pk_add_f32 v[84:85], v[84:85], v[88:89] op_sel_hi:[1,0] neg_lo:[0,1] neg_hi:[0,1]
	v_pk_mul_f32 v[96:97], v[88:89], v[96:97] op_sel:[1,0]
	v_pk_mul_f32 v[84:85], v[88:89], v[84:85] op_sel:[1,0]
	v_pk_mul_f32 v[96:97], v[116:117], v[96:97]
	v_pk_mul_f32 v[84:85], v[94:95], v[84:85]
	v_and_b32_sdwa v99, v97, v245 dst_sel:DWORD dst_unused:UNUSED_PAD src0_sel:WORD_1 src1_sel:DWORD
	v_and_b32_sdwa v100, v96, v245 dst_sel:DWORD dst_unused:UNUSED_PAD src0_sel:WORD_1 src1_sel:DWORD
	v_add3_u32 v96, v96, v100, s68
	v_add3_u32 v97, v97, v99, s68
	v_and_b32_sdwa v99, v85, v245 dst_sel:DWORD dst_unused:UNUSED_PAD src0_sel:WORD_1 src1_sel:DWORD
	v_and_b32_sdwa v100, v84, v245 dst_sel:DWORD dst_unused:UNUSED_PAD src0_sel:WORD_1 src1_sel:DWORD
	v_add3_u32 v85, v85, v99, s68
	v_add3_u32 v84, v84, v100, s68
	v_and_b32_e32 v85, 0xffff0000, v85
	v_and_b32_e32 v84, 0xffff0000, v84
	v_or_b32_sdwa v85, v85, v97 dst_sel:DWORD dst_unused:UNUSED_PAD src0_sel:DWORD src1_sel:WORD_1
	v_or_b32_sdwa v84, v84, v96 dst_sel:DWORD dst_unused:UNUSED_PAD src0_sel:DWORD src1_sel:WORD_1
	v_lshlrev_b32_e32 v97, 16, v87
	v_lshlrev_b32_e32 v96, 16, v86
	v_pk_add_f32 v[96:97], v[96:97], v[88:89] op_sel_hi:[1,0] neg_lo:[0,1] neg_hi:[0,1]
	v_and_b32_e32 v87, 0xffff0000, v87
	v_and_b32_e32 v86, 0xffff0000, v86
	v_pk_mul_f32 v[96:97], v[88:89], v[96:97] op_sel:[1,0]
	v_pk_add_f32 v[86:87], v[86:87], v[88:89] op_sel_hi:[1,0] neg_lo:[0,1] neg_hi:[0,1]
	v_pk_mul_f32 v[96:97], v[92:93], v[96:97]
	v_pk_mul_f32 v[86:87], v[88:89], v[86:87] op_sel:[1,0]
	v_and_b32_sdwa v88, v97, v245 dst_sel:DWORD dst_unused:UNUSED_PAD src0_sel:WORD_1 src1_sel:DWORD
	v_pk_mul_f32 v[86:87], v[90:91], v[86:87]
	v_and_b32_sdwa v89, v96, v245 dst_sel:DWORD dst_unused:UNUSED_PAD src0_sel:WORD_1 src1_sel:DWORD
	v_add3_u32 v89, v96, v89, s68
	v_add3_u32 v88, v97, v88, s68
	v_and_b32_sdwa v96, v87, v245 dst_sel:DWORD dst_unused:UNUSED_PAD src0_sel:WORD_1 src1_sel:DWORD
	v_and_b32_sdwa v97, v86, v245 dst_sel:DWORD dst_unused:UNUSED_PAD src0_sel:WORD_1 src1_sel:DWORD
	v_add3_u32 v87, v87, v96, s68
	v_add3_u32 v86, v86, v97, s68
	v_and_b32_e32 v87, 0xffff0000, v87
	v_and_b32_e32 v86, 0xffff0000, v86
	v_or_b32_sdwa v87, v87, v88 dst_sel:DWORD dst_unused:UNUSED_PAD src0_sel:DWORD src1_sel:WORD_1
	v_or_b32_sdwa v86, v86, v89 dst_sel:DWORD dst_unused:UNUSED_PAD src0_sel:DWORD src1_sel:WORD_1
	ds_write2_b64 v98, v[84:85], v[86:87] offset0:192 offset1:196
	ds_read_b64 v[84:85], v218 offset:11136
	v_lshlrev_b32_e32 v87, 16, v81
	v_lshlrev_b32_e32 v86, 16, v80
	v_and_b32_e32 v81, 0xffff0000, v81
	v_and_b32_e32 v80, 0xffff0000, v80
	s_waitcnt lgkmcnt(0)
; #define LAS __attribute__((address_space(3)))
; #define MFMA16(a, b, c) __builtin_amdgcn_mfma_f32_16x16x32_bf16((a), (b), (c), 0, 0, 0)
; __device__ __forceinline__ unsigned pk2(float lo, float hi) { return f2bf(lo) | (f2bf(hi) << 16); }
; __device__ __forceinline__ float bflo(unsigned w) { return __uint_as_float(w << 16); }
; __device__ __forceinline__ float bfhi(unsigned w) { return __uint_as_float(w & 0xffff0000u); }
; #define LDS_WAIT() asm volatile("s_waitcnt lgkmcnt(0)" ::: "memory")
; __device__ __forceinline__ void sgu_item(LAS unsigned char* wl, const bf16* proj, bf16* ymix, const float* vstat, const float* sgu_g, const bf16* Wm, const float* sgu_b, int chunk, int h, int lane) {
;     ...
;         for (int i = 0; i < 8; ++i) { const int s = rsub + 16 * i; const f32x2 ms = st[s]; const v4u w = raw[i];
;             v2u lo, hi; lo.x = pk2((bflo(w.x) - ms.x) * ms.y * g0[0], (bfhi(w.x) - ms.x) * ms.y * g0[1]); lo.y = pk2((bflo(w.y) - ms.x) * ms.y * g0[2], (bfhi(w.y) - ms.x) * ms.y * g0[3]);
;             hi.x = pk2((bflo(w.z) - ms.x) * ms.y * g1[0], (bfhi(w.z) - ms.x) * ms.y * g1[1]); hi.y = pk2((bflo(w.w) - ms.x) * ms.y * g1[2], (bfhi(w.w) - ms.x) * ms.y * g1[3]);
;             *(LAS v2u*)(wl + s * VP2 + (4 * c16) * 2) = lo; *(LAS v2u*)(wl + s * VP2 + (16 + 4 * c16) * 2) = hi; }
;         v4u uu8[8];
; #pragma unroll
;         for (int tb = 0; tb < 8; ++tb) uu8[tb] = __builtin_nontemporal_load((const v4u*)(proj + (R0 + 16 * tb + r) * DIN + 512 + colv + 8 * q));
;         LDS_WAIT();
;         v2u olo[8];
; #pragma unroll
;         for (int n = 0; n < 2; ++n) {
;             f32x4 z[8];
; #pragma unroll
;             for (int tb = 0; tb < 8; ++tb) z[tb] = (f32x4){0.f, 0.f, 0.f, 0.f};
;             int f = 0;
; #pragma unroll
;             for (int ks = 0; ks < 4; ++ks) {
;                 LAS unsigned char* ad = wl + (ks * 32 + 8 * q + (r >> 2)) * VP2 + (16 * n) * 2 + 8 * (r & 3);
;                 const s16x4 lo = __builtin_bit_cast(s16x4, __builtin_amdgcn_ds_read_tr16_b64_v4i16((LAS s16x4*)ad));
;                 const s16x4 hi = __builtin_bit_cast(s16x4, __builtin_amdgcn_ds_read_tr16_b64_v4i16((LAS s16x4*)(ad + 4 * VP2)));
;                 const bf16x8 vf = __builtin_shufflevector(lo, hi, 0, 1, 2, 3, 4, 5, 6, 7);
; #pragma unroll
;                 for (int tb = 2 * ks; tb < 8; ++tb) z[tb] = MFMA16(vf, wmf[f++], z[tb]);
	v_pk_add_f32 v[86:87], v[86:87], v[84:85] op_sel_hi:[1,0] neg_lo:[0,1] neg_hi:[0,1]
	v_pk_add_f32 v[80:81], v[80:81], v[84:85] op_sel_hi:[1,0] neg_lo:[0,1] neg_hi:[0,1]
	v_pk_mul_f32 v[86:87], v[84:85], v[86:87] op_sel:[1,0]
	v_pk_mul_f32 v[80:81], v[84:85], v[80:81] op_sel:[1,0]
	v_pk_mul_f32 v[86:87], v[116:117], v[86:87]
	v_pk_mul_f32 v[80:81], v[94:95], v[80:81]
	v_and_b32_sdwa v88, v87, v245 dst_sel:DWORD dst_unused:UNUSED_PAD src0_sel:WORD_1 src1_sel:DWORD
	v_and_b32_sdwa v89, v86, v245 dst_sel:DWORD dst_unused:UNUSED_PAD src0_sel:WORD_1 src1_sel:DWORD
	v_add3_u32 v86, v86, v89, s68
	v_add3_u32 v87, v87, v88, s68
	v_and_b32_sdwa v88, v81, v245 dst_sel:DWORD dst_unused:UNUSED_PAD src0_sel:WORD_1 src1_sel:DWORD
	v_and_b32_sdwa v89, v80, v245 dst_sel:DWORD dst_unused:UNUSED_PAD src0_sel:WORD_1 src1_sel:DWORD
	v_add3_u32 v81, v81, v88, s68
	v_add3_u32 v80, v80, v89, s68
	v_and_b32_e32 v81, 0xffff0000, v81
	v_and_b32_e32 v80, 0xffff0000, v80
	v_or_b32_sdwa v81, v81, v87 dst_sel:DWORD dst_unused:UNUSED_PAD src0_sel:DWORD src1_sel:WORD_1
	v_or_b32_sdwa v80, v80, v86 dst_sel:DWORD dst_unused:UNUSED_PAD src0_sel:DWORD src1_sel:WORD_1
	v_lshlrev_b32_e32 v87, 16, v83
	v_lshlrev_b32_e32 v86, 16, v82
	v_pk_add_f32 v[86:87], v[86:87], v[84:85] op_sel_hi:[1,0] neg_lo:[0,1] neg_hi:[0,1]
	v_and_b32_e32 v83, 0xffff0000, v83
	v_and_b32_e32 v82, 0xffff0000, v82
	v_pk_mul_f32 v[86:87], v[84:85], v[86:87] op_sel:[1,0]
	v_pk_add_f32 v[82:83], v[82:83], v[84:85] op_sel_hi:[1,0] neg_lo:[0,1] neg_hi:[0,1]
	v_pk_mul_f32 v[86:87], v[92:93], v[86:87]
	v_pk_mul_f32 v[82:83], v[84:85], v[82:83] op_sel:[1,0]
	v_and_b32_sdwa v84, v87, v245 dst_sel:DWORD dst_unused:UNUSED_PAD src0_sel:WORD_1 src1_sel:DWORD
	v_pk_mul_f32 v[82:83], v[90:91], v[82:83]
	v_and_b32_sdwa v85, v86, v245 dst_sel:DWORD dst_unused:UNUSED_PAD src0_sel:WORD_1 src1_sel:DWORD
	v_add3_u32 v85, v86, v85, s68
	v_add3_u32 v84, v87, v84, s68
	v_and_b32_sdwa v86, v83, v245 dst_sel:DWORD dst_unused:UNUSED_PAD src0_sel:WORD_1 src1_sel:DWORD
	v_and_b32_sdwa v87, v82, v245 dst_sel:DWORD dst_unused:UNUSED_PAD src0_sel:WORD_1 src1_sel:DWORD
	v_add3_u32 v83, v83, v86, s68
	v_add3_u32 v82, v82, v87, s68
	v_and_b32_e32 v83, 0xffff0000, v83
	v_and_b32_e32 v82, 0xffff0000, v82
	v_or_b32_sdwa v83, v83, v84 dst_sel:DWORD dst_unused:UNUSED_PAD src0_sel:DWORD src1_sel:WORD_1
	v_or_b32_sdwa v82, v82, v85 dst_sel:DWORD dst_unused:UNUSED_PAD src0_sel:DWORD src1_sel:WORD_1
	v_add_u32_e32 v84, 0x2000, v219
	ds_write2_b64 v84, v[80:81], v[82:83] offset0:96 offset1:100
	v_lshl_add_u64 v[80:81], v[188:189], 0, s[20:21]
	v_add_co_u32_e32 v82, vcc, s0, v80
	s_mov_b32 s0, 0xf10c000
	s_nop 0
	v_addc_co_u32_e32 v83, vcc, 0, v81, vcc
	global_load_dwordx4 v[104:107], v[82:83], off offset:1024 nt
	v_add_co_u32_e32 v82, vcc, s0, v80
	s_mov_b32 s0, 0xf118000
	s_nop 0
	v_addc_co_u32_e32 v83, vcc, 0, v81, vcc
	global_load_dwordx4 v[100:103], v[82:83], off offset:1024 nt
	v_add_co_u32_e32 v82, vcc, s0, v80
	s_mov_b32 s0, 0xf130000
	s_nop 0
	v_addc_co_u32_e32 v83, vcc, 0, v81, vcc
	global_load_dwordx4 v[96:99], v[82:83], off offset:1024 nt
	v_lshl_add_u64 v[82:83], v[190:191], 0, s[20:21]
	global_load_dwordx4 v[92:95], v[82:83], off nt
	v_add_co_u32_e32 v82, vcc, s0, v80
	s_mov_b32 s0, 0xf13c000
	s_nop 0
	v_addc_co_u32_e32 v83, vcc, 0, v81, vcc
	global_load_dwordx4 v[88:91], v[82:83], off offset:1024 nt
	v_add_co_u32_e32 v82, vcc, s0, v80
	s_mov_b32 s0, 0xf148000
	s_nop 0
	v_addc_co_u32_e32 v83, vcc, 0, v81, vcc
	global_load_dwordx4 v[84:87], v[82:83], off offset:1024 nt
	v_add_co_u32_e32 v80, vcc, s0, v80
	v_lshl_add_u64 v[108:109], v[186:187], 0, s[20:21]
	s_nop 0
	v_addc_co_u32_e32 v81, vcc, 0, v81, vcc
	global_load_dwordx4 v[80:83], v[80:81], off offset:1024 nt
	s_mov_b32 s0, 0x10900000
	global_load_dwordx4 v[108:111], v[108:109], off nt
	s_waitcnt lgkmcnt(0)
	ds_read_b64_tr_b16 v[116:117], v220 offset:320
	ds_read_b64_tr_b16 v[114:115], v220
	ds_read_b64_tr_b16 v[112:113], v220 offset:32
	ds_read_b64_tr_b16 v[208:209], v220 offset:2560
	ds_read_b64_tr_b16 v[210:211], v220 offset:2880
	s_waitcnt lgkmcnt(0)
	v_mfma_f32_16x16x32_bf16 v[118:121], v[114:117], v[0:3], 0
	v_mfma_f32_16x16x32_bf16 v[122:125], v[114:117], v[4:7], 0
	s_nop 6
	v_mov_b32_e32 v138, v119
	v_mov_b32_e32 v119, v120
	v_pk_add_f32 v[118:119], v[162:163], v[118:119]
	v_mfma_f32_16x16x32_bf16 v[126:129], v[114:117], v[8:11], 0
	v_mov_b32_e32 v139, v121
	v_pk_add_f32 v[138:139], v[162:163], v[138:139]
	v_mfma_f32_16x16x32_bf16 v[130:133], v[114:117], v[16:19], 0
	v_mfma_f32_16x16x32_bf16 v[134:137], v[114:117], v[24:27], 0
	v_mfma_f32_16x16x32_bf16 v[200:203], v[114:117], v[48:51], 0
	v_mfma_f32_16x16x32_bf16 v[204:207], v[114:117], v[32:35], 0
	v_mfma_f32_16x16x32_bf16 v[114:117], v[114:117], v[40:43], 0
	v_mfma_f32_16x16x32_bf16 v[126:129], v[208:211], v[12:15], v[126:129]
	v_mfma_f32_16x16x32_bf16 v[130:133], v[208:211], v[20:23], v[130:133]
	v_mfma_f32_16x16x32_bf16 v[134:137], v[208:211], v[28:31], v[134:137]
	v_mfma_f32_16x16x32_bf16 v[200:203], v[208:211], v[56:59], v[200:203]
	v_mfma_f32_16x16x32_bf16 v[204:207], v[208:211], v[36:39], v[204:207]
	v_mfma_f32_16x16x32_bf16 v[114:117], v[208:211], v[44:47], v[114:117]
	ds_read_b64_tr_b16 v[208:209], v220 offset:5120
	ds_read_b64_tr_b16 v[210:211], v220 offset:5440
	s_waitcnt lgkmcnt(0)
	v_mfma_f32_16x16x32_bf16 v[222:225], v[208:211], v[60:63], v[200:203]
	v_mfma_f32_16x16x32_bf16 v[200:203], v[208:211], v[64:67], v[204:207]
	s_nop 2
	ds_read_b64_tr_b16 v[204:205], v220 offset:7680
	ds_read_b64_tr_b16 v[206:207], v220 offset:8000
	s_waitcnt lgkmcnt(0)
	v_mfma_f32_16x16x32_bf16 v[226:229], v[204:207], v[68:71], v[200:203]
	s_waitcnt vmcnt(0)
; #define LAS __attribute__((address_space(3)))
; #define MFMA16(a, b, c) __builtin_amdgcn_mfma_f32_16x16x32_bf16((a), (b), (c), 0, 0, 0)
; __device__ __forceinline__ unsigned pk2(float lo, float hi) { return f2bf(lo) | (f2bf(hi) << 16); }
; __device__ __forceinline__ float bflo(unsigned w) { return __uint_as_float(w << 16); }
; __device__ __forceinline__ float bfhi(unsigned w) { return __uint_as_float(w & 0xffff0000u); }
; __device__ __forceinline__ void sgu_item(LAS unsigned char* wl, const bf16* proj, bf16* ymix, const float* vstat, const float* sgu_g, const bf16* Wm, const float* sgu_b, int chunk, int h, int lane) {
;     ...
; #pragma unroll
;             for (int ks = 0; ks < 4; ++ks) {
;                 LAS unsigned char* ad = wl + (ks * 32 + 8 * q + (r >> 2)) * VP2 + (16 * n) * 2 + 8 * (r & 3);
;                 const s16x4 lo = __builtin_bit_cast(s16x4, __builtin_amdgcn_ds_read_tr16_b64_v4i16((LAS s16x4*)ad));
;                 const s16x4 hi = __builtin_bit_cast(s16x4, __builtin_amdgcn_ds_read_tr16_b64_v4i16((LAS s16x4*)(ad + 4 * VP2)));
;                 const bf16x8 vf = __builtin_shufflevector(lo, hi, 0, 1, 2, 3, 4, 5, 6, 7);
; #pragma unroll
;                 for (int tb = 2 * ks; tb < 8; ++tb) z[tb] = MFMA16(vf, wmf[f++], z[tb]);
;             }
; #pragma unroll
;             for (int tb = 0; tb < 8; ++tb) { const v4u uu = uu8[tb]; const unsigned ux = n == 0 ? uu.x : uu.z, uy = n == 0 ? uu.y : uu.w;
;                 v2u o; o.x = pk2(bflo(ux) * (z[tb][0] + bias[tb]), bfhi(ux) * (z[tb][1] + bias[tb])); o.y = pk2(bflo(uy) * (z[tb][2] + bias[tb]), bfhi(uy) * (z[tb][3] + bias[tb]));
	s_nop 1
	v_and_b32_e32 v201, 0xffff0000, v105
	v_and_b32_e32 v200, 0xffff0000, v104
	v_lshlrev_b32_e32 v105, 16, v105
	v_lshlrev_b32_e32 v104, 16, v104
	v_pk_mul_f32 v[214:215], v[118:119], v[104:105]
	v_mov_b32_e32 v104, v123
	v_mov_b32_e32 v105, v125
	v_pk_add_f32 v[104:105], v[164:165], v[104:105]
	v_and_b32_e32 v119, 0xffff0000, v101
	v_and_b32_e32 v118, 0xffff0000, v100
	v_mov_b32_e32 v123, v124
	v_mfma_f32_16x16x32_bf16 v[114:117], v[208:211], v[72:75], v[114:117]
	v_mul_f32_e64 v212, v104, v118
	v_mul_f32_e64 v213, v105, v119
	v_pk_add_f32 v[104:105], v[164:165], v[122:123]
	v_lshlrev_b32_e32 v101, 16, v101
	v_lshlrev_b32_e32 v100, 16, v100
	v_mfma_f32_16x16x32_bf16 v[134:137], v[208:211], v[52:55], v[134:137]
	v_mul_f32_e64 v210, v104, v100
	v_mul_f32_e64 v211, v105, v101
	v_mov_b32_e32 v100, v127
	v_mov_b32_e32 v101, v129
	v_pk_add_f32 v[100:101], v[166:167], v[100:101]
	v_and_b32_e32 v105, 0xffff0000, v97
	v_and_b32_e32 v104, 0xffff0000, v96
	v_mov_b32_e32 v127, v128
	v_pk_mul_f32 v[208:209], v[100:101], v[104:105]
	v_pk_add_f32 v[100:101], v[166:167], v[126:127]
	v_lshlrev_b32_e32 v97, 16, v97
	v_lshlrev_b32_e32 v96, 16, v96
	v_mfma_f32_16x16x32_bf16 v[114:117], v[204:207], v[76:79], v[114:117]
	v_mul_f32_e64 v206, v100, v96
	v_mul_f32_e64 v207, v101, v97
	v_mov_b32_e32 v96, v131
	v_mov_b32_e32 v97, v133
	v_pk_add_f32 v[96:97], v[168:169], v[96:97]
	v_and_b32_e32 v101, 0xffff0000, v93
	v_and_b32_e32 v100, 0xffff0000, v92
	v_mov_b32_e32 v131, v132
	v_pk_mul_f32 v[204:205], v[96:97], v[100:101]
	v_pk_add_f32 v[96:97], v[168:169], v[130:131]
	v_lshlrev_b32_e32 v93, 16, v93
	v_lshlrev_b32_e32 v92, 16, v92
	v_pk_mul_f32 v[202:203], v[96:97], v[92:93]
	v_mov_b32_e32 v92, v135
	v_mov_b32_e32 v93, v137
	v_pk_add_f32 v[92:93], v[170:171], v[92:93]
	v_and_b32_e32 v97, 0xffff0000, v89
	v_and_b32_e32 v96, 0xffff0000, v88
	v_mov_b32_e32 v135, v136
	v_pk_mul_f32 v[216:217], v[138:139], v[200:201]
	v_pk_mul_f32 v[200:201], v[92:93], v[96:97]
	v_pk_add_f32 v[92:93], v[170:171], v[134:135]
	v_lshlrev_b32_e32 v89, 16, v89
	v_lshlrev_b32_e32 v88, 16, v88
	v_pk_mul_f32 v[104:105], v[92:93], v[88:89]
	v_mov_b32_e32 v88, v223
	v_mov_b32_e32 v89, v225
	v_pk_add_f32 v[88:89], v[172:173], v[88:89]
	v_and_b32_e32 v93, 0xffff0000, v85
	v_and_b32_e32 v92, 0xffff0000, v84
	v_mov_b32_e32 v223, v224
	v_pk_mul_f32 v[100:101], v[88:89], v[92:93]
	v_pk_add_f32 v[88:89], v[172:173], v[222:223]
	v_lshlrev_b32_e32 v85, 16, v85
	v_lshlrev_b32_e32 v84, 16, v84
	v_pk_mul_f32 v[96:97], v[88:89], v[84:85]
	v_mov_b32_e32 v84, v227
	v_mov_b32_e32 v85, v229
	v_pk_add_f32 v[84:85], v[174:175], v[84:85]
	v_and_b32_e32 v89, 0xffff0000, v81
	v_and_b32_e32 v88, 0xffff0000, v80
	v_mov_b32_e32 v227, v228
	v_pk_mul_f32 v[92:93], v[84:85], v[88:89]
	v_pk_add_f32 v[84:85], v[174:175], v[226:227]
	v_lshlrev_b32_e32 v81, 16, v81
	v_lshlrev_b32_e32 v80, 16, v80
	v_pk_mul_f32 v[80:81], v[84:85], v[80:81]
	v_mov_b32_e32 v84, v115
	v_mov_b32_e32 v85, v117
	v_pk_add_f32 v[84:85], v[176:177], v[84:85]
	v_and_b32_e32 v89, 0xffff0000, v109
	v_and_b32_e32 v88, 0xffff0000, v108
	v_mov_b32_e32 v115, v116
	v_pk_mul_f32 v[88:89], v[84:85], v[88:89]
	v_pk_add_f32 v[84:85], v[176:177], v[114:115]
	ds_read_b64_tr_b16 v[114:115], v220 offset:352
	ds_read_b64_tr_b16 v[234:235], v220 offset:2592
	ds_read_b64_tr_b16 v[236:237], v220 offset:2912
	s_waitcnt lgkmcnt(2)
	v_mfma_f32_16x16x32_bf16 v[120:123], v[112:115], v[16:19], 0
	v_lshlrev_b32_e32 v109, 16, v109
	v_lshlrev_b32_e32 v108, 16, v108
	v_pk_mul_f32 v[84:85], v[84:85], v[108:109]
	v_mfma_f32_16x16x32_bf16 v[226:229], v[112:115], v[48:51], 0
	v_bfe_u32 v196, v216, 16, 1
	v_add3_u32 v196, v216, v196, s68
	v_bfe_u32 v195, v217, 16, 1
	v_mfma_f32_16x16x32_bf16 v[230:233], v[112:115], v[32:35], 0
	v_add3_u32 v195, v217, v195, s68
	v_mfma_f32_16x16x32_bf16 v[116:119], v[112:115], v[8:11], 0
	v_mfma_f32_16x16x32_bf16 v[124:127], v[112:115], v[24:27], 0
	v_mfma_f32_16x16x32_bf16 v[222:225], v[112:115], v[0:3], 0
	v_mfma_f32_16x16x32_bf16 v[132:135], v[112:115], v[4:7], 0
	v_mfma_f32_16x16x32_bf16 v[112:115], v[112:115], v[40:43], 0
	s_nop 5
	v_mov_b32_e32 v108, v223
	v_mov_b32_e32 v223, v224
	v_mov_b32_e32 v109, v225
	s_waitcnt lgkmcnt(0)
	v_mfma_f32_16x16x32_bf16 v[128:131], v[234:237], v[20:23], v[120:123]
	v_add_f32_e64 v222, v162, v222
	v_add_f32_e64 v223, v163, v223
	v_pk_add_f32 v[108:109], v[162:163], v[108:109]
	v_mfma_f32_16x16x32_bf16 v[120:123], v[234:237], v[56:59], v[226:229]
	v_mfma_f32_16x16x32_bf16 v[226:229], v[234:237], v[36:39], v[230:233]
	s_nop 2
	ds_read_b64_tr_b16 v[230:231], v220 offset:5152
	ds_read_b64_tr_b16 v[232:233], v220 offset:5472
	v_mfma_f32_16x16x32_bf16 v[136:139], v[234:237], v[12:15], v[116:119]
	v_mfma_f32_16x16x32_bf16 v[116:119], v[234:237], v[28:31], v[124:127]
	v_mfma_f32_16x16x32_bf16 v[112:115], v[234:237], v[44:47], v[112:115]
	s_waitcnt lgkmcnt(0)
	v_mfma_f32_16x16x32_bf16 v[124:127], v[230:233], v[52:55], v[116:119]
	v_mfma_f32_16x16x32_bf16 v[116:119], v[230:233], v[64:67], v[226:229]
	s_nop 2
	ds_read_b64_tr_b16 v[226:227], v220 offset:7712
	ds_read_b64_tr_b16 v[228:229], v220 offset:8032
	v_mfma_f32_16x16x32_bf16 v[112:115], v[230:233], v[72:75], v[112:115]
	s_waitcnt lgkmcnt(0)
; __device__ __forceinline__ unsigned pk2(float lo, float hi) { return f2bf(lo) | (f2bf(hi) << 16); }
; __device__ __forceinline__ float bflo(unsigned w) { return __uint_as_float(w << 16); }
; __device__ __forceinline__ float bfhi(unsigned w) { return __uint_as_float(w & 0xffff0000u); }
; __device__ __forceinline__ void sgu_item(LAS unsigned char* wl, const bf16* proj, bf16* ymix, const float* vstat, const float* sgu_g, const bf16* Wm, const float* sgu_b, int chunk, int h, int lane) {
;     ...
; #pragma unroll
;             for (int tb = 0; tb < 8; ++tb) { const v4u uu = uu8[tb]; const unsigned ux = n == 0 ? uu.x : uu.z, uy = n == 0 ? uu.y : uu.w;
;                 v2u o; o.x = pk2(bflo(ux) * (z[tb][0] + bias[tb]), bfhi(ux) * (z[tb][1] + bias[tb])); o.y = pk2(bflo(uy) * (z[tb][2] + bias[tb]), bfhi(uy) * (z[tb][3] + bias[tb]));
;                 if (n == 0) olo[tb] = o;
;                 else { v4u w; w.x = olo[tb].x; w.y = olo[tb].y; w.z = o.x; w.w = o.y; *(v4u*)(ymix + (R0 + 16 * tb + r) * D + 512 + colv + 8 * q) = w; } }
	v_mfma_f32_16x16x32_bf16 v[116:119], v[226:229], v[68:71], v[116:119]
	v_mfma_f32_16x16x32_bf16 v[112:115], v[226:229], v[76:79], v[112:115]
	v_and_b32_e32 v227, 0xffff0000, v107
	v_and_b32_e32 v226, 0xffff0000, v106
	v_lshlrev_b32_e32 v107, 16, v107
	v_lshlrev_b32_e32 v106, 16, v106
	v_pk_mul_f32 v[106:107], v[222:223], v[106:107]
	v_pk_mul_f32 v[108:109], v[108:109], v[226:227]
	v_bfe_u32 v197, v106, 16, 1
	v_bfe_u32 v216, v107, 16, 1
	v_bfe_u32 v192, v109, 16, 1
	v_bfe_u32 v194, v108, 16, 1
	v_add3_u32 v107, v107, v216, s68
	v_add3_u32 v106, v106, v197, s68
	v_add3_u32 v108, v108, v194, s68
	v_add3_u32 v109, v109, v192, s68
	v_bfe_u32 v192, v214, 16, 1
	v_bfe_u32 v194, v215, 16, 1
	v_lshrrev_b32_e32 v106, 16, v106
	v_lshrrev_b32_e32 v107, 16, v107
	v_add3_u32 v194, v215, v194, s68
	v_add3_u32 v192, v214, v192, s68
	v_and_or_b32 v217, v109, s37, v107
	v_and_or_b32 v216, v108, s37, v106
	v_lshl_add_u64 v[106:107], v[182:183], 0, s[20:21]
	v_lshrrev_b32_e32 v192, 16, v192
	v_lshrrev_b32_e32 v194, 16, v194
	v_add_co_u32_e32 v108, vcc, s0, v106
	v_and_or_b32 v215, v195, s37, v194
	v_and_or_b32 v214, v196, s37, v192
	v_addc_co_u32_e32 v109, vcc, 0, v107, vcc
	global_store_dwordx4 v[108:109], v[214:217], off offset:1024
	v_mov_b32_e32 v108, v133
	v_mov_b32_e32 v109, v135
	v_mov_b32_e32 v133, v134
	v_pk_add_f32 v[108:109], v[164:165], v[108:109]
	v_and_b32_e32 v215, 0xffff0000, v103
	v_and_b32_e32 v214, 0xffff0000, v102
	v_pk_add_f32 v[132:133], v[164:165], v[132:133]
	v_lshlrev_b32_e32 v103, 16, v103
	v_lshlrev_b32_e32 v102, 16, v102
	v_pk_mul_f32 v[108:109], v[108:109], v[214:215]
	v_pk_mul_f32 v[102:103], v[132:133], v[102:103]
	v_bfe_u32 v134, v213, 16, 1
	v_bfe_u32 v132, v109, 16, 1
	v_bfe_u32 v133, v108, 16, 1
	v_bfe_u32 v135, v212, 16, 1
	v_add3_u32 v194, v213, v134, s68
	v_bfe_u32 v134, v102, 16, 1
	v_add3_u32 v192, v212, v135, s68
	v_add3_u32 v108, v108, v133, s68
	v_add3_u32 v109, v109, v132, s68
	v_bfe_u32 v132, v210, 16, 1
	v_bfe_u32 v133, v211, 16, 1
	v_bfe_u32 v135, v103, 16, 1
	v_add3_u32 v102, v102, v134, s68
	v_add3_u32 v103, v103, v135, s68
	v_add3_u32 v133, v211, v133, s68
	v_add3_u32 v132, v210, v132, s68
	v_lshrrev_b32_e32 v102, 16, v102
	s_mov_b32 s0, 0x10908000
	v_lshrrev_b32_e32 v132, 16, v132
	v_lshrrev_b32_e32 v133, 16, v133
	v_lshrrev_b32_e32 v103, 16, v103
	v_and_or_b32 v134, v108, s37, v102
	v_add_co_u32_e32 v102, vcc, s0, v106
	v_and_or_b32 v135, v109, s37, v103
	v_and_or_b32 v133, v194, s37, v133
	v_and_or_b32 v132, v192, s37, v132
	v_addc_co_u32_e32 v103, vcc, 0, v107, vcc
	global_store_dwordx4 v[102:103], v[132:135], off offset:1024
	v_mov_b32_e32 v102, v137
	v_mov_b32_e32 v103, v139
	v_pk_add_f32 v[102:103], v[166:167], v[102:103]
	v_and_b32_e32 v109, 0xffff0000, v99
	v_and_b32_e32 v108, 0xffff0000, v98
	v_mov_b32_e32 v137, v138
	v_pk_mul_f32 v[102:103], v[102:103], v[108:109]
	v_pk_add_f32 v[108:109], v[166:167], v[136:137]
	v_lshlrev_b32_e32 v99, 16, v99
	v_lshlrev_b32_e32 v98, 16, v98
	v_pk_mul_f32 v[98:99], v[108:109], v[98:99]
	v_bfe_u32 v133, v208, 16, 1
	v_bfe_u32 v108, v103, 16, 1
	v_bfe_u32 v109, v102, 16, 1
	v_add3_u32 v136, v208, v133, s68
	v_bfe_u32 v133, v98, 16, 1
	v_add3_u32 v102, v102, v109, s68
	v_add3_u32 v103, v103, v108, s68
	v_bfe_u32 v108, v206, 16, 1
	v_bfe_u32 v109, v207, 16, 1
	v_bfe_u32 v134, v99, 16, 1
	v_add3_u32 v98, v98, v133, s68
	v_bfe_u32 v132, v209, 16, 1
	v_add3_u32 v99, v99, v134, s68
	v_add3_u32 v109, v207, v109, s68
	v_add3_u32 v108, v206, v108, s68
	v_lshrrev_b32_e32 v98, 16, v98
	s_mov_b32 s0, 0x10910000
	v_add3_u32 v132, v209, v132, s68
	v_lshrrev_b32_e32 v108, 16, v108
	v_lshrrev_b32_e32 v109, 16, v109
	v_lshrrev_b32_e32 v99, 16, v99
	v_and_or_b32 v134, v102, s37, v98
	v_add_co_u32_e32 v98, vcc, s0, v106
	v_and_or_b32 v135, v103, s37, v99
	v_and_or_b32 v133, v132, s37, v109
	v_and_or_b32 v132, v136, s37, v108
	v_addc_co_u32_e32 v99, vcc, 0, v107, vcc
	global_store_dwordx4 v[98:99], v[132:135], off offset:1024
	v_mov_b32_e32 v98, v129
	v_mov_b32_e32 v99, v131
	v_pk_add_f32 v[98:99], v[168:169], v[98:99]
	v_and_b32_e32 v103, 0xffff0000, v95
	v_and_b32_e32 v102, 0xffff0000, v94
	v_mov_b32_e32 v129, v130
	v_pk_mul_f32 v[98:99], v[98:99], v[102:103]
	v_pk_add_f32 v[102:103], v[168:169], v[128:129]
	v_lshlrev_b32_e32 v95, 16, v95
	v_lshlrev_b32_e32 v94, 16, v94
	v_pk_mul_f32 v[94:95], v[102:103], v[94:95]
	v_bfe_u32 v102, v99, 16, 1
	v_bfe_u32 v103, v98, 16, 1
	v_add3_u32 v98, v98, v103, s68
	v_add3_u32 v99, v99, v102, s68
	v_bfe_u32 v102, v202, 16, 1
	v_bfe_u32 v103, v203, 16, 1
	v_bfe_u32 v128, v94, 16, 1
	v_bfe_u32 v129, v95, 16, 1
	v_bfe_u32 v108, v205, 16, 1
	v_bfe_u32 v109, v204, 16, 1
	v_add3_u32 v95, v95, v129, s68
	v_add3_u32 v94, v94, v128, s68
	v_add3_u32 v103, v203, v103, s68
	v_add3_u32 v102, v202, v102, s68
	v_add3_u32 v109, v204, v109, s68
	v_add3_u32 v108, v205, v108, s68
	v_lshrrev_b32_e32 v102, 16, v102
	v_lshrrev_b32_e32 v103, 16, v103
	v_lshrrev_b32_e32 v94, 16, v94
	v_lshrrev_b32_e32 v95, 16, v95
	v_and_or_b32 v131, v99, s37, v95
	v_and_or_b32 v130, v98, s37, v94
	v_and_or_b32 v129, v108, s37, v103
	v_and_or_b32 v128, v109, s37, v102
	v_lshl_add_u64 v[94:95], v[184:185], 0, s[20:21]
	global_store_dwordx4 v[94:95], v[128:131], off
	v_mov_b32_e32 v94, v125
	v_mov_b32_e32 v95, v127
	v_pk_add_f32 v[94:95], v[170:171], v[94:95]
; __device__ __forceinline__ unsigned pk2(float lo, float hi) { return f2bf(lo) | (f2bf(hi) << 16); }
; __device__ __forceinline__ float bflo(unsigned w) { return __uint_as_float(w << 16); }
; __device__ __forceinline__ float bfhi(unsigned w) { return __uint_as_float(w & 0xffff0000u); }
; #define LDS_WAIT() asm volatile("s_waitcnt lgkmcnt(0)" ::: "memory")
; #define lane (hw_lane())
; __device__ __forceinline__ void sgu_item(LAS unsigned char* wl, const bf16* proj, bf16* ymix, const float* vstat, const float* sgu_g, const bf16* Wm, const float* sgu_b, int chunk, int h, int lane) {
;     ...
; #pragma unroll
;             for (int tb = 0; tb < 8; ++tb) { const v4u uu = uu8[tb]; const unsigned ux = n == 0 ? uu.x : uu.z, uy = n == 0 ? uu.y : uu.w;
;                 v2u o; o.x = pk2(bflo(ux) * (z[tb][0] + bias[tb]), bfhi(ux) * (z[tb][1] + bias[tb])); o.y = pk2(bflo(uy) * (z[tb][2] + bias[tb]), bfhi(uy) * (z[tb][3] + bias[tb]));
;                 if (n == 0) olo[tb] = o;
;                 else { v4u w; w.x = olo[tb].x; w.y = olo[tb].y; w.z = o.x; w.w = o.y; *(v4u*)(ymix + (R0 + 16 * tb + r) * D + 512 + colv + 8 * q) = w; } }
;         }
;         LDS_WAIT();
; __device__ __forceinline__ void mixer_phase(LAS unsigned char* lds, const bf16* proj, bf16* ymix, const float* vstat, const bf16* WpT, const float* pscale, const float* sgu_g, const bf16* Wm, const float* sgu_b, int pool_first, int pool_step, int pool_limit, int sgu_first, int sgu_step, int sgu_limi ...
;     ...
;     for (int j = sgu_first; j < sgu_limit; j += sgu_step) sgu_item(wl, proj, ymix, vstat, sgu_g, Wm, sgu_b, j >> 2, j & 3, lane);
	v_and_b32_e32 v99, 0xffff0000, v91
	v_and_b32_e32 v98, 0xffff0000, v90
	v_mov_b32_e32 v125, v126
	v_pk_mul_f32 v[94:95], v[94:95], v[98:99]
	v_pk_add_f32 v[98:99], v[170:171], v[124:125]
	v_lshlrev_b32_e32 v91, 16, v91
	v_lshlrev_b32_e32 v90, 16, v90
	v_pk_mul_f32 v[90:91], v[98:99], v[90:91]
	v_bfe_u32 v103, v200, 16, 1
	v_bfe_u32 v98, v95, 16, 1
	v_bfe_u32 v99, v94, 16, 1
	v_add3_u32 v108, v200, v103, s68
	v_bfe_u32 v103, v90, 16, 1
	v_mfma_f32_16x16x32_bf16 v[120:123], v[230:233], v[60:63], v[120:123]
	v_add3_u32 v94, v94, v99, s68
	v_add3_u32 v95, v95, v98, s68
	v_bfe_u32 v98, v104, 16, 1
	v_bfe_u32 v99, v105, 16, 1
	v_bfe_u32 v109, v91, 16, 1
	v_add3_u32 v90, v90, v103, s68
	v_bfe_u32 v102, v201, 16, 1
	v_add3_u32 v91, v91, v109, s68
	v_add3_u32 v99, v105, v99, s68
	v_add3_u32 v98, v104, v98, s68
	v_lshrrev_b32_e32 v90, 16, v90
	s_mov_b32 s0, 0x10920000
	v_add3_u32 v102, v201, v102, s68
	v_lshrrev_b32_e32 v98, 16, v98
	v_lshrrev_b32_e32 v99, 16, v99
	v_lshrrev_b32_e32 v91, 16, v91
	v_and_or_b32 v104, v94, s37, v90
	v_add_co_u32_e32 v90, vcc, s0, v106
	v_and_or_b32 v105, v95, s37, v91
	v_and_or_b32 v103, v102, s37, v99
	v_and_or_b32 v102, v108, s37, v98
	v_addc_co_u32_e32 v91, vcc, 0, v107, vcc
	global_store_dwordx4 v[90:91], v[102:105], off offset:1024
	v_mov_b32_e32 v90, v121
	v_mov_b32_e32 v91, v123
	v_pk_add_f32 v[90:91], v[172:173], v[90:91]
	v_and_b32_e32 v95, 0xffff0000, v87
	v_and_b32_e32 v94, 0xffff0000, v86
	v_mov_b32_e32 v121, v122
	v_pk_mul_f32 v[90:91], v[90:91], v[94:95]
	v_pk_add_f32 v[94:95], v[172:173], v[120:121]
	v_lshlrev_b32_e32 v87, 16, v87
	v_lshlrev_b32_e32 v86, 16, v86
	v_pk_mul_f32 v[86:87], v[94:95], v[86:87]
	v_bfe_u32 v99, v100, 16, 1
	v_bfe_u32 v94, v91, 16, 1
	v_bfe_u32 v95, v90, 16, 1
	v_bfe_u32 v98, v101, 16, 1
	v_add3_u32 v99, v100, v99, s68
	v_bfe_u32 v100, v86, 16, 1
	v_add3_u32 v98, v101, v98, s68
	v_add3_u32 v90, v90, v95, s68
	v_add3_u32 v91, v91, v94, s68
	v_bfe_u32 v94, v96, 16, 1
	v_bfe_u32 v95, v97, 16, 1
	v_bfe_u32 v101, v87, 16, 1
	v_add3_u32 v86, v86, v100, s68
	v_add3_u32 v87, v87, v101, s68
	v_add3_u32 v95, v97, v95, s68
	v_add3_u32 v94, v96, v94, s68
	v_lshrrev_b32_e32 v86, 16, v86
	s_mov_b32 s0, 0x10928000
	v_lshrrev_b32_e32 v94, 16, v94
	v_lshrrev_b32_e32 v95, 16, v95
	v_lshrrev_b32_e32 v87, 16, v87
	v_and_or_b32 v96, v90, s37, v86
	v_add_co_u32_e32 v86, vcc, s0, v106
	v_and_or_b32 v97, v91, s37, v87
	v_and_or_b32 v95, v98, s37, v95
	v_and_or_b32 v94, v99, s37, v94
	v_addc_co_u32_e32 v87, vcc, 0, v107, vcc
	global_store_dwordx4 v[86:87], v[94:97], off offset:1024
	v_mov_b32_e32 v86, v117
	v_mov_b32_e32 v87, v119
	v_pk_add_f32 v[86:87], v[174:175], v[86:87]
	v_and_b32_e32 v91, 0xffff0000, v83
	v_and_b32_e32 v90, 0xffff0000, v82
	v_mov_b32_e32 v117, v118
	v_pk_mul_f32 v[86:87], v[86:87], v[90:91]
	v_pk_add_f32 v[90:91], v[174:175], v[116:117]
	v_lshlrev_b32_e32 v83, 16, v83
	v_lshlrev_b32_e32 v82, 16, v82
	v_pk_mul_f32 v[82:83], v[90:91], v[82:83]
	v_bfe_u32 v94, v93, 16, 1
	v_bfe_u32 v90, v87, 16, 1
	v_bfe_u32 v91, v86, 16, 1
	v_bfe_u32 v95, v92, 16, 1
	v_add3_u32 v93, v93, v94, s68
	v_bfe_u32 v94, v82, 16, 1
	v_add3_u32 v92, v92, v95, s68
	v_add3_u32 v86, v86, v91, s68
	v_add3_u32 v87, v87, v90, s68
	v_bfe_u32 v90, v80, 16, 1
	v_bfe_u32 v91, v81, 16, 1
	v_bfe_u32 v95, v83, 16, 1
	v_add3_u32 v82, v82, v94, s68
	v_add3_u32 v83, v83, v95, s68
	v_add3_u32 v81, v81, v91, s68
	v_add3_u32 v80, v80, v90, s68
	v_lshrrev_b32_e32 v82, 16, v82
	s_mov_b32 s0, 0x10930000
	v_lshrrev_b32_e32 v80, 16, v80
	v_lshrrev_b32_e32 v81, 16, v81
	v_lshrrev_b32_e32 v83, 16, v83
	v_and_or_b32 v82, v86, s37, v82
	v_add_co_u32_e32 v86, vcc, s0, v106
	v_and_or_b32 v83, v87, s37, v83
	v_and_or_b32 v81, v93, s37, v81
	v_and_or_b32 v80, v92, s37, v80
	v_addc_co_u32_e32 v87, vcc, 0, v107, vcc
	global_store_dwordx4 v[86:87], v[80:83], off offset:1024
	v_lshlrev_b32_e32 v87, 16, v111
	v_lshlrev_b32_e32 v86, 16, v110
	v_mov_b32_e32 v80, v113
	v_mov_b32_e32 v81, v115
	v_pk_add_f32 v[80:81], v[176:177], v[80:81]
	v_and_b32_e32 v83, 0xffff0000, v111
	v_and_b32_e32 v82, 0xffff0000, v110
	v_mov_b32_e32 v113, v114
	v_pk_mul_f32 v[80:81], v[80:81], v[82:83]
	v_pk_add_f32 v[82:83], v[176:177], v[112:113]
	v_bfe_u32 v90, v89, 16, 1
	v_pk_mul_f32 v[82:83], v[82:83], v[86:87]
	v_bfe_u32 v86, v81, 16, 1
	v_bfe_u32 v87, v80, 16, 1
	v_bfe_u32 v91, v88, 16, 1
	v_add3_u32 v88, v88, v91, s68
	v_add3_u32 v89, v89, v90, s68
	v_add3_u32 v80, v80, v87, s68
	v_add3_u32 v81, v81, v86, s68
	v_bfe_u32 v86, v84, 16, 1
	v_bfe_u32 v87, v85, 16, 1
	v_bfe_u32 v90, v82, 16, 1
	v_bfe_u32 v91, v83, 16, 1
	v_add3_u32 v83, v83, v91, s68
	v_add3_u32 v82, v82, v90, s68
	v_add3_u32 v85, v85, v87, s68
	v_add3_u32 v84, v84, v86, s68
	v_lshrrev_b32_e32 v84, 16, v84
	v_lshrrev_b32_e32 v85, 16, v85
	v_lshrrev_b32_e32 v82, 16, v82
	v_lshrrev_b32_e32 v83, 16, v83
	v_and_or_b32 v83, v81, s37, v83
	v_and_or_b32 v82, v80, s37, v82
	v_and_or_b32 v81, v89, s37, v85
	v_and_or_b32 v80, v88, s37, v84
	v_lshl_add_u64 v[84:85], v[180:181], 0, s[20:21]
	global_store_dwordx4 v[84:85], v[80:83], off
	s_waitcnt lgkmcnt(0)
	s_add_u32 s20, s20, 64
	s_addc_u32 s21, s21, 0
	s_cmpk_lg_i32 s20, 0x100
	s_cbranch_scc1 .LBB0_511
	s_add_i32 s5, s5, s77
	s_add_i32 s4, s4, s7
	s_cmp_lt_i32 s5, s2
	s_cbranch_scc1 .LBB0_510

; __device__ __forceinline__ float row_rstd(const float* slots, int row) {
;     const f32x4* s = (const f32x4*)(slots + (size_t)row * 16);
;     const f32x4 a = s[0], b = s[1], c = s[2], d = s[3];
;     const f32x4 t = (a + b) + (c + d);
;     const float ss = (t[0] + t[1]) + (t[2] + t[3]);
;     return __builtin_amdgcn_rsqf(ss * (1.0f / 1024.0f) + 1e-6f);
; }
;     __device__ __forceinline__ void operator()(f32x4 (&acc)[2][2][4][2], const Unit& u, int wr, int wc, int fr, int fq) const {
;         float loc[2];
; #pragma unroll
;         for (int ai = 0; ai < 2; ++ai) loc[ai] = scale * row_rstd(slots, u.pm * BM + wr * 64 + ai * HALF + fq * 16 + fr);
; #pragma unroll
;         for (int ai = 0; ai < 2; ++ai)
; #pragma unroll
;             for (int m = 0; m < 4; ++m) { float mx = -3.0e38f; const float rsm = __shfl(loc[ai], m * 16 + fr);
; #pragma unroll
;                 for (int bj = 0; bj < 2; ++bj)
; #pragma unroll
;                     for (int n = 0; n < 2; ++n) { const f32x4 x = acc[ai][bj][m][n] * rsm; acc[ai][bj][m][n] = x; mx = fmaxf(fmaxf(mx, fmaxf(x[0], x[1])), fmaxf(x[2], x[3])); }
;                 mx = fmaxf(mx, __shfl_xor(mx, 16)); mx = fmaxf(mx, __shfl_xor(mx, 32));
;                 if (fq == 0) xch[(ai * HALF + wr * 64 + m * 16 + fr) * 4 + wc] = mx; }
.LBB0_690:
	s_lshl_b32 s13, s67, 8
	v_add_u32_e32 v158, s13, v213
	v_ashrrev_i32_e32 v159, 31, v158
	v_lshlrev_b64 v[128:129], 6, v[158:159]
	v_lshl_add_u64 v[140:141], s[4:5], 0, v[128:129]
	global_load_dwordx4 v[128:131], v[140:141], off
	global_load_dwordx4 v[132:135], v[140:141], off offset:16
	global_load_dwordx4 v[136:139], v[140:141], off offset:32
	s_nop 0
	global_load_dwordx4 v[140:143], v[140:141], off offset:48
	v_and_b32_e32 v157, 64, v252
	v_xor_b32_e32 v159, 16, v252
	s_waitcnt vmcnt(0) lgkmcnt(0)
	v_pk_add_f32 v[130:131], v[130:131], v[134:135]
	v_pk_add_f32 v[128:129], v[128:129], v[132:133]
	v_pk_add_f32 v[132:133], v[138:139], v[142:143]
	v_pk_add_f32 v[134:135], v[136:137], v[140:141]
	v_pk_add_f32 v[130:131], v[130:131], v[132:133]
	v_pk_add_f32 v[128:129], v[128:129], v[134:135]
	v_pk_mov_b32 v[132:133], v[128:129], v[130:131] op_sel:[1,0]
	v_mov_b32_e32 v129, v131
	v_pk_add_f32 v[128:129], v[132:133], v[128:129]
	v_add_f32_e32 v128, v128, v129
	v_fmamk_f32 v128, v128, 0x3a800000, v244
	v_rsq_f32_e32 v128, v128
	s_nop 0
	v_mul_f32_e32 v156, 0x3db8aa3b, v128
	v_add_u32_e32 v128, 0x80, v158
	v_ashrrev_i32_e32 v129, 31, v128
	v_lshlrev_b64 v[128:129], 6, v[128:129]
	v_lshl_add_u64 v[132:133], s[4:5], 0, v[128:129]
	global_load_dwordx4 v[136:139], v[132:133], off
	global_load_dwordx4 v[140:143], v[132:133], off offset:16
	global_load_dwordx4 v[128:131], v[132:133], off offset:32
	s_nop 0
	global_load_dwordx4 v[132:135], v[132:133], off offset:48
	v_or_b32_e32 v158, v157, v210
	v_lshlrev_b32_e32 v236, 2, v158
	ds_bpermute_b32 v158, v236, v156
	v_add_u32_e32 v157, 64, v157
	v_cmp_lt_i32_e32 vcc, v159, v157
	s_nop 1
	v_cndmask_b32_e32 v159, v252, v159, vcc
	v_lshlrev_b32_e32 v234, 2, v159
	v_xor_b32_e32 v159, 32, v252
	v_cmp_lt_i32_e32 vcc, v159, v157
	s_waitcnt lgkmcnt(0)
	v_pk_mul_f32 v[126:127], v[126:127], v[158:159] op_sel_hi:[1,0]
	v_pk_mul_f32 v[124:125], v[124:125], v[158:159] op_sel_hi:[1,0]
	v_cndmask_b32_e32 v157, v252, v159, vcc
	v_max_f32_e32 v159, v126, v127
	v_lshlrev_b32_e32 v235, 2, v157
	v_max_f32_e32 v157, v124, v125
	v_pk_mul_f32 v[122:123], v[122:123], v[158:159] op_sel_hi:[1,0]
	v_pk_mul_f32 v[180:181], v[120:121], v[158:159] op_sel_hi:[1,0]
	v_max3_f32 v157, v157, s6, v159
	v_max_f32_e32 v120, v180, v181
	v_max_f32_e32 v121, v122, v123
	v_max3_f32 v157, v157, v120, v121
	v_pk_mul_f32 v[120:121], v[118:119], v[158:159] op_sel_hi:[1,0]
	v_pk_mul_f32 v[182:183], v[116:117], v[158:159] op_sel_hi:[1,0]
	v_max_f32_e32 v117, v120, v121
	v_max_f32_e32 v116, v182, v183
	v_pk_mul_f32 v[114:115], v[114:115], v[158:159] op_sel_hi:[1,0]
	v_pk_mul_f32 v[112:113], v[112:113], v[158:159] op_sel_hi:[1,0]
	v_max3_f32 v116, v157, v116, v117
	v_max_f32_e32 v117, v112, v113
	v_max_f32_e32 v118, v114, v115
	v_max3_f32 v116, v116, v117, v118
	ds_bpermute_b32 v117, v234, v116
	s_waitcnt lgkmcnt(0)
	v_max_f32_e32 v117, v117, v117
	v_max_f32_e32 v116, v116, v117
	ds_bpermute_b32 v117, v235, v116
	s_and_saveexec_b64 s[22:23], s[40:41]
	s_cbranch_execz .LBB0_692
	s_waitcnt lgkmcnt(0)
	v_max_f32_e32 v117, v117, v117
	v_max_f32_e32 v116, v116, v116
	v_max_f32_e32 v116, v116, v117
	ds_write_b32 v223, v116

; #define PG8_LAS __attribute__((address_space(3)))
; __device__ __forceinline__ unsigned cvt_pk_bf16(float lo, float hi) { unsigned r; asm volatile("v_cvt_pk_bf16_f32 %0, %1, %2" : "=v"(r) : "v"(lo), "v"(hi)); return r; }
;     __device__ __forceinline__ void operator()(f32x4 (&acc)[2][2][4][2], const Unit& u, int wr, int wc, int fr, int fq) const {
;     ...
;         asm volatile("s_waitcnt lgkmcnt(0)" ::: "memory"); __builtin_amdgcn_s_barrier(); asm volatile("" ::: "memory");
; #pragma unroll
;         for (int ai = 0; ai < 2; ++ai)
; #pragma unroll
;             for (int m = 0; m < 4; ++m) { const int r = ai * HALF + wr * 64 + m * 16 + fr; const f32x4 s4 = *(const PG8_LAS f32x4*)(xch + 1024 + r * 4);
;                 const float inv = 1.0f / ((s4[0] + s4[1]) + (s4[2] + s4[3]));
;                 bf16_t* rowp = P + (size_t)(u.pm >> 5) * bgap + (size_t)(u.pm * BM + r) * 1024 + u.pn * BM + wc * 32 + 8 * fq;
; #pragma unroll
;                 for (int bj = 0; bj < 2; ++bj) { const f32x4 v0 = acc[ai][bj][m][0] * inv, v1 = acc[ai][bj][m][1] * inv;
;                     u32x4 w; w.x = cvt_pk_bf16(v0[0], v0[1]); w.y = cvt_pk_bf16(v0[2], v0[3]); w.z = cvt_pk_bf16(v1[0], v1[1]); w.w = cvt_pk_bf16(v1[2], v1[3]);
;                     *(u32x4*)(rowp + bj * HALF) = w; }
.LBB0_722:
	s_or_b64 exec, exec, s[22:23]
	s_waitcnt lgkmcnt(0)
	s_barrier
	v_add_u32_e32 v128, s2, v214
	s_waitcnt lgkmcnt(0)
	ds_read_b128 v[128:131], v128
	s_ashr_i32 s17, s67, 5
	s_lshl_b32 s24, s66, 8
	s_ashr_i32 s25, s24, 31
	s_waitcnt lgkmcnt(0)
	v_mov_b32_e32 v132, v129
	v_mov_b32_e32 v133, v130
	v_mov_b32_e32 v129, v131
	v_pk_add_f32 v[128:129], v[132:133], v[128:129]
	v_add_f32_e32 v128, v128, v129
	v_div_scale_f32 v129, s[22:23], v128, v128, 1.0
	v_rcp_f32_e32 v130, v129
	s_mul_hi_i32 s23, s17, 0x1c00000
	s_mul_i32 s17, s17, 0x1c00000
	s_add_u32 s22, s47, s17
	v_fma_f32 v131, -v129, v130, 1.0
	v_fmac_f32_e32 v130, v131, v130
	v_div_scale_f32 v131, vcc, 1.0, v128, 1.0
	v_mul_f32_e32 v132, v131, v130
	v_fma_f32 v133, -v129, v132, v131
	v_fmac_f32_e32 v132, v133, v130
	v_fma_f32 v129, -v129, v132, v131
	v_div_fmas_f32 v129, v129, v130, v132
	v_add_u32_e32 v130, s13, v211
	v_ashrrev_i32_e32 v131, 31, v130
	s_addc_u32 s23, s60, s23
	v_lshlrev_b64 v[130:131], 11, v[130:131]
	v_lshl_add_u64 v[130:131], s[22:23], 0, v[130:131]
	s_lshl_b64 s[24:25], s[24:25], 1
	v_div_fixup_f32 v128, v129, v128, 1.0
	v_lshl_add_u64 v[130:131], v[130:131], 0, s[24:25]
	v_lshl_add_u64 v[130:131], v[130:131], 0, s[86:87]
	v_pk_mul_f32 v[118:119], v[118:119], v[128:129] op_sel_hi:[1,0]
	v_pk_mul_f32 v[110:111], v[110:111], v[128:129] op_sel_hi:[1,0]
	v_lshl_add_u64 v[130:131], v[130:131], 0, v[192:193]
	v_pk_mul_f32 v[124:125], v[124:125], v[128:129] op_sel_hi:[1,0]
	v_pk_mul_f32 v[132:133], v[116:117], v[128:129] op_sel_hi:[1,0]
	v_cvt_pk_bf16_f32 v116, v110, v111
	v_cvt_pk_bf16_f32 v117, v118, v119
	v_pk_mul_f32 v[110:111], v[122:123], v[128:129] op_sel_hi:[1,0]
	v_cvt_pk_bf16_f32 v118, v132, v133
	v_cvt_pk_bf16_f32 v119, v124, v125
	v_pk_mul_f32 v[108:109], v[108:109], v[128:129] op_sel_hi:[1,0]
	global_store_dwordx4 v[130:131], v[116:119], off
	v_cvt_pk_bf16_f32 v108, v108, v109
	v_cvt_pk_bf16_f32 v109, v110, v111
	s_nop 1
	v_pk_mul_f32 v[116:117], v[126:127], v[128:129] op_sel_hi:[1,0]
	v_pk_mul_f32 v[118:119], v[120:121], v[128:129] op_sel_hi:[1,0]
	v_cvt_pk_bf16_f32 v110, v118, v119
	v_cvt_pk_bf16_f32 v111, v116, v117
	global_store_dwordx4 v[130:131], v[108:111], off offset:256
	ds_read_b128 v[108:111], v228
	s_waitcnt lgkmcnt(0)
	v_mov_b32_e32 v116, v109
	v_mov_b32_e32 v117, v110
	v_mov_b32_e32 v109, v111
	v_pk_add_f32 v[108:109], v[116:117], v[108:109]
	v_add_f32_e32 v108, v108, v109
	v_div_scale_f32 v109, s[26:27], v108, v108, 1.0
	v_rcp_f32_e32 v110, v109
	s_nop 0
	v_fma_f32 v111, -v109, v110, 1.0
	v_fmac_f32_e32 v110, v111, v110
	v_div_scale_f32 v111, vcc, 1.0, v108, 1.0
	v_mul_f32_e32 v116, v111, v110
	v_fma_f32 v117, -v109, v116, v111
	v_fmac_f32_e32 v116, v117, v110
	v_fma_f32 v109, -v109, v116, v111
	v_div_fmas_f32 v109, v109, v110, v116
	v_div_fixup_f32 v110, v109, v108, 1.0
	v_add_u32_e32 v108, s13, v217
	v_ashrrev_i32_e32 v109, 31, v108
	v_lshlrev_b64 v[108:109], 11, v[108:109]
	v_lshl_add_u64 v[108:109], s[22:23], 0, v[108:109]
	v_lshl_add_u64 v[108:109], v[108:109], 0, s[24:25]
	v_lshl_add_u64 v[108:109], v[108:109], 0, s[86:87]
	v_pk_mul_f32 v[94:95], v[94:95], v[110:111] op_sel_hi:[1,0]
	v_lshl_add_u64 v[116:117], v[108:109], 0, v[192:193]
	v_pk_mul_f32 v[108:109], v[106:107], v[110:111] op_sel_hi:[1,0]
	v_pk_mul_f32 v[100:101], v[100:101], v[110:111] op_sel_hi:[1,0]
	v_cvt_pk_bf16_f32 v106, v94, v95
	v_pk_mul_f32 v[94:95], v[104:105], v[110:111] op_sel_hi:[1,0]
	v_pk_mul_f32 v[92:93], v[92:93], v[110:111] op_sel_hi:[1,0]
	v_pk_mul_f32 v[112:113], v[112:113], v[110:111] op_sel_hi:[1,0]
	v_cvt_pk_bf16_f32 v107, v108, v109
	v_cvt_pk_bf16_f32 v108, v100, v101
	v_pk_mul_f32 v[100:101], v[114:115], v[110:111] op_sel_hi:[1,0]
	v_cvt_pk_bf16_f32 v109, v112, v113
	global_store_dwordx4 v[116:117], v[106:109], off
	v_pk_mul_f32 v[102:103], v[102:103], v[110:111] op_sel_hi:[1,0]
	v_cvt_pk_bf16_f32 v92, v92, v93
	v_cvt_pk_bf16_f32 v93, v94, v95
	s_nop 0
	v_cvt_pk_bf16_f32 v94, v102, v103
	v_cvt_pk_bf16_f32 v95, v100, v101
	global_store_dwordx4 v[116:117], v[92:95], off offset:256
	ds_read_b128 v[92:95], v229
	s_waitcnt lgkmcnt(0)
	v_mov_b32_e32 v100, v93
	v_mov_b32_e32 v101, v94
	v_mov_b32_e32 v93, v95
	v_pk_add_f32 v[92:93], v[100:101], v[92:93]
	v_add_f32_e32 v92, v92, v93
	v_div_scale_f32 v93, s[26:27], v92, v92, 1.0
	v_rcp_f32_e32 v94, v93
	s_nop 0
	v_fma_f32 v95, -v93, v94, 1.0
	v_fmac_f32_e32 v94, v95, v94
	v_div_scale_f32 v95, vcc, 1.0, v92, 1.0
	v_mul_f32_e32 v100, v95, v94
	v_fma_f32 v101, -v93, v100, v95
	v_fmac_f32_e32 v100, v101, v94
	v_fma_f32 v93, -v93, v100, v95
	v_div_fmas_f32 v93, v93, v94, v100
	v_div_fixup_f32 v94, v93, v92, 1.0
	v_add_u32_e32 v92, s13, v218
	v_ashrrev_i32_e32 v93, 31, v92
	v_lshlrev_b64 v[92:93], 11, v[92:93]
	v_lshl_add_u64 v[92:93], s[22:23], 0, v[92:93]
	v_lshl_add_u64 v[92:93], v[92:93], 0, s[24:25]
	v_lshl_add_u64 v[92:93], v[92:93], 0, s[86:87]
	v_pk_mul_f32 v[78:79], v[78:79], v[94:95] op_sel_hi:[1,0]
	v_lshl_add_u64 v[100:101], v[92:93], 0, v[192:193]
	v_pk_mul_f32 v[92:93], v[90:91], v[94:95] op_sel_hi:[1,0]
	v_pk_mul_f32 v[84:85], v[84:85], v[94:95] op_sel_hi:[1,0]
	v_cvt_pk_bf16_f32 v90, v78, v79
	v_pk_mul_f32 v[78:79], v[88:89], v[94:95] op_sel_hi:[1,0]
	v_pk_mul_f32 v[76:77], v[76:77], v[94:95] op_sel_hi:[1,0]
	v_pk_mul_f32 v[96:97], v[96:97], v[94:95] op_sel_hi:[1,0]
	v_cvt_pk_bf16_f32 v91, v92, v93
	v_cvt_pk_bf16_f32 v92, v84, v85
	v_pk_mul_f32 v[84:85], v[98:99], v[94:95] op_sel_hi:[1,0]
	v_cvt_pk_bf16_f32 v93, v96, v97
	global_store_dwordx4 v[100:101], v[90:93], off
	v_pk_mul_f32 v[86:87], v[86:87], v[94:95] op_sel_hi:[1,0]
	v_cvt_pk_bf16_f32 v76, v76, v77
	v_cvt_pk_bf16_f32 v77, v78, v79
	s_nop 0
	v_cvt_pk_bf16_f32 v78, v86, v87
	v_cvt_pk_bf16_f32 v79, v84, v85
	global_store_dwordx4 v[100:101], v[76:79], off offset:256
	ds_read_b128 v[76:79], v230
	s_waitcnt lgkmcnt(0)
; #define PG8_LAS __attribute__((address_space(3)))
; __device__ __forceinline__ unsigned cvt_pk_bf16(float lo, float hi) { unsigned r; asm volatile("v_cvt_pk_bf16_f32 %0, %1, %2" : "=v"(r) : "v"(lo), "v"(hi)); return r; }
;     __device__ __forceinline__ void operator()(f32x4 (&acc)[2][2][4][2], const Unit& u, int wr, int wc, int fr, int fq) const {
;     ...
;             for (int m = 0; m < 4; ++m) { const int r = ai * HALF + wr * 64 + m * 16 + fr; const f32x4 s4 = *(const PG8_LAS f32x4*)(xch + 1024 + r * 4);
;                 const float inv = 1.0f / ((s4[0] + s4[1]) + (s4[2] + s4[3]));
;                 bf16_t* rowp = P + (size_t)(u.pm >> 5) * bgap + (size_t)(u.pm * BM + r) * 1024 + u.pn * BM + wc * 32 + 8 * fq;
; #pragma unroll
;                 for (int bj = 0; bj < 2; ++bj) { const f32x4 v0 = acc[ai][bj][m][0] * inv, v1 = acc[ai][bj][m][1] * inv;
;                     u32x4 w; w.x = cvt_pk_bf16(v0[0], v0[1]); w.y = cvt_pk_bf16(v0[2], v0[3]); w.z = cvt_pk_bf16(v1[0], v1[1]); w.w = cvt_pk_bf16(v1[2], v1[3]);
;                     *(u32x4*)(rowp + bj * HALF) = w; }
	v_mov_b32_e32 v84, v77
	v_mov_b32_e32 v85, v78
	v_mov_b32_e32 v77, v79
	v_pk_add_f32 v[76:77], v[84:85], v[76:77]
	v_add_f32_e32 v76, v76, v77
	v_div_scale_f32 v77, s[26:27], v76, v76, 1.0
	v_rcp_f32_e32 v78, v77
	s_nop 0
	v_fma_f32 v79, -v77, v78, 1.0
	v_fmac_f32_e32 v78, v79, v78
	v_div_scale_f32 v79, vcc, 1.0, v76, 1.0
	v_mul_f32_e32 v84, v79, v78
	v_fma_f32 v85, -v77, v84, v79
	v_fmac_f32_e32 v84, v85, v78
	v_fma_f32 v77, -v77, v84, v79
	v_div_fmas_f32 v77, v77, v78, v84
	v_div_fixup_f32 v78, v77, v76, 1.0
	v_add_u32_e32 v76, s13, v219
	v_ashrrev_i32_e32 v77, 31, v76
	v_lshlrev_b64 v[76:77], 11, v[76:77]
	v_lshl_add_u64 v[76:77], s[22:23], 0, v[76:77]
	v_lshl_add_u64 v[76:77], v[76:77], 0, s[24:25]
	v_lshl_add_u64 v[76:77], v[76:77], 0, s[86:87]
	v_lshl_add_u64 v[84:85], v[76:77], 0, v[192:193]
	v_pk_mul_f32 v[76:77], v[74:75], v[78:79] op_sel_hi:[1,0]
	v_pk_mul_f32 v[64:65], v[64:65], v[78:79] op_sel_hi:[1,0]
	v_pk_mul_f32 v[68:69], v[68:69], v[78:79] op_sel_hi:[1,0]
	v_pk_mul_f32 v[70:71], v[70:71], v[78:79] op_sel_hi:[1,0]
	v_pk_mul_f32 v[80:81], v[80:81], v[78:79] op_sel_hi:[1,0]
	v_cvt_pk_bf16_f32 v74, v64, v65
	v_cvt_pk_bf16_f32 v75, v76, v77
	v_cvt_pk_bf16_f32 v76, v68, v69
	v_pk_mul_f32 v[64:65], v[72:73], v[78:79] op_sel_hi:[1,0]
	v_cvt_pk_bf16_f32 v77, v80, v81
	global_store_dwordx4 v[84:85], v[74:77], off
	v_pk_mul_f32 v[60:61], v[60:61], v[78:79] op_sel_hi:[1,0]
	v_pk_mul_f32 v[72:73], v[82:83], v[78:79] op_sel_hi:[1,0]
	v_cvt_pk_bf16_f32 v68, v60, v61
	v_cvt_pk_bf16_f32 v69, v64, v65
	v_cvt_pk_bf16_f32 v70, v70, v71
	v_add_u32_e32 v60, s2, v216
	v_cvt_pk_bf16_f32 v71, v72, v73
	global_store_dwordx4 v[84:85], v[68:71], off offset:256
	ds_read_b128 v[68:71], v60
	s_waitcnt lgkmcnt(0)
	v_mov_b32_e32 v60, v69
	v_mov_b32_e32 v61, v70
	v_mov_b32_e32 v69, v71
	v_pk_add_f32 v[60:61], v[60:61], v[68:69]
	v_add_f32_e32 v60, v60, v61
	v_div_scale_f32 v61, s[26:27], v60, v60, 1.0
	v_rcp_f32_e32 v64, v61
	s_nop 0
	v_fma_f32 v65, -v61, v64, 1.0
	v_fmac_f32_e32 v64, v65, v64
	v_div_scale_f32 v65, vcc, 1.0, v60, 1.0
	v_mul_f32_e32 v68, v65, v64
	v_fma_f32 v69, -v61, v68, v65
	v_fmac_f32_e32 v68, v69, v64
	v_fma_f32 v61, -v61, v68, v65
	v_div_fmas_f32 v61, v61, v64, v68
	v_div_fixup_f32 v64, v61, v60, 1.0
	v_add_u32_e32 v60, s13, v215
	v_ashrrev_i32_e32 v61, 31, v60
	v_lshlrev_b64 v[60:61], 11, v[60:61]
	v_lshl_add_u64 v[60:61], s[22:23], 0, v[60:61]
	v_lshl_add_u64 v[60:61], v[60:61], 0, s[24:25]
	v_lshl_add_u64 v[60:61], v[60:61], 0, s[86:87]
	v_pk_mul_f32 v[46:47], v[46:47], v[64:65] op_sel_hi:[1,0]
	v_lshl_add_u64 v[68:69], v[60:61], 0, v[192:193]
	v_pk_mul_f32 v[60:61], v[58:59], v[64:65] op_sel_hi:[1,0]
	v_pk_mul_f32 v[52:53], v[52:53], v[64:65] op_sel_hi:[1,0]
	v_cvt_pk_bf16_f32 v58, v46, v47
	v_pk_mul_f32 v[46:47], v[56:57], v[64:65] op_sel_hi:[1,0]
	v_pk_mul_f32 v[44:45], v[44:45], v[64:65] op_sel_hi:[1,0]
	v_pk_mul_f32 v[62:63], v[62:63], v[64:65] op_sel_hi:[1,0]
	v_cvt_pk_bf16_f32 v59, v60, v61
	v_cvt_pk_bf16_f32 v60, v52, v53
	v_pk_mul_f32 v[52:53], v[66:67], v[64:65] op_sel_hi:[1,0]
	v_cvt_pk_bf16_f32 v61, v62, v63
	global_store_dwordx4 v[68:69], v[58:61], off
	v_pk_mul_f32 v[54:55], v[54:55], v[64:65] op_sel_hi:[1,0]
	v_cvt_pk_bf16_f32 v44, v44, v45
	v_cvt_pk_bf16_f32 v45, v46, v47
	s_nop 0
	v_cvt_pk_bf16_f32 v46, v54, v55
	v_cvt_pk_bf16_f32 v47, v52, v53
	global_store_dwordx4 v[68:69], v[44:47], off offset:256
	ds_read_b128 v[44:47], v231
	s_waitcnt lgkmcnt(0)
	v_mov_b32_e32 v52, v45
	v_mov_b32_e32 v53, v46
	v_mov_b32_e32 v45, v47
	v_pk_add_f32 v[44:45], v[52:53], v[44:45]
	v_add_f32_e32 v44, v44, v45
	v_div_scale_f32 v45, s[26:27], v44, v44, 1.0
	v_rcp_f32_e32 v46, v45
	s_nop 0
	v_fma_f32 v47, -v45, v46, 1.0
	v_fmac_f32_e32 v46, v47, v46
	v_div_scale_f32 v47, vcc, 1.0, v44, 1.0
	v_mul_f32_e32 v52, v47, v46
	v_fma_f32 v53, -v45, v52, v47
	v_fmac_f32_e32 v52, v53, v46
	v_fma_f32 v45, -v45, v52, v47
	v_div_fmas_f32 v45, v45, v46, v52
	v_div_fixup_f32 v46, v45, v44, 1.0
	v_add_u32_e32 v44, s13, v220
	v_ashrrev_i32_e32 v45, 31, v44
	v_lshlrev_b64 v[44:45], 11, v[44:45]
	v_lshl_add_u64 v[44:45], s[22:23], 0, v[44:45]
	v_lshl_add_u64 v[44:45], v[44:45], 0, s[24:25]
	v_lshl_add_u64 v[44:45], v[44:45], 0, s[86:87]
	v_pk_mul_f32 v[30:31], v[30:31], v[46:47] op_sel_hi:[1,0]
	v_lshl_add_u64 v[52:53], v[44:45], 0, v[192:193]
	v_pk_mul_f32 v[44:45], v[42:43], v[46:47] op_sel_hi:[1,0]
	v_pk_mul_f32 v[36:37], v[36:37], v[46:47] op_sel_hi:[1,0]
	v_cvt_pk_bf16_f32 v42, v30, v31
	v_pk_mul_f32 v[30:31], v[40:41], v[46:47] op_sel_hi:[1,0]
	v_pk_mul_f32 v[28:29], v[28:29], v[46:47] op_sel_hi:[1,0]
	v_pk_mul_f32 v[48:49], v[48:49], v[46:47] op_sel_hi:[1,0]
	v_cvt_pk_bf16_f32 v43, v44, v45
	v_cvt_pk_bf16_f32 v44, v36, v37
	v_pk_mul_f32 v[36:37], v[50:51], v[46:47] op_sel_hi:[1,0]
	v_cvt_pk_bf16_f32 v45, v48, v49
	global_store_dwordx4 v[52:53], v[42:45], off
	v_pk_mul_f32 v[38:39], v[38:39], v[46:47] op_sel_hi:[1,0]
	v_cvt_pk_bf16_f32 v28, v28, v29
	v_cvt_pk_bf16_f32 v29, v30, v31
	s_nop 0
	v_cvt_pk_bf16_f32 v30, v38, v39
	v_cvt_pk_bf16_f32 v31, v36, v37
	global_store_dwordx4 v[52:53], v[28:31], off offset:256
	ds_read_b128 v[28:31], v232
	s_waitcnt lgkmcnt(0)
; #define PG8_LAS __attribute__((address_space(3)))
; __device__ __forceinline__ unsigned cvt_pk_bf16(float lo, float hi) { unsigned r; asm volatile("v_cvt_pk_bf16_f32 %0, %1, %2" : "=v"(r) : "v"(lo), "v"(hi)); return r; }
; #define PG8_BAR __builtin_amdgcn_s_barrier()
;     __device__ __forceinline__ void operator()(f32x4 (&acc)[2][2][4][2], const Unit& u, int wr, int wc, int fr, int fq) const {
;     ...
;             for (int m = 0; m < 4; ++m) { const int r = ai * HALF + wr * 64 + m * 16 + fr; const f32x4 s4 = *(const PG8_LAS f32x4*)(xch + 1024 + r * 4);
;                 const float inv = 1.0f / ((s4[0] + s4[1]) + (s4[2] + s4[3]));
;                 bf16_t* rowp = P + (size_t)(u.pm >> 5) * bgap + (size_t)(u.pm * BM + r) * 1024 + u.pn * BM + wc * 32 + 8 * fq;
; #pragma unroll
;                 for (int bj = 0; bj < 2; ++bj) { const f32x4 v0 = acc[ai][bj][m][0] * inv, v1 = acc[ai][bj][m][1] * inv;
;                     u32x4 w; w.x = cvt_pk_bf16(v0[0], v0[1]); w.y = cvt_pk_bf16(v0[2], v0[3]); w.z = cvt_pk_bf16(v1[0], v1[1]); w.w = cvt_pk_bf16(v1[2], v1[3]);
;                     *(u32x4*)(rowp + bj * HALF) = w; }
; template <class Epi, class Sched, bool ALIGN_EPI = false, bool SP2 = false>
; __device__ __forceinline__ void gemm_phase(PG8_LAS unsigned char* lds, const Gemm g, const Sched& S, const Epi& E, int wave_in) {
;     ...
;         if constexpr (!Epi::AFTER_DRAIN) { E(acc, cur, wr, wc, fr, fq); S.done(cur); }
;         if (!has_next) break;
; #pragma unroll
;         for (int a = 0; a < 2; ++a)
; #pragma unroll
;             for (int b = 0; b < 2; ++b)
; #pragma unroll
;                 for (int m = 0; m < 4; ++m)
; #pragma unroll
;                     for (int n = 0; n < 2; ++n) acc[a][b][m][n] = (f32x4){0.f, 0.f, 0.f, 0.f};
;         cur = nxt; cA = nA; cB = nB; ++ui;
;         if constexpr (ALIGN_EPI) { if (wr == 1) PG8_BAR; }
	v_mov_b32_e32 v36, v29
	v_mov_b32_e32 v37, v30
	v_mov_b32_e32 v29, v31
	v_pk_add_f32 v[28:29], v[36:37], v[28:29]
	v_add_f32_e32 v28, v28, v29
	v_div_scale_f32 v29, s[26:27], v28, v28, 1.0
	v_rcp_f32_e32 v30, v29
	s_nop 0
	v_fma_f32 v31, -v29, v30, 1.0
	v_fmac_f32_e32 v30, v31, v30
	v_div_scale_f32 v31, vcc, 1.0, v28, 1.0
	v_mul_f32_e32 v36, v31, v30
	v_fma_f32 v37, -v29, v36, v31
	v_fmac_f32_e32 v36, v37, v30
	v_fma_f32 v29, -v29, v36, v31
	v_div_fmas_f32 v29, v29, v30, v36
	v_div_fixup_f32 v30, v29, v28, 1.0
	v_add_u32_e32 v28, s13, v221
	v_ashrrev_i32_e32 v29, 31, v28
	v_lshlrev_b64 v[28:29], 11, v[28:29]
	v_lshl_add_u64 v[28:29], s[22:23], 0, v[28:29]
	v_lshl_add_u64 v[28:29], v[28:29], 0, s[24:25]
	v_lshl_add_u64 v[28:29], v[28:29], 0, s[86:87]
	v_pk_mul_f32 v[14:15], v[14:15], v[30:31] op_sel_hi:[1,0]
	v_lshl_add_u64 v[36:37], v[28:29], 0, v[192:193]
	v_pk_mul_f32 v[28:29], v[26:27], v[30:31] op_sel_hi:[1,0]
	v_pk_mul_f32 v[20:21], v[20:21], v[30:31] op_sel_hi:[1,0]
	v_cvt_pk_bf16_f32 v26, v14, v15
	v_pk_mul_f32 v[14:15], v[24:25], v[30:31] op_sel_hi:[1,0]
	v_pk_mul_f32 v[12:13], v[12:13], v[30:31] op_sel_hi:[1,0]
	v_pk_mul_f32 v[32:33], v[32:33], v[30:31] op_sel_hi:[1,0]
	v_cvt_pk_bf16_f32 v27, v28, v29
	v_cvt_pk_bf16_f32 v28, v20, v21
	v_pk_mul_f32 v[20:21], v[34:35], v[30:31] op_sel_hi:[1,0]
	v_cvt_pk_bf16_f32 v29, v32, v33
	global_store_dwordx4 v[36:37], v[26:29], off
	v_pk_mul_f32 v[22:23], v[22:23], v[30:31] op_sel_hi:[1,0]
	v_cvt_pk_bf16_f32 v12, v12, v13
	v_cvt_pk_bf16_f32 v13, v14, v15
	s_nop 0
	v_cvt_pk_bf16_f32 v14, v22, v23
	v_cvt_pk_bf16_f32 v15, v20, v21
	global_store_dwordx4 v[36:37], v[12:15], off offset:256
	ds_read_b128 v[12:15], v233
	s_waitcnt lgkmcnt(0)
	v_mov_b32_e32 v20, v13
	v_mov_b32_e32 v21, v14
	v_mov_b32_e32 v13, v15
	v_pk_add_f32 v[12:13], v[20:21], v[12:13]
	v_add_f32_e32 v12, v12, v13
	v_div_scale_f32 v13, s[26:27], v12, v12, 1.0
	v_rcp_f32_e32 v14, v13
	s_nop 0
	v_fma_f32 v15, -v13, v14, 1.0
	v_fmac_f32_e32 v14, v15, v14
	v_div_scale_f32 v15, vcc, 1.0, v12, 1.0
	v_mul_f32_e32 v20, v15, v14
	v_fma_f32 v21, -v13, v20, v15
	v_fmac_f32_e32 v20, v21, v14
	v_fma_f32 v13, -v13, v20, v15
	v_div_fmas_f32 v13, v13, v14, v20
	v_add_u32_e32 v14, s13, v222
	v_ashrrev_i32_e32 v15, 31, v14
	v_lshlrev_b64 v[14:15], 11, v[14:15]
	v_lshl_add_u64 v[14:15], s[22:23], 0, v[14:15]
	v_div_fixup_f32 v12, v13, v12, 1.0
	v_lshl_add_u64 v[14:15], v[14:15], 0, s[24:25]
	v_lshl_add_u64 v[14:15], v[14:15], 0, s[86:87]
	v_pk_mul_f32 v[2:3], v[2:3], v[12:13] op_sel_hi:[1,0]
	v_lshl_add_u64 v[14:15], v[14:15], 0, v[192:193]
	v_pk_mul_f32 v[10:11], v[10:11], v[12:13] op_sel_hi:[1,0]
	v_pk_mul_f32 v[4:5], v[4:5], v[12:13] op_sel_hi:[1,0]
	v_cvt_pk_bf16_f32 v2, v2, v3
	v_cvt_pk_bf16_f32 v3, v10, v11
	v_pk_mul_f32 v[16:17], v[16:17], v[12:13] op_sel_hi:[1,0]
	v_cvt_pk_bf16_f32 v4, v4, v5
	v_pk_mul_f32 v[0:1], v[0:1], v[12:13] op_sel_hi:[1,0]
	v_cvt_pk_bf16_f32 v5, v16, v17
	global_store_dwordx4 v[14:15], v[2:5], off
	v_pk_mul_f32 v[6:7], v[6:7], v[12:13] op_sel_hi:[1,0]
	v_cvt_pk_bf16_f32 v0, v0, v1
	s_andn2_b64 vcc, exec, s[42:43]
	v_pk_mul_f32 v[2:3], v[8:9], v[12:13] op_sel_hi:[1,0]
	v_pk_mul_f32 v[4:5], v[18:19], v[12:13] op_sel_hi:[1,0]
	v_cvt_pk_bf16_f32 v1, v2, v3
	v_cvt_pk_bf16_f32 v2, v6, v7
	s_mov_b64 s[22:23], -1
	v_cvt_pk_bf16_f32 v3, v4, v5
	global_store_dwordx4 v[14:15], v[0:3], off offset:256
	s_cbranch_vccnz .LBB0_679
	s_andn2_b64 vcc, exec, s[0:1]
	s_cbranch_vccnz .LBB0_678
	s_barrier
	s_branch .LBB0_678

; #define lane (hw_lane())
; __device__ __forceinline__ float row_rstd(const float* slots, int row) {
;     const f32x4* s = (const f32x4*)(slots + (size_t)row * 16);
;     const f32x4 a = s[0], b = s[1], c = s[2], d = s[3];
;     const f32x4 t = (a + b) + (c + d);
;     const float ss = (t[0] + t[1]) + (t[2] + t[3]);
;     return __builtin_amdgcn_rsqf(ss * (1.0f / 1024.0f) + 1e-6f);
; }
; __global__ void __launch_bounds__(512, 2) fwd_megakernel(Args a) {
;     ...
;     { const float* fg = a.in[I_FING]; const int ln = lane, gw0 = grouped ? grp * SEQ + gj * 256 + wave * 32 : gw, fstep = grouped ? 1 : NGW, flim = grouped ? gw0 + 32 : M;
;       v2u nw[4]; float nrs = 0.f;
;       if (gw0 < flim) { const v2u* xr = (const v2u*)(HB + (size_t)gw0 * D) + ln; nrs = pg8::row_rstd(slots, gw0);
; #pragma unroll
;         for (int j = 0; j < 4; ++j) nw[j] = __builtin_nontemporal_load(xr + 64 * j); }
.Lfn_generic:
	s_mov_b64 s[0:1], s[58:59]
	s_ashr_i32 s19, s18, 31
	s_lshl_b64 s[2:3], s[18:19], 11
	s_add_u32 s0, s0, s2
	s_addc_u32 s1, s1, s3
	s_mov_b64 s[2:3], s[58:59]
	s_lshl_b64 s[4:5], s[18:19], 6
	s_add_u32 s4, s2, s4
	s_addc_u32 s5, s3, s5
	s_mov_b32 s6, 0x5500000
	v_mov_b32_e32 v2, s4
	s_add_u32 s2, s4, 0x5500000
	v_mov_b32_e32 v3, s5
	v_add_co_u32_e32 v2, vcc, s6, v2
	s_addc_u32 s3, s5, 0
	s_nop 0
	v_addc_co_u32_e32 v3, vcc, 0, v3, vcc
	v_mov_b64_e32 v[4:5], s[2:3]
	global_load_dwordx4 v[16:19], v[2:3], off
	global_load_dwordx4 v[20:23], v[4:5], off offset:16
	global_load_dwordx4 v[24:27], v[4:5], off offset:32
	global_load_dwordx4 v[28:31], v[4:5], off offset:48
	v_ashrrev_i32_e32 v1, 31, v0
	v_lshlrev_b64 v[4:5], 3, v[0:1]
	v_lshl_add_u64 v[2:3], s[0:1], 0, v[4:5]
	s_mov_b32 s0, 0x7100000
	v_add_co_u32_e32 v10, vcc, s0, v2
	s_mov_b64 s[4:5], 0x7100000
	s_nop 0
	v_addc_co_u32_e32 v11, vcc, 0, v3, vcc
	v_lshl_add_u64 v[8:9], v[2:3], 0, s[4:5]
	global_load_dwordx2 v[14:15], v[10:11], off nt
	global_load_dwordx2 v[12:13], v[8:9], off offset:512 nt
	global_load_dwordx2 v[6:7], v[8:9], off offset:1024 nt
	global_load_dwordx2 v[2:3], v[8:9], off offset:1536 nt
	s_add_i32 s0, s18, s16
	s_ashr_i32 s1, s0, 31
	s_lshl_b64 s[2:3], s[0:1], 6
	s_add_u32 s9, s2, 0x5500000
	v_mov_b32_e32 v11, 0x358637bd
	s_addc_u32 s10, s3, 0
	s_ashr_i32 s17, s16, 31
	s_lshl_b64 s[2:3], s[0:1], 11
	s_lshl_b64 s[6:7], s[18:19], 12
	s_lshl_b64 s[0:1], s[16:17], 6
	v_lshl_add_u64 v[4:5], s[2:3], 0, v[4:5]
	s_lshl_b64 s[2:3], s[16:17], 11
	v_lshl_add_u64 v[4:5], v[4:5], 0, s[4:5]
	s_add_u32 s4, s56, s6
	v_lshlrev_b64 v[8:9], 4, v[0:1]
	s_addc_u32 s5, s57, s7
	v_lshl_add_u64 v[0:1], s[54:55], 0, v[8:9]
	v_lshl_add_u64 v[8:9], s[4:5], 0, v[8:9]
	s_mov_b64 s[4:5], 0xc00
	v_lshl_add_u64 v[8:9], v[8:9], 0, s[4:5]
	s_lshl_b64 s[4:5], s[16:17], 12
	s_waitcnt vmcnt(0) lgkmcnt(0)
	v_pk_add_f32 v[18:19], v[18:19], v[22:23]
	v_pk_add_f32 v[16:17], v[16:17], v[20:21]
	v_pk_add_f32 v[20:21], v[26:27], v[30:31]
	v_pk_add_f32 v[22:23], v[24:25], v[28:29]
	v_pk_add_f32 v[18:19], v[18:19], v[20:21]
	v_pk_add_f32 v[16:17], v[16:17], v[22:23]
	v_pk_mov_b32 v[20:21], v[16:17], v[18:19] op_sel:[1,0]
	v_mov_b32_e32 v17, v19
	v_pk_add_f32 v[16:17], v[20:21], v[16:17]
	s_nop 0
	v_add_f32_e32 v10, v16, v17
	v_fmamk_f32 v10, v10, 0x3a800000, v11
	v_rsq_f32_e32 v10, v10
	s_branch .LBB0_1118

; __device__ __forceinline__ float row_rstd(const float* slots, int row) {
;     const f32x4* s = (const f32x4*)(slots + (size_t)row * 16);
;     const f32x4 a = s[0], b = s[1], c = s[2], d = s[3];
;     const f32x4 t = (a + b) + (c + d);
;     const float ss = (t[0] + t[1]) + (t[2] + t[3]);
;     return __builtin_amdgcn_rsqf(ss * (1.0f / 1024.0f) + 1e-6f);
; }
; __global__ void __launch_bounds__(512, 2) fwd_megakernel(Args a) {
;     ...
;       for (int m = gw0; m < flim; m += fstep) { f32x4* orow = (f32x4*)(hres + (size_t)m * D) + ln;
;         v2u w[4]; const float rs = nrs;
; #pragma unroll
;         for (int j = 0; j < 4; ++j) w[j] = nw[j];
;         { const int mn = m + fstep; if (mn < flim) { const v2u* xr = (const v2u*)(HB + (size_t)mn * D) + ln; nrs = pg8::row_rstd(slots, mn);
; #pragma unroll
;             for (int j = 0; j < 4; ++j) nw[j] = __builtin_nontemporal_load(xr + 64 * j); } }
.LBB0_1118:
	s_add_i32 s18, s18, s16
	s_cmp_ge_i32 s18, s8
	s_cselect_b64 s[6:7], -1, 0
	s_and_b64 vcc, exec, s[6:7]
	v_mov_b32_e32 v24, v10
	v_mov_b32_e32 v16, v14
	v_mov_b32_e32 v17, v15
	v_mov_b32_e32 v18, v12
	v_mov_b32_e32 v19, v13
	v_mov_b32_e32 v20, v6
	v_mov_b32_e32 v21, v7
	v_mov_b32_e32 v22, v2
	v_mov_b32_e32 v23, v3
	s_cbranch_vccnz .LBB0_1117
	s_mov_b64 s[12:13], s[58:59]
	s_mov_b64 s[14:15], s[58:59]
	s_add_u32 s14, s14, s9
	s_addc_u32 s15, s15, s10
	v_mov_b64_e32 v[16:17], s[14:15]
	global_load_dwordx4 v[24:27], v[16:17], off
	global_load_dwordx4 v[28:31], v[16:17], off offset:16
	global_load_dwordx4 v[32:35], v[16:17], off offset:32
	global_load_dwordx4 v[36:39], v[16:17], off offset:48
	v_lshl_add_u64 v[40:41], s[12:13], 0, v[4:5]
	global_load_dwordx2 v[16:17], v[40:41], off nt
	global_load_dwordx2 v[18:19], v[40:41], off offset:512 nt
	global_load_dwordx2 v[20:21], v[40:41], off offset:1024 nt
	global_load_dwordx2 v[22:23], v[40:41], off offset:1536 nt
	s_waitcnt vmcnt(0) lgkmcnt(0)
	v_pk_add_f32 v[26:27], v[26:27], v[30:31]
	v_pk_add_f32 v[24:25], v[24:25], v[28:29]
	v_pk_add_f32 v[28:29], v[34:35], v[38:39]
	v_pk_add_f32 v[30:31], v[32:33], v[36:37]
	v_pk_add_f32 v[26:27], v[26:27], v[28:29]
	v_pk_add_f32 v[24:25], v[24:25], v[30:31]
	v_pk_mov_b32 v[28:29], v[24:25], v[26:27] op_sel:[1,0]
	v_mov_b32_e32 v25, v27
	v_pk_add_f32 v[24:25], v[28:29], v[24:25]
	s_nop 0
	v_add_f32_e32 v24, v24, v25
	v_fmamk_f32 v24, v24, 0x3a800000, v11
	v_rsq_f32_e32 v24, v24
	s_branch .LBB0_1117
